# GEMM epilogue 16-byte stores made write-through (sc1) to shrink the L2 write-back at grid barriers
# baseline (speedup 1.0000x reference)
; __device__ __forceinline__ unsigned cvt_pk_bf16(float lo, float hi) { unsigned r; asm volatile("v_cvt_pk_bf16_f32 %0, %1, %2" : "=v"(r) : "v"(lo), "v"(hi)); return r; }
;     __device__ __forceinline__ void operator()(f32x4 (&acc)[2][2][4][2], const Unit& u, int wr, int wc, int fr, int fq) const {
;         bf16_t* base; size_t s_ai, s_m, s_bj;
;         if (frag && u.pn >= fmin) { base = O + ((size_t)(u.pm * frag + u.pn) << 16) + (size_t)((((wr * 4 + wc) * 16) * 64 + fq * 16 + fr) << 3); s_ai = 4096; s_m = 1024; s_bj = 512; }
;         else if (frag) { base = O + ((size_t)(u.pm * frag + u.pn) << 16) + (size_t)(((wr * 64 + fr) << 8) + wc * 32 + 8 * fq); s_ai = (size_t)HALF * 256; s_m = 16 * 256; s_bj = HALF; }
;         else { base = O + (size_t)(u.pm * BM + wr * 64 + fr) * ldc + u.pn * BM + wc * 32 + 8 * fq; s_ai = (size_t)HALF * ldc; s_m = (size_t)16 * ldc; s_bj = HALF; }
; #pragma unroll
;         for (int ai = 0; ai < 2; ++ai)
; #pragma unroll
;             for (int m = 0; m < 4; ++m)
; #pragma unroll
;                 for (int bj = 0; bj < 2; ++bj) { const f32x4 v0 = acc[ai][bj][m][0], v1 = acc[ai][bj][m][1];
;                     u32x4 w; w.x = cvt_pk_bf16(v0[0], v0[1]); w.y = cvt_pk_bf16(v0[2], v0[3]); w.z = cvt_pk_bf16(v1[0], v1[1]); w.w = cvt_pk_bf16(v1[2], v1[3]);
;                     *(u32x4*)(base + ai * s_ai + m * s_m + bj * s_bj) = w; }
.LBB0_82:
	s_mul_i32 s10, s10, 28
	s_add_i32 s46, s10, s45
	s_ashr_i32 s47, s46, 31
	s_lshl_b64 s[46:47], s[46:47], 17
	s_add_u32 s46, s6, s46
	s_addc_u32 s47, s7, s47
	v_ashrrev_i32_e32 v145, 31, v144
	v_lshl_add_u64 v[144:145], v[144:145], 1, s[46:47]
	s_lshl_b32 s10, s24, 1
	v_cvt_pk_bf16_f32 v124, v124, v125
	v_cvt_pk_bf16_f32 v125, v126, v127
	v_cvt_pk_bf16_f32 v126, v120, v121
	v_cvt_pk_bf16_f32 v127, v122, v123
	global_store_dwordx4 v[144:145], v[124:127], off sc1
	v_cvt_pk_bf16_f32 v116, v116, v117
	v_cvt_pk_bf16_f32 v117, v118, v119
	v_cvt_pk_bf16_f32 v118, v108, v109
	v_lshl_add_u64 v[108:109], v[144:145], 0, s[10:11]
	s_lshl_b32 s20, s20, 1
	s_mov_b32 s21, s11
	v_cvt_pk_bf16_f32 v119, v110, v111
	global_store_dwordx4 v[108:109], v[116:119], off sc1
	v_cvt_pk_bf16_f32 v108, v112, v113
	v_cvt_pk_bf16_f32 v109, v114, v115
	v_cvt_pk_bf16_f32 v110, v104, v105
	v_cvt_pk_bf16_f32 v111, v106, v107
	s_lshl_b32 s22, s22, 1
	s_nop 0
	v_lshl_add_u64 v[116:117], v[144:145], 0, s[20:21]
	global_store_dwordx4 v[116:117], v[108:111], off sc1
	v_cvt_pk_bf16_f32 v96, v96, v97
	v_cvt_pk_bf16_f32 v97, v98, v99
	v_cvt_pk_bf16_f32 v98, v88, v89
	v_lshl_add_u64 v[88:89], v[116:117], 0, s[10:11]
	v_cvt_pk_bf16_f32 v99, v90, v91
	global_store_dwordx4 v[88:89], v[96:99], off sc1
	v_cvt_pk_bf16_f32 v88, v100, v101
	v_cvt_pk_bf16_f32 v89, v102, v103
	v_cvt_pk_bf16_f32 v90, v92, v93
	v_cvt_pk_bf16_f32 v91, v94, v95
	s_mov_b32 s23, s11
	s_nop 0
	v_lshl_add_u64 v[96:97], v[116:117], 0, s[20:21]
	global_store_dwordx4 v[96:97], v[88:91], off sc1
	v_cvt_pk_bf16_f32 v80, v80, v81
	v_cvt_pk_bf16_f32 v81, v82, v83
	v_cvt_pk_bf16_f32 v82, v72, v73
	v_lshl_add_u64 v[72:73], v[96:97], 0, s[10:11]
	v_cvt_pk_bf16_f32 v83, v74, v75
	global_store_dwordx4 v[72:73], v[80:83], off sc1
	v_cvt_pk_bf16_f32 v72, v84, v85
	v_cvt_pk_bf16_f32 v73, v86, v87
	v_cvt_pk_bf16_f32 v74, v76, v77
	v_cvt_pk_bf16_f32 v75, v78, v79
	s_and_b64 vcc, exec, s[0:1]
	s_nop 0
	v_lshl_add_u64 v[80:81], v[96:97], 0, s[20:21]
	global_store_dwordx4 v[80:81], v[72:75], off sc1
	v_cvt_pk_bf16_f32 v68, v68, v69
	v_cvt_pk_bf16_f32 v69, v70, v71
	v_cvt_pk_bf16_f32 v70, v64, v65
	v_lshl_add_u64 v[64:65], v[80:81], 0, s[10:11]
	v_cvt_pk_bf16_f32 v71, v66, v67
	global_store_dwordx4 v[64:65], v[68:71], off sc1
	v_lshl_add_u64 v[64:65], v[144:145], 0, s[22:23]
	v_cvt_pk_bf16_f32 v60, v60, v61
	v_cvt_pk_bf16_f32 v61, v62, v63
	v_cvt_pk_bf16_f32 v62, v56, v57
	v_cvt_pk_bf16_f32 v63, v58, v59
	global_store_dwordx4 v[64:65], v[60:63], off sc1
	v_cvt_pk_bf16_f32 v48, v48, v49
	v_cvt_pk_bf16_f32 v49, v50, v51
	v_cvt_pk_bf16_f32 v50, v40, v41
	v_lshl_add_u64 v[40:41], v[64:65], 0, s[10:11]
	v_cvt_pk_bf16_f32 v51, v42, v43
	global_store_dwordx4 v[40:41], v[48:51], off sc1
	v_cvt_pk_bf16_f32 v40, v52, v53
	v_cvt_pk_bf16_f32 v41, v54, v55
	v_cvt_pk_bf16_f32 v42, v44, v45
	v_cvt_pk_bf16_f32 v43, v46, v47
	s_mov_b32 s45, s12
	s_nop 0
	v_lshl_add_u64 v[48:49], v[64:65], 0, s[20:21]
	global_store_dwordx4 v[48:49], v[40:43], off sc1
	v_cvt_pk_bf16_f32 v32, v32, v33
	v_cvt_pk_bf16_f32 v33, v34, v35
	v_cvt_pk_bf16_f32 v34, v24, v25
	v_lshl_add_u64 v[24:25], v[48:49], 0, s[10:11]
	v_cvt_pk_bf16_f32 v35, v26, v27
	global_store_dwordx4 v[24:25], v[32:35], off sc1
	v_cvt_pk_bf16_f32 v24, v36, v37
	v_cvt_pk_bf16_f32 v25, v38, v39
	v_cvt_pk_bf16_f32 v26, v28, v29
	v_cvt_pk_bf16_f32 v27, v30, v31
	s_mov_b64 s[22:23], s[18:19]
	s_nop 0
	v_lshl_add_u64 v[32:33], v[48:49], 0, s[20:21]
	global_store_dwordx4 v[32:33], v[24:27], off sc1
	v_cvt_pk_bf16_f32 v16, v16, v17
	v_cvt_pk_bf16_f32 v17, v18, v19
	v_cvt_pk_bf16_f32 v18, v8, v9
	v_lshl_add_u64 v[8:9], v[32:33], 0, s[10:11]
	v_cvt_pk_bf16_f32 v19, v10, v11
	global_store_dwordx4 v[8:9], v[16:19], off sc1
	v_cvt_pk_bf16_f32 v8, v20, v21
	v_cvt_pk_bf16_f32 v9, v22, v23
	v_cvt_pk_bf16_f32 v10, v12, v13
	v_cvt_pk_bf16_f32 v11, v14, v15
	s_nop 1
	v_lshl_add_u64 v[16:17], v[32:33], 0, s[20:21]
	global_store_dwordx4 v[16:17], v[8:11], off sc1
	v_cvt_pk_bf16_f32 v4, v4, v5
	v_cvt_pk_bf16_f32 v5, v6, v7
	v_cvt_pk_bf16_f32 v6, v0, v1
	v_lshl_add_u64 v[0:1], v[16:17], 0, s[10:11]
	s_mov_b32 s10, s14
	s_mov_b64 s[20:21], s[16:17]
	v_cvt_pk_bf16_f32 v7, v2, v3
	global_store_dwordx4 v[0:1], v[4:7], off sc1
	s_cbranch_vccnz .LBB0_91

; #define PG8_STAGE(bufoff, gbase, voff) do { _Pragma("unroll") for (int _i = 0; _i < 2; ++_i) \
;         __builtin_amdgcn_global_load_lds((const unsigned*)((const char*)(gbase) + (voff)[_i]), (LAS unsigned*)(lds + (bufoff) + ldsw + _i * 8192), 16, 0, 0); } while (0)
; #define PG8_LDA(dst, b, h) do { _Pragma("unroll") for (int m = 0; m < 4; ++m) _Pragma("unroll") for (int k = 0; k < 2; ++k) dst[m][k] = *(const LAS bf16x8*)(lds + PG8_SA(b, h) + aoff + m * 2048 + k * 1024); } while (0)
; #define PG8_LDB(dst, b, h) do { _Pragma("unroll") for (int n = 0; n < 2; ++n) _Pragma("unroll") for (int k = 0; k < 2; ++k) dst[n][k] = *(const LAS bf16x8*)(lds + PG8_SB(b, h) + boff + n * 2048 + k * 1024); } while (0)
; #define PG8_MMA(ai, bj, At, Bt) do { __builtin_amdgcn_s_setprio(1); _Pragma("unroll") for (int m = 0; m < 4; ++m) _Pragma("unroll") for (int n = 0; n < 2; ++n) _Pragma("unroll") for (int k = 0; k < 2; ++k) \
;         acc[ai][bj][m][n] = __builtin_amdgcn_mfma_f32_16x16x32_bf16(Bt[n][k], At[m][k], acc[ai][bj][m][n], 0, 0, 0); __builtin_amdgcn_s_setprio(0); } while (0)
; #define PG8_WAIT_V(n) asm volatile("s_waitcnt vmcnt(" #n ")" ::: "memory")
; #define PG8_WAIT_L(n) asm volatile("s_waitcnt lgkmcnt(" #n ")" ::: "memory")
; #define PG8_BAR __builtin_amdgcn_s_barrier()
; #define PG8_SCHED __builtin_amdgcn_sched_barrier(0)
; template <class Epi, bool KS0 = false>
; __device__ __forceinline__ void gemm_phase(const int WID, LAS unsigned char* lds, const Gemm g, const StaticOrder& S, const Epi& E) {
;     ...
;             PG8_LDB(B0, 0, 0); PG8_SCHED; PG8_LDA(At, 0, 0); PG8_STAGE(PG8_SA(1, 1), a1 + hstep, voffA);
;             PG8_WAIT_L(8); PG8_BAR; PG8_WAIT_L(0); PG8_MMA(0, 0, At, B0); PG8_BAR; PG8_SCHED;
;             PG8_LDB(B1, 0, 1); PG8_STAGE(PG8_SB(0, 0), b2, voffB);
;             PG8_BAR; PG8_WAIT_L(0); PG8_MMA(0, 1, At, B1); PG8_BAR;
;             PG8_LDA(At, 0, 1); PG8_STAGE(PG8_SA(0, 0), a2, voffA);
;             PG8_BAR; PG8_WAIT_L(0); PG8_MMA(1, 0, At, B0); PG8_BAR; PG8_SCHED;
;             PG8_STAGE(PG8_SB(0, 1), b2 + hstep, voffB);
;             PG8_WAIT_V(6); PG8_BAR; PG8_MMA(1, 1, At, B1); PG8_BAR;
.LBB0_670:
	ds_read_b128 v[128:131], v206
	ds_read_b128 v[132:135], v206 offset:1024
	ds_read_b128 v[136:139], v206 offset:2048
	ds_read_b128 v[140:143], v206 offset:3072
	s_add_u32 s42, s20, 0xfff80080
	s_addc_u32 s43, s21, -1
	s_cmp_eq_u32 s53, 28
	s_cselect_b32 s45, s11, s43
	s_cselect_b32 s44, s19, s42
	s_cselect_b32 s43, s9, s52
	s_cselect_b32 s42, s50, s51
	v_lshl_add_u64 v[192:193], s[20:21], 0, v[184:185]
	s_add_i32 m0, s23, 0xc000
	ds_read_b128 v[144:147], v207
	ds_read_b128 v[148:151], v207 offset:1024
	ds_read_b128 v[152:155], v207 offset:2048
	ds_read_b128 v[156:159], v207 offset:3072
	ds_read_b128 v[160:163], v207 offset:4096
	ds_read_b128 v[164:167], v207 offset:5120
	ds_read_b128 v[168:171], v207 offset:6144
	ds_read_b128 v[172:175], v207 offset:7168
	global_load_lds_dwordx4 v[192:193], off
	v_lshl_add_u64 v[192:193], s[20:21], 0, v[186:187]
	s_add_i32 m0, s23, 0xe000
	s_nop 0
	global_load_lds_dwordx4 v[192:193], off
	s_waitcnt lgkmcnt(8)
	s_barrier
	s_waitcnt lgkmcnt(0)
	s_setprio 1
	s_waitcnt lgkmcnt(0)
	v_mfma_f32_16x16x32_bf16 v[124:127], v[128:131], v[144:147], v[124:127]
	v_mfma_f32_16x16x32_bf16 v[120:123], v[136:139], v[144:147], v[120:123]
	v_mfma_f32_16x16x32_bf16 v[108:111], v[128:131], v[152:155], v[108:111]
	v_mfma_f32_16x16x32_bf16 v[104:107], v[136:139], v[152:155], v[104:107]
	v_mfma_f32_16x16x32_bf16 v[92:95], v[128:131], v[160:163], v[92:95]
	v_mfma_f32_16x16x32_bf16 v[88:91], v[136:139], v[160:163], v[88:91]
	v_mfma_f32_16x16x32_bf16 v[76:79], v[128:131], v[168:171], v[76:79]
	v_mfma_f32_16x16x32_bf16 v[72:75], v[136:139], v[168:171], v[72:75]
	v_mfma_f32_16x16x32_bf16 v[124:127], v[132:135], v[148:151], v[124:127]
	v_mfma_f32_16x16x32_bf16 v[120:123], v[140:143], v[148:151], v[120:123]
	v_mfma_f32_16x16x32_bf16 v[108:111], v[132:135], v[156:159], v[108:111]
	v_mfma_f32_16x16x32_bf16 v[104:107], v[140:143], v[156:159], v[104:107]
	v_mfma_f32_16x16x32_bf16 v[92:95], v[132:135], v[164:167], v[92:95]
	v_mfma_f32_16x16x32_bf16 v[88:91], v[140:143], v[164:167], v[88:91]
	v_mfma_f32_16x16x32_bf16 v[76:79], v[132:135], v[172:175], v[76:79]
	v_mfma_f32_16x16x32_bf16 v[72:75], v[140:143], v[172:175], v[72:75]
	s_setprio 0
	s_barrier
	s_add_i32 s54, s35, s26
	v_lshl_add_u64 v[214:215], s[42:43], 0, v[178:179]
	s_mov_b32 m0, s54
	ds_read_b128 v[192:195], v208
	ds_read_b128 v[196:199], v208 offset:1024
	ds_read_b128 v[200:203], v208 offset:2048
	ds_read_b128 v[210:213], v208 offset:3072
	global_load_lds_dwordx4 v[214:215], off
	v_lshl_add_u64 v[216:217], s[42:43], 0, v[182:183]
	s_add_i32 m0, s54, 0x2000
	s_nop 0
	global_load_lds_dwordx4 v[216:217], off
	s_barrier
	s_waitcnt lgkmcnt(0)
	s_setprio 1
	s_waitcnt lgkmcnt(0)
	v_mfma_f32_16x16x32_bf16 v[116:119], v[192:195], v[144:147], v[116:119]
	v_mfma_f32_16x16x32_bf16 v[112:115], v[200:203], v[144:147], v[112:115]
	v_mfma_f32_16x16x32_bf16 v[100:103], v[192:195], v[152:155], v[100:103]
	v_mfma_f32_16x16x32_bf16 v[96:99], v[200:203], v[152:155], v[96:99]
	v_mfma_f32_16x16x32_bf16 v[84:87], v[192:195], v[160:163], v[84:87]
	v_mfma_f32_16x16x32_bf16 v[80:83], v[200:203], v[160:163], v[80:83]
	v_mfma_f32_16x16x32_bf16 v[68:71], v[192:195], v[168:171], v[68:71]
	v_mfma_f32_16x16x32_bf16 v[64:67], v[200:203], v[168:171], v[64:67]
	v_mfma_f32_16x16x32_bf16 v[116:119], v[196:199], v[148:151], v[116:119]
	v_mfma_f32_16x16x32_bf16 v[112:115], v[210:213], v[148:151], v[112:115]
	v_mfma_f32_16x16x32_bf16 v[100:103], v[196:199], v[156:159], v[100:103]
	v_mfma_f32_16x16x32_bf16 v[96:99], v[210:213], v[156:159], v[96:99]
	v_mfma_f32_16x16x32_bf16 v[84:87], v[196:199], v[164:167], v[84:87]
	v_mfma_f32_16x16x32_bf16 v[80:83], v[210:213], v[164:167], v[80:83]
	v_mfma_f32_16x16x32_bf16 v[68:71], v[196:199], v[172:175], v[68:71]
	v_mfma_f32_16x16x32_bf16 v[64:67], v[210:213], v[172:175], v[64:67]
	s_setprio 0
	s_mov_b32 m0, s23
	v_lshl_add_u64 v[218:219], s[44:45], 0, v[176:177]
	s_barrier
	ds_read_b128 v[144:147], v207 offset:16384
	ds_read_b128 v[148:151], v207 offset:17408
	ds_read_b128 v[152:155], v207 offset:18432
	ds_read_b128 v[156:159], v207 offset:19456
	ds_read_b128 v[160:163], v207 offset:20480
	ds_read_b128 v[164:167], v207 offset:21504
	ds_read_b128 v[168:171], v207 offset:22528
	ds_read_b128 v[172:175], v207 offset:23552
	global_load_lds_dwordx4 v[218:219], off
	v_lshl_add_u64 v[220:221], s[44:45], 0, v[180:181]
	s_mov_b32 m0, s24
	s_nop 0
	global_load_lds_dwordx4 v[220:221], off
	s_barrier
	s_waitcnt lgkmcnt(0)
	s_setprio 1
	s_waitcnt lgkmcnt(0)
	v_mfma_f32_16x16x32_bf16 v[60:63], v[128:131], v[144:147], v[60:63]
	v_mfma_f32_16x16x32_bf16 v[56:59], v[136:139], v[144:147], v[56:59]
	v_mfma_f32_16x16x32_bf16 v[44:47], v[128:131], v[152:155], v[44:47]
	v_mfma_f32_16x16x32_bf16 v[40:43], v[136:139], v[152:155], v[40:43]
	v_mfma_f32_16x16x32_bf16 v[28:31], v[128:131], v[160:163], v[28:31]
	v_mfma_f32_16x16x32_bf16 v[24:27], v[136:139], v[160:163], v[24:27]
	v_mfma_f32_16x16x32_bf16 v[12:15], v[128:131], v[168:171], v[12:15]
	v_mfma_f32_16x16x32_bf16 v[8:11], v[136:139], v[168:171], v[8:11]
	v_mfma_f32_16x16x32_bf16 v[60:63], v[132:135], v[148:151], v[60:63]
	v_mfma_f32_16x16x32_bf16 v[56:59], v[140:143], v[148:151], v[56:59]
	v_mfma_f32_16x16x32_bf16 v[44:47], v[132:135], v[156:159], v[44:47]
	v_mfma_f32_16x16x32_bf16 v[40:43], v[140:143], v[156:159], v[40:43]
	v_mfma_f32_16x16x32_bf16 v[28:31], v[132:135], v[164:167], v[28:31]
	v_mfma_f32_16x16x32_bf16 v[24:27], v[140:143], v[164:167], v[24:27]
	v_mfma_f32_16x16x32_bf16 v[12:15], v[132:135], v[172:175], v[12:15]
	v_mfma_f32_16x16x32_bf16 v[8:11], v[140:143], v[172:175], v[8:11]
	s_setprio 0
	s_barrier
; #define PG8_STAGE(bufoff, gbase, voff) do { _Pragma("unroll") for (int _i = 0; _i < 2; ++_i) \
;         __builtin_amdgcn_global_load_lds((const unsigned*)((const char*)(gbase) + (voff)[_i]), (LAS unsigned*)(lds + (bufoff) + ldsw + _i * 8192), 16, 0, 0); } while (0)
; #define PG8_LDA(dst, b, h) do { _Pragma("unroll") for (int m = 0; m < 4; ++m) _Pragma("unroll") for (int k = 0; k < 2; ++k) dst[m][k] = *(const LAS bf16x8*)(lds + PG8_SA(b, h) + aoff + m * 2048 + k * 1024); } while (0)
; #define PG8_LDB(dst, b, h) do { _Pragma("unroll") for (int n = 0; n < 2; ++n) _Pragma("unroll") for (int k = 0; k < 2; ++k) dst[n][k] = *(const LAS bf16x8*)(lds + PG8_SB(b, h) + boff + n * 2048 + k * 1024); } while (0)
; #define PG8_MMA(ai, bj, At, Bt) do { __builtin_amdgcn_s_setprio(1); _Pragma("unroll") for (int m = 0; m < 4; ++m) _Pragma("unroll") for (int n = 0; n < 2; ++n) _Pragma("unroll") for (int k = 0; k < 2; ++k) \
;         acc[ai][bj][m][n] = __builtin_amdgcn_mfma_f32_16x16x32_bf16(Bt[n][k], At[m][k], acc[ai][bj][m][n], 0, 0, 0); __builtin_amdgcn_s_setprio(0); } while (0)
; #define PG8_WAIT_V(n) asm volatile("s_waitcnt vmcnt(" #n ")" ::: "memory")
; #define PG8_WAIT_L(n) asm volatile("s_waitcnt lgkmcnt(" #n ")" ::: "memory")
; #define PG8_BAR __builtin_amdgcn_s_barrier()
; #define PG8_SCHED __builtin_amdgcn_sched_barrier(0)
; template <class Epi, bool KS0 = false>
; __device__ __forceinline__ void gemm_phase(const int WID, LAS unsigned char* lds, const Gemm g, const StaticOrder& S, const Epi& E) {
;     ...
;             PG8_STAGE(PG8_SB(0, 1), b2 + hstep, voffB);
;             PG8_WAIT_V(6); PG8_BAR; PG8_MMA(1, 1, At, B1); PG8_BAR;
;             PG8_LDB(B0, 1, 0); PG8_SCHED; PG8_LDA(At, 1, 0); PG8_STAGE(PG8_SA(0, 1), a2 + hstep, voffA);
;             PG8_WAIT_L(8); PG8_BAR; PG8_WAIT_L(0); PG8_MMA(0, 0, At, B0); PG8_BAR; PG8_SCHED;
;             PG8_LDB(B1, 1, 1); PG8_STAGE(PG8_SB(1, 0), b3, voffB);
;             PG8_BAR; PG8_WAIT_L(0); PG8_MMA(0, 1, At, B1); PG8_BAR;
;             PG8_LDA(At, 1, 1); PG8_STAGE(PG8_SA(1, 0), a3, voffA);
	s_add_u32 s54, s42, 0x80000
	s_addc_u32 s55, s43, 0
	s_add_i32 s58, s48, s26
	v_lshl_add_u64 v[128:129], s[54:55], 0, v[178:179]
	s_mov_b32 m0, s58
	s_nop 0
	global_load_lds_dwordx4 v[128:129], off
	v_lshl_add_u64 v[128:129], s[54:55], 0, v[182:183]
	s_add_i32 m0, s58, 0x2000
	s_nop 0
	global_load_lds_dwordx4 v[128:129], off
	s_waitcnt vmcnt(6)
	s_barrier
	s_setprio 1
	v_mfma_f32_16x16x32_bf16 v[52:55], v[192:195], v[144:147], v[52:55]
	v_mfma_f32_16x16x32_bf16 v[48:51], v[200:203], v[144:147], v[48:51]
	v_mfma_f32_16x16x32_bf16 v[36:39], v[192:195], v[152:155], v[36:39]
	v_mfma_f32_16x16x32_bf16 v[32:35], v[200:203], v[152:155], v[32:35]
	v_mfma_f32_16x16x32_bf16 v[20:23], v[192:195], v[160:163], v[20:23]
	v_mfma_f32_16x16x32_bf16 v[16:19], v[200:203], v[160:163], v[16:19]
	v_mfma_f32_16x16x32_bf16 v[4:7], v[192:195], v[168:171], v[4:7]
	v_mfma_f32_16x16x32_bf16 v[0:3], v[200:203], v[168:171], v[0:3]
	v_mfma_f32_16x16x32_bf16 v[52:55], v[196:199], v[148:151], v[52:55]
	v_mfma_f32_16x16x32_bf16 v[48:51], v[210:213], v[148:151], v[48:51]
	v_mfma_f32_16x16x32_bf16 v[36:39], v[196:199], v[156:159], v[36:39]
	v_mfma_f32_16x16x32_bf16 v[32:35], v[210:213], v[156:159], v[32:35]
	v_mfma_f32_16x16x32_bf16 v[20:23], v[196:199], v[164:167], v[20:23]
	v_mfma_f32_16x16x32_bf16 v[16:19], v[210:213], v[164:167], v[16:19]
	v_mfma_f32_16x16x32_bf16 v[4:7], v[196:199], v[172:175], v[4:7]
	v_mfma_f32_16x16x32_bf16 v[0:3], v[210:213], v[172:175], v[0:3]
	s_setprio 0
	s_add_i32 s54, 0, 0x18000
	v_add_u32_e32 v140, s54, v205
	s_barrier
	ds_read_b128 v[128:131], v140
	ds_read_b128 v[132:135], v140 offset:1024
	ds_read_b128 v[136:139], v140 offset:2048
	ds_read_b128 v[140:143], v140 offset:3072
	s_add_u32 s44, s44, 0x80000
	s_addc_u32 s45, s45, 0
	s_mov_b32 m0, s25
	v_lshl_add_u64 v[192:193], s[44:45], 0, v[176:177]
	ds_read_b128 v[144:147], v207 offset:32768
	ds_read_b128 v[148:151], v207 offset:33792
	ds_read_b128 v[152:155], v207 offset:34816
	ds_read_b128 v[156:159], v207 offset:35840
	ds_read_b128 v[160:163], v207 offset:36864
	ds_read_b128 v[164:167], v207 offset:37888
	ds_read_b128 v[168:171], v207 offset:38912
	ds_read_b128 v[172:175], v207 offset:39936
	global_load_lds_dwordx4 v[192:193], off
	v_lshl_add_u64 v[192:193], s[44:45], 0, v[180:181]
	s_mov_b32 m0, s28
	s_nop 0
	global_load_lds_dwordx4 v[192:193], off
	s_waitcnt lgkmcnt(8)
	s_barrier
	s_waitcnt lgkmcnt(0)
	s_setprio 1
	s_waitcnt lgkmcnt(0)
	v_mfma_f32_16x16x32_bf16 v[124:127], v[128:131], v[144:147], v[124:127]
	v_mfma_f32_16x16x32_bf16 v[120:123], v[136:139], v[144:147], v[120:123]
	v_mfma_f32_16x16x32_bf16 v[108:111], v[128:131], v[152:155], v[108:111]
	v_mfma_f32_16x16x32_bf16 v[104:107], v[136:139], v[152:155], v[104:107]
	v_mfma_f32_16x16x32_bf16 v[92:95], v[128:131], v[160:163], v[92:95]
	v_mfma_f32_16x16x32_bf16 v[88:91], v[136:139], v[160:163], v[88:91]
	v_mfma_f32_16x16x32_bf16 v[76:79], v[128:131], v[168:171], v[76:79]
	v_mfma_f32_16x16x32_bf16 v[72:75], v[136:139], v[168:171], v[72:75]
	v_mfma_f32_16x16x32_bf16 v[124:127], v[132:135], v[148:151], v[124:127]
	v_mfma_f32_16x16x32_bf16 v[120:123], v[140:143], v[148:151], v[120:123]
	v_mfma_f32_16x16x32_bf16 v[108:111], v[132:135], v[156:159], v[108:111]
	v_mfma_f32_16x16x32_bf16 v[104:107], v[140:143], v[156:159], v[104:107]
	v_mfma_f32_16x16x32_bf16 v[92:95], v[132:135], v[164:167], v[92:95]
	v_mfma_f32_16x16x32_bf16 v[88:91], v[140:143], v[164:167], v[88:91]
	v_mfma_f32_16x16x32_bf16 v[76:79], v[132:135], v[172:175], v[76:79]
	v_mfma_f32_16x16x32_bf16 v[72:75], v[140:143], v[172:175], v[72:75]
	s_setprio 0
	s_barrier
	s_add_i32 s44, 0, 0x1c000
	s_add_i32 s45, s54, s26
	v_add_u32_e32 v210, s44, v205
	v_lshl_add_u64 v[214:215], v[214:215], 0, s[0:1]
	s_mov_b32 m0, s45
	ds_read_b128 v[192:195], v210
	ds_read_b128 v[196:199], v210 offset:1024
	ds_read_b128 v[200:203], v210 offset:2048
	ds_read_b128 v[210:213], v210 offset:3072
	global_load_lds_dwordx4 v[214:215], off
	v_lshl_add_u64 v[214:215], v[216:217], 0, s[0:1]
	s_add_i32 m0, s45, 0x2000
	s_nop 0
	global_load_lds_dwordx4 v[214:215], off
	s_barrier
	s_waitcnt lgkmcnt(0)
	s_setprio 1
	s_waitcnt lgkmcnt(0)
	v_mfma_f32_16x16x32_bf16 v[116:119], v[192:195], v[144:147], v[116:119]
	v_mfma_f32_16x16x32_bf16 v[112:115], v[200:203], v[144:147], v[112:115]
	v_mfma_f32_16x16x32_bf16 v[100:103], v[192:195], v[152:155], v[100:103]
	v_mfma_f32_16x16x32_bf16 v[96:99], v[200:203], v[152:155], v[96:99]
	v_mfma_f32_16x16x32_bf16 v[84:87], v[192:195], v[160:163], v[84:87]
	v_mfma_f32_16x16x32_bf16 v[80:83], v[200:203], v[160:163], v[80:83]
	v_mfma_f32_16x16x32_bf16 v[68:71], v[192:195], v[168:171], v[68:71]
	v_mfma_f32_16x16x32_bf16 v[64:67], v[200:203], v[168:171], v[64:67]
	v_mfma_f32_16x16x32_bf16 v[116:119], v[196:199], v[148:151], v[116:119]
	v_mfma_f32_16x16x32_bf16 v[112:115], v[210:213], v[148:151], v[112:115]
	v_mfma_f32_16x16x32_bf16 v[100:103], v[196:199], v[156:159], v[100:103]
	v_mfma_f32_16x16x32_bf16 v[96:99], v[210:213], v[156:159], v[96:99]
	v_mfma_f32_16x16x32_bf16 v[84:87], v[196:199], v[164:167], v[84:87]
	v_mfma_f32_16x16x32_bf16 v[80:83], v[210:213], v[164:167], v[80:83]
	v_mfma_f32_16x16x32_bf16 v[68:71], v[196:199], v[172:175], v[68:71]
	v_mfma_f32_16x16x32_bf16 v[64:67], v[210:213], v[172:175], v[64:67]
	s_setprio 0
	s_mov_b32 m0, s29
	v_lshl_add_u64 v[214:215], v[218:219], 0, s[0:1]
	s_barrier
	ds_read_b128 v[144:147], v207 offset:49152
	ds_read_b128 v[148:151], v207 offset:50176
	ds_read_b128 v[152:155], v207 offset:51200
	ds_read_b128 v[156:159], v207 offset:52224
	ds_read_b128 v[160:163], v207 offset:53248
	ds_read_b128 v[164:167], v207 offset:54272
	ds_read_b128 v[168:171], v207 offset:55296
	ds_read_b128 v[172:175], v207 offset:56320
	global_load_lds_dwordx4 v[214:215], off
	v_lshl_add_u64 v[214:215], v[220:221], 0, s[0:1]
	s_mov_b32 m0, s34
	s_nop 0
	global_load_lds_dwordx4 v[214:215], off
	s_barrier
; __device__ __forceinline__ float bflo(unsigned w) { return __uint_as_float(w << 16); }
; __device__ __forceinline__ float bfhi(unsigned w) { return __uint_as_float(w & 0xffff0000u); }
; #define PG8_STAGE(bufoff, gbase, voff) do { _Pragma("unroll") for (int _i = 0; _i < 2; ++_i) \
;         __builtin_amdgcn_global_load_lds((const unsigned*)((const char*)(gbase) + (voff)[_i]), (LAS unsigned*)(lds + (bufoff) + ldsw + _i * 8192), 16, 0, 0); } while (0)
; #define PG8_MMA(ai, bj, At, Bt) do { __builtin_amdgcn_s_setprio(1); _Pragma("unroll") for (int m = 0; m < 4; ++m) _Pragma("unroll") for (int n = 0; n < 2; ++n) _Pragma("unroll") for (int k = 0; k < 2; ++k) \
;         acc[ai][bj][m][n] = __builtin_amdgcn_mfma_f32_16x16x32_bf16(Bt[n][k], At[m][k], acc[ai][bj][m][n], 0, 0, 0); __builtin_amdgcn_s_setprio(0); } while (0)
; #define PG8_WAIT_V(n) asm volatile("s_waitcnt vmcnt(" #n ")" ::: "memory")
; #define PG8_WAIT_L(n) asm volatile("s_waitcnt lgkmcnt(" #n ")" ::: "memory")
; #define PG8_BAR __builtin_amdgcn_s_barrier()
; template <class Epi, bool KS0 = false>
; __device__ __forceinline__ void gemm_phase(const int WID, LAS unsigned char* lds, const Gemm g, const StaticOrder& S, const Epi& E) {
;     ...
;             PG8_BAR; PG8_WAIT_L(0); PG8_MMA(1, 0, At, B0); PG8_BAR; PG8_SCHED;
;             PG8_STAGE(PG8_SB(1, 1), b3 + hstep, voffB);
;             PG8_WAIT_V(6); PG8_BAR; PG8_MMA(1, 1, At, B1); PG8_BAR;
;         }
;     __device__ __forceinline__ void operator()(f32x4 (&acc)[2][2][4][2], const Unit& u, int wr, int wc, int fr, int fq) const {
;         const int row0 = u.pm * BM + wr * 64 + fr, col0 = u.pn * BM + wc * 32 + 8 * fq;
; #pragma unroll
;         for (int ai = 0; ai < 2; ++ai) {
;             f32x4 r[4][2][2];
; #pragma unroll
;             for (int m = 0; m < 4; ++m)
; #pragma unroll
;                 for (int bj = 0; bj < 2; ++bj) { const size_t o = (size_t)(row0 + ai * HALF + m * 16) * DM + col0 + bj * HALF;
;                     if (RB) { const u32x4 w = *(const u32x4*)((const bf16_t*)res + o); r[m][bj][0] = (f32x4){bflo(w.x), bfhi(w.x), bflo(w.y), bfhi(w.y)}; r[m][bj][1] = (f32x4){bflo(w.z), bfhi(w.z), bflo(w.w), bfhi(w.w)}; }
;                     else { r[m][bj][0] = __builtin_nontemporal_load((const f32x4*)((const float*)res + o)); r[m][bj][1] = __builtin_nontemporal_load((const f32x4*)((const float*)res + o + 4)); } }
	s_waitcnt lgkmcnt(0)
	s_setprio 1
	s_waitcnt lgkmcnt(0)
	v_mfma_f32_16x16x32_bf16 v[60:63], v[128:131], v[144:147], v[60:63]
	v_mfma_f32_16x16x32_bf16 v[56:59], v[136:139], v[144:147], v[56:59]
	v_mfma_f32_16x16x32_bf16 v[44:47], v[128:131], v[152:155], v[44:47]
	v_mfma_f32_16x16x32_bf16 v[40:43], v[136:139], v[152:155], v[40:43]
	v_mfma_f32_16x16x32_bf16 v[28:31], v[128:131], v[160:163], v[28:31]
	v_mfma_f32_16x16x32_bf16 v[24:27], v[136:139], v[160:163], v[24:27]
	v_mfma_f32_16x16x32_bf16 v[12:15], v[128:131], v[168:171], v[12:15]
	v_mfma_f32_16x16x32_bf16 v[8:11], v[136:139], v[168:171], v[8:11]
	v_mfma_f32_16x16x32_bf16 v[60:63], v[132:135], v[148:151], v[60:63]
	v_mfma_f32_16x16x32_bf16 v[56:59], v[140:143], v[148:151], v[56:59]
	v_mfma_f32_16x16x32_bf16 v[44:47], v[132:135], v[156:159], v[44:47]
	v_mfma_f32_16x16x32_bf16 v[40:43], v[140:143], v[156:159], v[40:43]
	v_mfma_f32_16x16x32_bf16 v[28:31], v[132:135], v[164:167], v[28:31]
	v_mfma_f32_16x16x32_bf16 v[24:27], v[140:143], v[164:167], v[24:27]
	v_mfma_f32_16x16x32_bf16 v[12:15], v[132:135], v[172:175], v[12:15]
	v_mfma_f32_16x16x32_bf16 v[8:11], v[140:143], v[172:175], v[8:11]
	s_setprio 0
	s_barrier
	s_add_u32 s42, s42, 0x80080
	s_addc_u32 s43, s43, 0
	s_add_i32 s44, s44, s26
	v_lshl_add_u64 v[128:129], s[42:43], 0, v[178:179]
	s_mov_b32 m0, s44
	s_nop 0
	global_load_lds_dwordx4 v[128:129], off
	v_lshl_add_u64 v[128:129], s[42:43], 0, v[182:183]
	s_add_i32 m0, s44, 0x2000
	s_nop 0
	global_load_lds_dwordx4 v[128:129], off
	s_waitcnt vmcnt(6)
	s_barrier
	s_setprio 1
	v_mfma_f32_16x16x32_bf16 v[52:55], v[192:195], v[144:147], v[52:55]
	v_mfma_f32_16x16x32_bf16 v[48:51], v[200:203], v[144:147], v[48:51]
	v_mfma_f32_16x16x32_bf16 v[36:39], v[192:195], v[152:155], v[36:39]
	v_mfma_f32_16x16x32_bf16 v[32:35], v[200:203], v[152:155], v[32:35]
	v_mfma_f32_16x16x32_bf16 v[20:23], v[192:195], v[160:163], v[20:23]
	v_mfma_f32_16x16x32_bf16 v[16:19], v[200:203], v[160:163], v[16:19]
	v_mfma_f32_16x16x32_bf16 v[4:7], v[192:195], v[168:171], v[4:7]
	v_mfma_f32_16x16x32_bf16 v[0:3], v[200:203], v[168:171], v[0:3]
	v_mfma_f32_16x16x32_bf16 v[52:55], v[196:199], v[148:151], v[52:55]
	v_mfma_f32_16x16x32_bf16 v[48:51], v[210:213], v[148:151], v[48:51]
	v_mfma_f32_16x16x32_bf16 v[36:39], v[196:199], v[156:159], v[36:39]
	v_mfma_f32_16x16x32_bf16 v[32:35], v[210:213], v[156:159], v[32:35]
	v_mfma_f32_16x16x32_bf16 v[20:23], v[196:199], v[164:167], v[20:23]
	v_mfma_f32_16x16x32_bf16 v[16:19], v[210:213], v[164:167], v[16:19]
	v_mfma_f32_16x16x32_bf16 v[4:7], v[196:199], v[172:175], v[4:7]
	v_mfma_f32_16x16x32_bf16 v[0:3], v[210:213], v[172:175], v[0:3]
	s_setprio 0
	s_add_i32 s53, s53, 2
	s_add_u32 s20, s20, 0x100
	s_addc_u32 s21, s21, 0
	s_add_u32 s51, s51, 0x100
	s_addc_u32 s52, s52, 0
	s_cmp_gt_u32 s53, 29
	s_barrier
	s_cbranch_scc0 .LBB0_670
	v_mbcnt_lo_u32_b32 v128, -1, 0
	v_mbcnt_hi_u32_b32 v128, -1, v128
	s_lshl_b32 s9, s18, 8
	v_ashrrev_i32_e32 v210, 4, v128
	v_and_b32_e32 v128, 15, v128
	s_add_i32 s9, s9, s22
	v_readlane_b32 s11, v254, 19
	v_add_u32_e32 v194, s9, v128
	s_lshl_b32 s9, s2, 8
	s_or_b32 s9, s9, s11
	v_lshl_add_u32 v192, v210, 3, s9
	v_ashrrev_i32_e32 v193, 31, v192
	v_ashrrev_i32_e32 v195, 31, v194
	v_lshl_add_u64 v[196:197], v[192:193], 2, s[56:57]
	v_lshlrev_b64 v[128:129], 13, v[194:195]
	v_lshl_add_u64 v[128:129], v[196:197], 0, v[128:129]
	global_load_dwordx4 v[212:215], v[128:129], off nt
	global_load_dwordx4 v[216:219], v[128:129], off offset:16 nt
	global_load_dwordx4 v[220:223], v[128:129], off offset:512 nt
	global_load_dwordx4 v[224:227], v[128:129], off offset:528 nt
	v_add_u32_e32 v202, 16, v194
	v_add_u32_e32 v200, 32, v194
	v_add_u32_e32 v198, 48, v194
	v_ashrrev_i32_e32 v203, 31, v202
	v_ashrrev_i32_e32 v201, 31, v200
	v_ashrrev_i32_e32 v199, 31, v198
	v_lshlrev_b64 v[128:129], 13, v[202:203]
	v_lshlrev_b64 v[130:131], 13, v[200:201]
	v_lshlrev_b64 v[132:133], 13, v[198:199]
	v_lshl_add_u64 v[128:129], v[196:197], 0, v[128:129]
	v_lshl_add_u64 v[130:131], v[196:197], 0, v[130:131]
	v_lshl_add_u64 v[132:133], v[196:197], 0, v[132:133]
	global_load_dwordx4 v[168:171], v[128:129], off offset:16 nt
	global_load_dwordx4 v[172:175], v[128:129], off nt
	global_load_dwordx4 v[160:163], v[128:129], off offset:528 nt
	global_load_dwordx4 v[164:167], v[128:129], off offset:512 nt
	global_load_dwordx4 v[152:155], v[130:131], off offset:16 nt
	global_load_dwordx4 v[156:159], v[130:131], off nt
	global_load_dwordx4 v[144:147], v[130:131], off offset:528 nt
	global_load_dwordx4 v[148:151], v[130:131], off offset:512 nt
	global_load_dwordx4 v[136:139], v[132:133], off offset:16 nt
	global_load_dwordx4 v[140:143], v[132:133], off nt
	s_nop 0
	global_load_dwordx4 v[128:131], v[132:133], off offset:528 nt
	s_nop 0
	global_load_dwordx4 v[132:135], v[132:133], off offset:512 nt
	v_and_b32_e32 v228, 64, v209
	v_xor_b32_e32 v211, 16, v209
	v_add_u32_e32 v228, 64, v228
	v_xor_b32_e32 v229, 32, v209
	v_cmp_lt_i32_e32 vcc, v211, v228
	s_lshl_b32 s18, s2, 2
	s_ashr_i32 s19, s18, 31
	v_cndmask_b32_e32 v211, v209, v211, vcc
	v_cmp_lt_i32_e32 vcc, v229, v228
	s_waitcnt vmcnt(0)
; __device__ __forceinline__ unsigned cvt_pk_bf16(float lo, float hi) { unsigned r; asm volatile("v_cvt_pk_bf16_f32 %0, %1, %2" : "=v"(r) : "v"(lo), "v"(hi)); return r; }
;     __device__ __forceinline__ void operator()(f32x4 (&acc)[2][2][4][2], const Unit& u, int wr, int wc, int fr, int fq) const {
;     ...
;             for (int m = 0; m < 4; ++m) { const int row = row0 + ai * HALF + m * 16; const size_t off = (size_t)row * DM + col0; float s = 0.f;
; #pragma unroll
;                 for (int bj = 0; bj < 2; ++bj) { const f32x4 v0 = acc[ai][bj][m][0] + r[m][bj][0], v1 = acc[ai][bj][m][1] + r[m][bj][1];
;                     u32x4 w; w.x = cvt_pk_bf16(v0[0], v0[1]); w.y = cvt_pk_bf16(v0[2], v0[3]); w.z = cvt_pk_bf16(v1[0], v1[1]); w.w = cvt_pk_bf16(v1[2], v1[3]);
;                     *(u32x4*)(outb + off + bj * HALF) = w;
;                     s += ((v0[0] * v0[0] + v0[1] * v0[1]) + (v0[2] * v0[2] + v0[3] * v0[3])) + ((v1[0] * v1[0] + v1[1] * v1[1]) + (v1[2] * v1[2] + v1[3] * v1[3])); }
;                 s += __shfl_xor(s, 16); s += __shfl_xor(s, 32);
;                 if (fq == 0) ssq[(size_t)row * 32 + u.pn * 4 + wc] = s; }
	v_pk_add_f32 v[126:127], v[126:127], v[214:215]
	v_pk_add_f32 v[124:125], v[124:125], v[212:213]
	v_pk_add_f32 v[122:123], v[122:123], v[218:219]
	v_pk_add_f32 v[120:121], v[120:121], v[216:217]
	v_pk_add_f32 v[118:119], v[118:119], v[222:223]
	v_pk_add_f32 v[116:117], v[116:117], v[220:221]
	v_pk_add_f32 v[212:213], v[114:115], v[226:227]
	v_pk_add_f32 v[214:215], v[112:113], v[224:225]
	v_cndmask_b32_e32 v230, v209, v229, vcc
	v_cmp_eq_u32_e32 vcc, 0, v210
	v_lshlrev_b32_e32 v210, 2, v211
	v_cvt_pk_bf16_f32 v112, v124, v125
	v_cvt_pk_bf16_f32 v113, v126, v127
	v_mul_f32_e32 v114, v125, v125
	v_mul_f32_e32 v115, v127, v127
	v_mul_f32_e32 v125, v121, v121
	v_mul_f32_e32 v127, v123, v123
	v_mul_f32_e32 v211, v117, v117
	v_mul_f32_e32 v216, v119, v119
	v_mul_f32_e32 v217, v215, v215
	v_mul_f32_e32 v218, v213, v213
	v_fmac_f32_e32 v114, v124, v124
	v_fmac_f32_e32 v115, v126, v126
	v_fmac_f32_e32 v125, v120, v120
	v_fmac_f32_e32 v127, v122, v122
	v_fmac_f32_e32 v211, v116, v116
	v_fmac_f32_e32 v216, v118, v118
	v_fmac_f32_e32 v217, v214, v214
	v_fmac_f32_e32 v218, v212, v212
	v_add_f32_e32 v114, v114, v115
	v_add_f32_e32 v115, v125, v127
	v_add_f32_e32 v124, v211, v216
	v_add_f32_e32 v125, v217, v218
	v_add_f32_e32 v114, v114, v115
	v_add_f32_e32 v115, v124, v125
	v_add_f32_e32 v124, v114, v115
	ds_bpermute_b32 v125, v210, v124
	v_lshlrev_b64 v[228:229], 12, v[194:195]
	v_lshl_add_u64 v[228:229], s[6:7], 0, v[228:229]
	v_lshl_add_u64 v[228:229], v[192:193], 1, v[228:229]
	v_cvt_pk_bf16_f32 v114, v120, v121
	v_cvt_pk_bf16_f32 v115, v122, v123
	global_store_dwordx4 v[228:229], v[112:115], off sc1
	v_lshlrev_b32_e32 v120, 2, v230
	s_waitcnt lgkmcnt(0)
	v_add_f32_e32 v112, v124, v125
	ds_bpermute_b32 v113, v120, v112
	v_cvt_pk_bf16_f32 v114, v116, v117
	v_cvt_pk_bf16_f32 v115, v118, v119
	v_cvt_pk_bf16_f32 v116, v214, v215
	v_cvt_pk_bf16_f32 v117, v212, v213
	global_store_dwordx4 v[228:229], v[114:117], off offset:256 sc1
	s_and_saveexec_b64 s[20:21], vcc
	s_cbranch_execz .LBB0_673
	v_lshlrev_b64 v[114:115], 7, v[194:195]
	v_lshl_add_u64 v[114:115], s[16:17], 0, v[114:115]
	v_lshl_add_u64 v[114:115], s[18:19], 2, v[114:115]
	s_lshl_b32 s2, s27, 2
	v_lshl_add_u64 v[114:115], v[114:115], 0, s[2:3]
	s_waitcnt lgkmcnt(0)
	v_add_f32_e32 v112, v112, v113
	global_store_dword v[114:115], v112, off
.LBB0_673:
	s_or_b64 exec, exec, s[20:21]
	v_pk_add_f32 v[108:109], v[108:109], v[172:173]
	v_pk_add_f32 v[110:111], v[110:111], v[174:175]
	v_pk_add_f32 v[116:117], v[104:105], v[168:169]
	v_cvt_pk_bf16_f32 v104, v108, v109
	v_mul_f32_e32 v109, v109, v109
	v_fmac_f32_e32 v109, v108, v108
	v_mul_f32_e32 v108, v111, v111
	v_pk_add_f32 v[114:115], v[106:107], v[170:171]
	v_fmac_f32_e32 v108, v110, v110
	v_cvt_pk_bf16_f32 v105, v110, v111
	v_add_f32_e32 v108, v109, v108
	v_mul_f32_e32 v109, v117, v117
	v_mul_f32_e32 v110, v115, v115
	v_fmac_f32_e32 v109, v116, v116
	v_fmac_f32_e32 v110, v114, v114
	v_pk_add_f32 v[102:103], v[102:103], v[166:167]
	v_pk_add_f32 v[100:101], v[100:101], v[164:165]
	v_add_f32_e32 v109, v109, v110
	v_pk_add_f32 v[110:111], v[96:97], v[160:161]
	v_mul_f32_e32 v96, v101, v101
	v_mul_f32_e32 v97, v103, v103
	v_cvt_pk_bf16_f32 v106, v116, v117
	v_cvt_pk_bf16_f32 v107, v114, v115
	v_add_f32_e32 v114, v108, v109
	v_pk_add_f32 v[108:109], v[98:99], v[162:163]
	v_fmac_f32_e32 v96, v100, v100
	v_fmac_f32_e32 v97, v102, v102
	v_add_f32_e32 v96, v96, v97
	v_mul_f32_e32 v97, v111, v111
	v_mul_f32_e32 v98, v109, v109
	v_fmac_f32_e32 v97, v110, v110
	v_fmac_f32_e32 v98, v108, v108
	v_add_f32_e32 v97, v97, v98
	v_add_f32_e32 v96, v96, v97
	v_add_f32_e32 v99, v114, v96
	ds_bpermute_b32 v114, v210, v99
	s_waitcnt lgkmcnt(1)
	v_lshlrev_b64 v[112:113], 12, v[202:203]
	v_lshl_add_u64 v[96:97], s[6:7], 0, v[112:113]
	v_lshl_add_u64 v[112:113], v[192:193], 1, v[96:97]
	global_store_dwordx4 v[112:113], v[104:107], off sc1
	s_waitcnt lgkmcnt(0)
	v_add_f32_e32 v96, v99, v114
	ds_bpermute_b32 v97, v120, v96
	v_cvt_pk_bf16_f32 v98, v100, v101
	v_cvt_pk_bf16_f32 v99, v102, v103
	v_cvt_pk_bf16_f32 v100, v110, v111
	v_cvt_pk_bf16_f32 v101, v108, v109
	global_store_dwordx4 v[112:113], v[98:101], off offset:256 sc1
	s_and_saveexec_b64 s[20:21], vcc
	s_cbranch_execz .LBB0_675
	v_lshlrev_b64 v[98:99], 7, v[202:203]
	v_lshl_add_u64 v[98:99], s[16:17], 0, v[98:99]
	v_lshl_add_u64 v[98:99], s[18:19], 2, v[98:99]
	s_lshl_b32 s2, s27, 2
	v_lshl_add_u64 v[98:99], v[98:99], 0, s[2:3]
	s_waitcnt lgkmcnt(0)
	v_add_f32_e32 v96, v96, v97
	global_store_dword v[98:99], v96, off
.LBB0_675:
	s_or_b64 exec, exec, s[20:21]
	v_pk_add_f32 v[92:93], v[92:93], v[156:157]
	v_pk_add_f32 v[94:95], v[94:95], v[158:159]
	v_pk_add_f32 v[100:101], v[88:89], v[152:153]
	v_cvt_pk_bf16_f32 v88, v92, v93
	v_mul_f32_e32 v93, v93, v93
	v_fmac_f32_e32 v93, v92, v92
	v_mul_f32_e32 v92, v95, v95
	v_pk_add_f32 v[98:99], v[90:91], v[154:155]
	v_fmac_f32_e32 v92, v94, v94
	v_cvt_pk_bf16_f32 v89, v94, v95
	v_add_f32_e32 v92, v93, v92
	v_mul_f32_e32 v93, v101, v101
	v_mul_f32_e32 v94, v99, v99
	v_fmac_f32_e32 v93, v100, v100
	v_fmac_f32_e32 v94, v98, v98
	v_pk_add_f32 v[86:87], v[86:87], v[150:151]
	v_pk_add_f32 v[84:85], v[84:85], v[148:149]
	v_add_f32_e32 v93, v93, v94
	v_pk_add_f32 v[94:95], v[80:81], v[144:145]
	v_mul_f32_e32 v80, v85, v85
	v_mul_f32_e32 v81, v87, v87
	v_cvt_pk_bf16_f32 v90, v100, v101
	v_cvt_pk_bf16_f32 v91, v98, v99
	v_add_f32_e32 v98, v92, v93
	v_pk_add_f32 v[92:93], v[82:83], v[146:147]
	v_fmac_f32_e32 v80, v84, v84
	v_fmac_f32_e32 v81, v86, v86
	v_add_f32_e32 v80, v80, v81
	v_mul_f32_e32 v81, v95, v95
	v_mul_f32_e32 v82, v93, v93
	v_fmac_f32_e32 v81, v94, v94
	v_fmac_f32_e32 v82, v92, v92
	v_add_f32_e32 v81, v81, v82
	v_add_f32_e32 v80, v80, v81
	v_add_f32_e32 v83, v98, v80
	ds_bpermute_b32 v98, v210, v83
	s_waitcnt lgkmcnt(1)
	v_lshlrev_b64 v[96:97], 12, v[200:201]
	v_lshl_add_u64 v[80:81], s[6:7], 0, v[96:97]
	v_lshl_add_u64 v[96:97], v[192:193], 1, v[80:81]
	global_store_dwordx4 v[96:97], v[88:91], off sc1
	s_waitcnt lgkmcnt(0)
	v_add_f32_e32 v80, v83, v98
	ds_bpermute_b32 v81, v120, v80
	v_cvt_pk_bf16_f32 v82, v84, v85
	v_cvt_pk_bf16_f32 v83, v86, v87
	v_cvt_pk_bf16_f32 v84, v94, v95
	v_cvt_pk_bf16_f32 v85, v92, v93
	global_store_dwordx4 v[96:97], v[82:85], off offset:256 sc1
	s_and_saveexec_b64 s[20:21], vcc
	s_cbranch_execz .LBB0_677
	v_lshlrev_b64 v[82:83], 7, v[200:201]
	v_lshl_add_u64 v[82:83], s[16:17], 0, v[82:83]
	v_lshl_add_u64 v[82:83], s[18:19], 2, v[82:83]
	s_lshl_b32 s2, s27, 2
	v_lshl_add_u64 v[82:83], v[82:83], 0, s[2:3]
	s_waitcnt lgkmcnt(0)
	v_add_f32_e32 v80, v80, v81
	global_store_dword v[82:83], v80, off
; __device__ __forceinline__ unsigned cvt_pk_bf16(float lo, float hi) { unsigned r; asm volatile("v_cvt_pk_bf16_f32 %0, %1, %2" : "=v"(r) : "v"(lo), "v"(hi)); return r; }
; __device__ __forceinline__ float bflo(unsigned w) { return __uint_as_float(w << 16); }
; __device__ __forceinline__ float bfhi(unsigned w) { return __uint_as_float(w & 0xffff0000u); }
;     __device__ __forceinline__ void operator()(f32x4 (&acc)[2][2][4][2], const Unit& u, int wr, int wc, int fr, int fq) const {
;     ...
;                 for (int bj = 0; bj < 2; ++bj) { const size_t o = (size_t)(row0 + ai * HALF + m * 16) * DM + col0 + bj * HALF;
;                     if (RB) { const u32x4 w = *(const u32x4*)((const bf16_t*)res + o); r[m][bj][0] = (f32x4){bflo(w.x), bfhi(w.x), bflo(w.y), bfhi(w.y)}; r[m][bj][1] = (f32x4){bflo(w.z), bfhi(w.z), bflo(w.w), bfhi(w.w)}; }
;                     else { r[m][bj][0] = __builtin_nontemporal_load((const f32x4*)((const float*)res + o)); r[m][bj][1] = __builtin_nontemporal_load((const f32x4*)((const float*)res + o + 4)); } }
; #pragma unroll
;             for (int m = 0; m < 4; ++m) { const int row = row0 + ai * HALF + m * 16; const size_t off = (size_t)row * DM + col0; float s = 0.f;
; #pragma unroll
;                 for (int bj = 0; bj < 2; ++bj) { const f32x4 v0 = acc[ai][bj][m][0] + r[m][bj][0], v1 = acc[ai][bj][m][1] + r[m][bj][1];
;                     u32x4 w; w.x = cvt_pk_bf16(v0[0], v0[1]); w.y = cvt_pk_bf16(v0[2], v0[3]); w.z = cvt_pk_bf16(v1[0], v1[1]); w.w = cvt_pk_bf16(v1[2], v1[3]);
;                     *(u32x4*)(outb + off + bj * HALF) = w;
;                     s += ((v0[0] * v0[0] + v0[1] * v0[1]) + (v0[2] * v0[2] + v0[3] * v0[3])) + ((v1[0] * v1[0] + v1[1] * v1[1]) + (v1[2] * v1[2] + v1[3] * v1[3])); }
;                 s += __shfl_xor(s, 16); s += __shfl_xor(s, 32);
;                 if (fq == 0) ssq[(size_t)row * 32 + u.pn * 4 + wc] = s; }
;             asm volatile("" ::: "memory"); }
.LBB0_677:
	s_or_b64 exec, exec, s[20:21]
	v_pk_add_f32 v[76:77], v[76:77], v[140:141]
	v_pk_add_f32 v[78:79], v[78:79], v[142:143]
	v_pk_add_f32 v[84:85], v[72:73], v[136:137]
	v_cvt_pk_bf16_f32 v72, v76, v77
	v_mul_f32_e32 v77, v77, v77
	v_fmac_f32_e32 v77, v76, v76
	v_mul_f32_e32 v76, v79, v79
	v_pk_add_f32 v[82:83], v[74:75], v[138:139]
	v_fmac_f32_e32 v76, v78, v78
	v_cvt_pk_bf16_f32 v73, v78, v79
	v_add_f32_e32 v76, v77, v76
	v_mul_f32_e32 v77, v85, v85
	v_mul_f32_e32 v78, v83, v83
	v_fmac_f32_e32 v77, v84, v84
	v_fmac_f32_e32 v78, v82, v82
	v_pk_add_f32 v[70:71], v[70:71], v[134:135]
	v_pk_add_f32 v[68:69], v[68:69], v[132:133]
	v_add_f32_e32 v77, v77, v78
	v_pk_add_f32 v[78:79], v[64:65], v[128:129]
	v_mul_f32_e32 v64, v69, v69
	v_mul_f32_e32 v65, v71, v71
	v_cvt_pk_bf16_f32 v74, v84, v85
	v_cvt_pk_bf16_f32 v75, v82, v83
	v_add_f32_e32 v82, v76, v77
	v_pk_add_f32 v[76:77], v[66:67], v[130:131]
	v_fmac_f32_e32 v64, v68, v68
	v_fmac_f32_e32 v65, v70, v70
	v_add_f32_e32 v64, v64, v65
	v_mul_f32_e32 v65, v79, v79
	v_mul_f32_e32 v66, v77, v77
	v_fmac_f32_e32 v65, v78, v78
	v_fmac_f32_e32 v66, v76, v76
	v_add_f32_e32 v65, v65, v66
	v_add_f32_e32 v64, v64, v65
	v_add_f32_e32 v67, v82, v64
	ds_bpermute_b32 v82, v210, v67
	s_waitcnt lgkmcnt(1)
	v_lshlrev_b64 v[80:81], 12, v[198:199]
	v_lshl_add_u64 v[64:65], s[6:7], 0, v[80:81]
	v_lshl_add_u64 v[80:81], v[192:193], 1, v[64:65]
	global_store_dwordx4 v[80:81], v[72:75], off sc1
	s_waitcnt lgkmcnt(0)
	v_add_f32_e32 v64, v67, v82
	ds_bpermute_b32 v65, v120, v64
	v_cvt_pk_bf16_f32 v66, v68, v69
	v_cvt_pk_bf16_f32 v67, v70, v71
	v_cvt_pk_bf16_f32 v68, v78, v79
	v_cvt_pk_bf16_f32 v69, v76, v77
	global_store_dwordx4 v[80:81], v[66:69], off offset:256 sc1
	s_and_saveexec_b64 s[20:21], vcc
	s_cbranch_execz .LBB0_679
	v_lshlrev_b64 v[66:67], 7, v[198:199]
	v_lshl_add_u64 v[66:67], s[16:17], 0, v[66:67]
	v_lshl_add_u64 v[66:67], s[18:19], 2, v[66:67]
	s_lshl_b32 s2, s27, 2
	v_lshl_add_u64 v[66:67], v[66:67], 0, s[2:3]
	s_waitcnt lgkmcnt(0)
	v_add_f32_e32 v64, v64, v65
	global_store_dword v[66:67], v64, off
.LBB0_679:
	s_or_b64 exec, exec, s[20:21]
	v_add_u32_e32 v118, 0x80, v194
	v_ashrrev_i32_e32 v119, 31, v118
	s_waitcnt lgkmcnt(0)
	v_lshlrev_b64 v[64:65], 13, v[118:119]
	v_lshl_add_u64 v[64:65], v[196:197], 0, v[64:65]
	global_load_dwordx4 v[122:125], v[64:65], off nt
	global_load_dwordx4 v[126:129], v[64:65], off offset:16 nt
	global_load_dwordx4 v[130:133], v[64:65], off offset:512 nt
	global_load_dwordx4 v[134:137], v[64:65], off offset:528 nt
	v_add_u32_e32 v116, 0x90, v194
	v_add_u32_e32 v114, 0xa0, v194
	v_add_u32_e32 v112, 0xb0, v194
	v_ashrrev_i32_e32 v117, 31, v116
	v_ashrrev_i32_e32 v115, 31, v114
	v_ashrrev_i32_e32 v113, 31, v112
	v_lshlrev_b64 v[64:65], 13, v[116:117]
	v_lshlrev_b64 v[66:67], 13, v[114:115]
	v_lshlrev_b64 v[68:69], 13, v[112:113]
	v_lshl_add_u64 v[64:65], v[196:197], 0, v[64:65]
	v_lshl_add_u64 v[66:67], v[196:197], 0, v[66:67]
	v_lshl_add_u64 v[68:69], v[196:197], 0, v[68:69]
	global_load_dwordx4 v[104:107], v[64:65], off offset:16 nt
	global_load_dwordx4 v[108:111], v[64:65], off nt
	global_load_dwordx4 v[96:99], v[64:65], off offset:528 nt
	global_load_dwordx4 v[100:103], v[64:65], off offset:512 nt
	global_load_dwordx4 v[88:91], v[66:67], off offset:16 nt
	global_load_dwordx4 v[92:95], v[66:67], off nt
	global_load_dwordx4 v[80:83], v[66:67], off offset:528 nt
	global_load_dwordx4 v[84:87], v[66:67], off offset:512 nt
	global_load_dwordx4 v[72:75], v[68:69], off offset:16 nt
	global_load_dwordx4 v[76:79], v[68:69], off nt
	s_nop 0
	global_load_dwordx4 v[64:67], v[68:69], off offset:528 nt
	s_nop 0
	global_load_dwordx4 v[68:71], v[68:69], off offset:512 nt
	v_lshlrev_b64 v[138:139], 12, v[118:119]
	s_waitcnt vmcnt(15)
	v_pk_add_f32 v[62:63], v[62:63], v[124:125]
	v_pk_add_f32 v[60:61], v[60:61], v[122:123]
	s_waitcnt vmcnt(14)
	v_pk_add_f32 v[58:59], v[58:59], v[128:129]
	v_pk_add_f32 v[56:57], v[56:57], v[126:127]
	s_waitcnt vmcnt(13)
	v_pk_add_f32 v[54:55], v[54:55], v[132:133]
	v_pk_add_f32 v[52:53], v[52:53], v[130:131]
	s_waitcnt vmcnt(12)
	v_pk_add_f32 v[122:123], v[50:51], v[136:137]
	v_pk_add_f32 v[124:125], v[48:49], v[134:135]
	v_cvt_pk_bf16_f32 v48, v60, v61
	v_cvt_pk_bf16_f32 v49, v62, v63
	v_cvt_pk_bf16_f32 v50, v56, v57
	v_cvt_pk_bf16_f32 v51, v58, v59
	v_mul_f32_e32 v61, v61, v61
	v_mul_f32_e32 v63, v63, v63
	v_mul_f32_e32 v57, v57, v57
	v_mul_f32_e32 v59, v59, v59
	v_mul_f32_e32 v121, v53, v53
	v_mul_f32_e32 v126, v55, v55
	v_mul_f32_e32 v127, v125, v125
	v_mul_f32_e32 v128, v123, v123
	v_fmac_f32_e32 v61, v60, v60
	v_fmac_f32_e32 v63, v62, v62
	v_fmac_f32_e32 v57, v56, v56
	v_fmac_f32_e32 v59, v58, v58
	v_fmac_f32_e32 v121, v52, v52
	v_fmac_f32_e32 v126, v54, v54
	v_fmac_f32_e32 v127, v124, v124
	v_fmac_f32_e32 v128, v122, v122
	v_add_f32_e32 v56, v61, v63
	v_add_f32_e32 v57, v57, v59
	v_add_f32_e32 v58, v121, v126
	v_add_f32_e32 v59, v127, v128
	v_add_f32_e32 v56, v56, v57
	v_add_f32_e32 v57, v58, v59
	v_add_f32_e32 v58, v56, v57
	ds_bpermute_b32 v59, v210, v58
	v_lshl_add_u64 v[56:57], s[6:7], 0, v[138:139]
	v_lshl_add_u64 v[56:57], v[192:193], 1, v[56:57]
	global_store_dwordx4 v[56:57], v[48:51], off sc1
	s_waitcnt lgkmcnt(0)
	s_nop 0
	v_add_f32_e32 v48, v58, v59
	ds_bpermute_b32 v49, v120, v48
	v_cvt_pk_bf16_f32 v50, v52, v53
	v_cvt_pk_bf16_f32 v51, v54, v55
	v_cvt_pk_bf16_f32 v52, v124, v125
	v_cvt_pk_bf16_f32 v53, v122, v123
	global_store_dwordx4 v[56:57], v[50:53], off offset:256 sc1
	s_and_saveexec_b64 s[20:21], vcc
	s_cbranch_execz .LBB0_681
	v_lshlrev_b64 v[50:51], 7, v[118:119]
	v_lshl_add_u64 v[50:51], s[16:17], 0, v[50:51]
	v_lshl_add_u64 v[50:51], s[18:19], 2, v[50:51]
	s_lshl_b32 s2, s27, 2
	v_lshl_add_u64 v[50:51], v[50:51], 0, s[2:3]
	s_waitcnt lgkmcnt(0)
	v_add_f32_e32 v48, v48, v49
	global_store_dword v[50:51], v48, off
; __device__ __forceinline__ unsigned cvt_pk_bf16(float lo, float hi) { unsigned r; asm volatile("v_cvt_pk_bf16_f32 %0, %1, %2" : "=v"(r) : "v"(lo), "v"(hi)); return r; }
;     __device__ __forceinline__ void operator()(f32x4 (&acc)[2][2][4][2], const Unit& u, int wr, int wc, int fr, int fq) const {
;     ...
;             for (int m = 0; m < 4; ++m) { const int row = row0 + ai * HALF + m * 16; const size_t off = (size_t)row * DM + col0; float s = 0.f;
; #pragma unroll
;                 for (int bj = 0; bj < 2; ++bj) { const f32x4 v0 = acc[ai][bj][m][0] + r[m][bj][0], v1 = acc[ai][bj][m][1] + r[m][bj][1];
;                     u32x4 w; w.x = cvt_pk_bf16(v0[0], v0[1]); w.y = cvt_pk_bf16(v0[2], v0[3]); w.z = cvt_pk_bf16(v1[0], v1[1]); w.w = cvt_pk_bf16(v1[2], v1[3]);
;                     *(u32x4*)(outb + off + bj * HALF) = w;
;                     s += ((v0[0] * v0[0] + v0[1] * v0[1]) + (v0[2] * v0[2] + v0[3] * v0[3])) + ((v1[0] * v1[0] + v1[1] * v1[1]) + (v1[2] * v1[2] + v1[3] * v1[3])); }
;                 s += __shfl_xor(s, 16); s += __shfl_xor(s, 32);
;                 if (fq == 0) ssq[(size_t)row * 32 + u.pn * 4 + wc] = s; }
;             asm volatile("" ::: "memory"); }
.LBB0_681:
	s_or_b64 exec, exec, s[20:21]
	s_waitcnt vmcnt(12)
	v_pk_add_f32 v[44:45], v[44:45], v[108:109]
	v_pk_add_f32 v[46:47], v[46:47], v[110:111]
	v_pk_add_f32 v[52:53], v[40:41], v[104:105]
	v_cvt_pk_bf16_f32 v40, v44, v45
	v_mul_f32_e32 v45, v45, v45
	v_fmac_f32_e32 v45, v44, v44
	v_mul_f32_e32 v44, v47, v47
	v_pk_add_f32 v[50:51], v[42:43], v[106:107]
	v_fmac_f32_e32 v44, v46, v46
	v_cvt_pk_bf16_f32 v41, v46, v47
	v_add_f32_e32 v44, v45, v44
	v_mul_f32_e32 v45, v53, v53
	v_mul_f32_e32 v46, v51, v51
	v_fmac_f32_e32 v45, v52, v52
	v_fmac_f32_e32 v46, v50, v50
	s_waitcnt vmcnt(10)
	v_pk_add_f32 v[38:39], v[38:39], v[102:103]
	v_pk_add_f32 v[36:37], v[36:37], v[100:101]
	v_add_f32_e32 v45, v45, v46
	v_pk_add_f32 v[46:47], v[32:33], v[96:97]
	v_mul_f32_e32 v32, v37, v37
	v_mul_f32_e32 v33, v39, v39
	v_cvt_pk_bf16_f32 v42, v52, v53
	v_cvt_pk_bf16_f32 v43, v50, v51
	v_add_f32_e32 v50, v44, v45
	v_pk_add_f32 v[44:45], v[34:35], v[98:99]
	v_fmac_f32_e32 v32, v36, v36
	v_fmac_f32_e32 v33, v38, v38
	v_add_f32_e32 v32, v32, v33
	v_mul_f32_e32 v33, v47, v47
	v_mul_f32_e32 v34, v45, v45
	v_fmac_f32_e32 v33, v46, v46
	v_fmac_f32_e32 v34, v44, v44
	v_add_f32_e32 v33, v33, v34
	v_add_f32_e32 v32, v32, v33
	v_add_f32_e32 v35, v50, v32
	ds_bpermute_b32 v50, v210, v35
	s_waitcnt lgkmcnt(1)
	v_lshlrev_b64 v[48:49], 12, v[116:117]
	v_lshl_add_u64 v[32:33], s[6:7], 0, v[48:49]
	v_lshl_add_u64 v[48:49], v[192:193], 1, v[32:33]
	global_store_dwordx4 v[48:49], v[40:43], off sc1
	s_waitcnt lgkmcnt(0)
	v_add_f32_e32 v32, v35, v50
	ds_bpermute_b32 v33, v120, v32
	v_cvt_pk_bf16_f32 v34, v36, v37
	v_cvt_pk_bf16_f32 v35, v38, v39
	v_cvt_pk_bf16_f32 v36, v46, v47
	v_cvt_pk_bf16_f32 v37, v44, v45
	global_store_dwordx4 v[48:49], v[34:37], off offset:256 sc1
	s_and_saveexec_b64 s[20:21], vcc
	s_cbranch_execz .LBB0_683
	v_lshlrev_b64 v[34:35], 7, v[116:117]
	v_lshl_add_u64 v[34:35], s[16:17], 0, v[34:35]
	v_lshl_add_u64 v[34:35], s[18:19], 2, v[34:35]
	s_lshl_b32 s2, s27, 2
	v_lshl_add_u64 v[34:35], v[34:35], 0, s[2:3]
	s_waitcnt lgkmcnt(0)
	v_add_f32_e32 v32, v32, v33
	global_store_dword v[34:35], v32, off
.LBB0_683:
	s_or_b64 exec, exec, s[20:21]
	s_waitcnt vmcnt(10)
	v_pk_add_f32 v[28:29], v[28:29], v[92:93]
	v_pk_add_f32 v[30:31], v[30:31], v[94:95]
	v_pk_add_f32 v[36:37], v[24:25], v[88:89]
	v_cvt_pk_bf16_f32 v24, v28, v29
	v_mul_f32_e32 v29, v29, v29
	v_fmac_f32_e32 v29, v28, v28
	v_mul_f32_e32 v28, v31, v31
	v_pk_add_f32 v[34:35], v[26:27], v[90:91]
	v_fmac_f32_e32 v28, v30, v30
	v_cvt_pk_bf16_f32 v25, v30, v31
	v_add_f32_e32 v28, v29, v28
	v_mul_f32_e32 v29, v37, v37
	v_mul_f32_e32 v30, v35, v35
	v_fmac_f32_e32 v29, v36, v36
	v_fmac_f32_e32 v30, v34, v34
	s_waitcnt vmcnt(8)
	v_pk_add_f32 v[22:23], v[22:23], v[86:87]
	v_pk_add_f32 v[20:21], v[20:21], v[84:85]
	v_add_f32_e32 v29, v29, v30
	v_pk_add_f32 v[30:31], v[16:17], v[80:81]
	v_mul_f32_e32 v16, v21, v21
	v_mul_f32_e32 v17, v23, v23
	v_cvt_pk_bf16_f32 v26, v36, v37
	v_cvt_pk_bf16_f32 v27, v34, v35
	v_add_f32_e32 v34, v28, v29
	v_pk_add_f32 v[28:29], v[18:19], v[82:83]
	v_fmac_f32_e32 v16, v20, v20
	v_fmac_f32_e32 v17, v22, v22
	v_add_f32_e32 v16, v16, v17
	v_mul_f32_e32 v17, v31, v31
	v_mul_f32_e32 v18, v29, v29
	v_fmac_f32_e32 v17, v30, v30
	v_fmac_f32_e32 v18, v28, v28
	v_add_f32_e32 v17, v17, v18
	v_add_f32_e32 v16, v16, v17
	v_add_f32_e32 v19, v34, v16
	ds_bpermute_b32 v34, v210, v19
	s_waitcnt lgkmcnt(1)
	v_lshlrev_b64 v[32:33], 12, v[114:115]
	v_lshl_add_u64 v[16:17], s[6:7], 0, v[32:33]
	v_lshl_add_u64 v[32:33], v[192:193], 1, v[16:17]
	global_store_dwordx4 v[32:33], v[24:27], off sc1
	s_waitcnt lgkmcnt(0)
	v_add_f32_e32 v16, v19, v34
	ds_bpermute_b32 v17, v120, v16
	v_cvt_pk_bf16_f32 v18, v20, v21
	v_cvt_pk_bf16_f32 v19, v22, v23
	v_cvt_pk_bf16_f32 v20, v30, v31
	v_cvt_pk_bf16_f32 v21, v28, v29
	global_store_dwordx4 v[32:33], v[18:21], off offset:256 sc1
	s_and_saveexec_b64 s[20:21], vcc
	s_cbranch_execz .LBB0_685
	v_lshlrev_b64 v[18:19], 7, v[114:115]
	v_lshl_add_u64 v[18:19], s[16:17], 0, v[18:19]
	v_lshl_add_u64 v[18:19], s[18:19], 2, v[18:19]
	s_lshl_b32 s2, s27, 2
	v_lshl_add_u64 v[18:19], v[18:19], 0, s[2:3]
	s_waitcnt lgkmcnt(0)
	v_add_f32_e32 v16, v16, v17
	global_store_dword v[18:19], v16, off
.LBB0_685:
	s_or_b64 exec, exec, s[20:21]
	s_waitcnt vmcnt(8)
	v_pk_add_f32 v[12:13], v[12:13], v[76:77]
	v_pk_add_f32 v[14:15], v[14:15], v[78:79]
	v_pk_add_f32 v[20:21], v[8:9], v[72:73]
	v_cvt_pk_bf16_f32 v8, v12, v13
	v_mul_f32_e32 v13, v13, v13
	v_fmac_f32_e32 v13, v12, v12
	v_mul_f32_e32 v12, v15, v15
	v_pk_add_f32 v[18:19], v[10:11], v[74:75]
	v_fmac_f32_e32 v12, v14, v14
	v_cvt_pk_bf16_f32 v9, v14, v15
	v_add_f32_e32 v12, v13, v12
	v_mul_f32_e32 v13, v21, v21
	v_mul_f32_e32 v14, v19, v19
	v_fmac_f32_e32 v13, v20, v20
	v_fmac_f32_e32 v14, v18, v18
	s_waitcnt vmcnt(6)
	v_pk_add_f32 v[6:7], v[6:7], v[70:71]
	v_pk_add_f32 v[4:5], v[4:5], v[68:69]
	v_add_f32_e32 v13, v13, v14
	v_pk_add_f32 v[14:15], v[0:1], v[64:65]
	v_mul_f32_e32 v0, v5, v5
	v_mul_f32_e32 v1, v7, v7
	v_cvt_pk_bf16_f32 v10, v20, v21
	v_cvt_pk_bf16_f32 v11, v18, v19
	v_add_f32_e32 v18, v12, v13
	v_pk_add_f32 v[12:13], v[2:3], v[66:67]
	v_fmac_f32_e32 v0, v4, v4
	v_fmac_f32_e32 v1, v6, v6
	v_add_f32_e32 v0, v0, v1
	v_mul_f32_e32 v1, v15, v15
	v_mul_f32_e32 v2, v13, v13
	v_fmac_f32_e32 v1, v14, v14
	v_fmac_f32_e32 v2, v12, v12
	v_add_f32_e32 v1, v1, v2
	v_add_f32_e32 v0, v0, v1
	v_add_f32_e32 v3, v18, v0
	ds_bpermute_b32 v18, v210, v3
	s_waitcnt lgkmcnt(1)
	v_lshlrev_b64 v[16:17], 12, v[112:113]
	v_lshl_add_u64 v[0:1], s[6:7], 0, v[16:17]
	v_lshl_add_u64 v[16:17], v[192:193], 1, v[0:1]
	global_store_dwordx4 v[16:17], v[8:11], off sc1
	s_waitcnt lgkmcnt(0)
	v_add_f32_e32 v0, v3, v18
	ds_bpermute_b32 v1, v120, v0
	v_cvt_pk_bf16_f32 v2, v4, v5
	v_cvt_pk_bf16_f32 v3, v6, v7
	v_cvt_pk_bf16_f32 v4, v14, v15
	v_cvt_pk_bf16_f32 v5, v12, v13
	global_store_dwordx4 v[16:17], v[2:5], off offset:256 sc1
	s_and_saveexec_b64 s[20:21], vcc
	s_cbranch_execz .LBB0_662
	v_lshlrev_b64 v[2:3], 7, v[112:113]
	v_lshl_add_u64 v[2:3], s[16:17], 0, v[2:3]
	v_lshl_add_u64 v[2:3], s[18:19], 2, v[2:3]
	s_lshl_b32 s2, s27, 2
	v_lshl_add_u64 v[2:3], v[2:3], 0, s[2:3]
	s_waitcnt lgkmcnt(0)
	v_add_f32_e32 v0, v0, v1
	global_store_dword v[2:3], v0, off
	s_branch .LBB0_662

; __device__ __forceinline__ unsigned cvt_pk_bf16(float lo, float hi) { unsigned r; asm volatile("v_cvt_pk_bf16_f32 %0, %1, %2" : "=v"(r) : "v"(lo), "v"(hi)); return r; }
;     __device__ __forceinline__ void operator()(f32x4 (&acc)[2][2][4][2], const Unit& u, int wr, int wc, int fr, int fq) const {
;         bf16_t* base; size_t s_ai, s_m, s_bj;
;         if (frag && u.pn >= fmin) { base = O + ((size_t)(u.pm * frag + u.pn) << 16) + (size_t)((((wr * 4 + wc) * 16) * 64 + fq * 16 + fr) << 3); s_ai = 4096; s_m = 1024; s_bj = 512; }
;         else if (frag) { base = O + ((size_t)(u.pm * frag + u.pn) << 16) + (size_t)(((wr * 64 + fr) << 8) + wc * 32 + 8 * fq); s_ai = (size_t)HALF * 256; s_m = 16 * 256; s_bj = HALF; }
;         else { base = O + (size_t)(u.pm * BM + wr * 64 + fr) * ldc + u.pn * BM + wc * 32 + 8 * fq; s_ai = (size_t)HALF * ldc; s_m = (size_t)16 * ldc; s_bj = HALF; }
; #pragma unroll
;         for (int ai = 0; ai < 2; ++ai)
; #pragma unroll
;             for (int m = 0; m < 4; ++m)
; #pragma unroll
;                 for (int bj = 0; bj < 2; ++bj) { const f32x4 v0 = acc[ai][bj][m][0], v1 = acc[ai][bj][m][1];
;                     u32x4 w; w.x = cvt_pk_bf16(v0[0], v0[1]); w.y = cvt_pk_bf16(v0[2], v0[3]); w.z = cvt_pk_bf16(v1[0], v1[1]); w.w = cvt_pk_bf16(v1[2], v1[3]);
;                     *(u32x4*)(base + ai * s_ai + m * s_m + bj * s_bj) = w; }
.LBB0_695:
	s_lshl_b32 s0, s0, 3
	s_add_i32 s34, s0, s62
	s_ashr_i32 s35, s34, 31
	s_lshl_b64 s[34:35], s[34:35], 17
	s_add_u32 s34, s23, s34
	s_addc_u32 s35, s24, s35
	v_ashrrev_i32_e32 v141, 31, v140
	v_lshl_add_u64 v[140:141], v[140:141], 1, s[34:35]
	s_lshl_b32 s0, s30, 1
	v_cvt_pk_bf16_f32 v124, v124, v125
	v_cvt_pk_bf16_f32 v125, v126, v127
	v_cvt_pk_bf16_f32 v126, v120, v121
	v_cvt_pk_bf16_f32 v127, v122, v123
	global_store_dwordx4 v[140:141], v[124:127], off sc1
	v_cvt_pk_bf16_f32 v116, v116, v117
	v_cvt_pk_bf16_f32 v117, v118, v119
	v_cvt_pk_bf16_f32 v118, v108, v109
	v_lshl_add_u64 v[108:109], v[140:141], 0, s[0:1]
	s_lshl_b32 s18, s18, 1
	s_mov_b32 s19, s1
	v_cvt_pk_bf16_f32 v119, v110, v111
	global_store_dwordx4 v[108:109], v[116:119], off sc1
	v_cvt_pk_bf16_f32 v108, v112, v113
	v_cvt_pk_bf16_f32 v109, v114, v115
	v_cvt_pk_bf16_f32 v110, v104, v105
	v_cvt_pk_bf16_f32 v111, v106, v107
	s_lshl_b32 s20, s20, 1
	s_nop 0
	v_lshl_add_u64 v[116:117], v[140:141], 0, s[18:19]
	global_store_dwordx4 v[116:117], v[108:111], off sc1
	v_cvt_pk_bf16_f32 v96, v96, v97
	v_cvt_pk_bf16_f32 v97, v98, v99
	v_cvt_pk_bf16_f32 v98, v88, v89
	v_lshl_add_u64 v[88:89], v[116:117], 0, s[0:1]
	v_cvt_pk_bf16_f32 v99, v90, v91
	global_store_dwordx4 v[88:89], v[96:99], off sc1
	v_cvt_pk_bf16_f32 v88, v100, v101
	v_cvt_pk_bf16_f32 v89, v102, v103
	v_cvt_pk_bf16_f32 v90, v92, v93
	v_cvt_pk_bf16_f32 v91, v94, v95
	s_mov_b32 s21, s1
	s_nop 0
	v_lshl_add_u64 v[96:97], v[116:117], 0, s[18:19]
	global_store_dwordx4 v[96:97], v[88:91], off sc1
	v_cvt_pk_bf16_f32 v80, v80, v81
	v_cvt_pk_bf16_f32 v81, v82, v83
	v_cvt_pk_bf16_f32 v82, v72, v73
	v_lshl_add_u64 v[72:73], v[96:97], 0, s[0:1]
	v_cvt_pk_bf16_f32 v83, v74, v75
	global_store_dwordx4 v[72:73], v[80:83], off sc1
	v_cvt_pk_bf16_f32 v72, v84, v85
	v_cvt_pk_bf16_f32 v73, v86, v87
	v_cvt_pk_bf16_f32 v74, v76, v77
	v_cvt_pk_bf16_f32 v75, v78, v79
	s_and_b64 vcc, exec, s[40:41]
	s_nop 0
	v_lshl_add_u64 v[80:81], v[96:97], 0, s[18:19]
	global_store_dwordx4 v[80:81], v[72:75], off sc1
	v_cvt_pk_bf16_f32 v68, v68, v69
	v_cvt_pk_bf16_f32 v69, v70, v71
	v_cvt_pk_bf16_f32 v70, v64, v65
	v_lshl_add_u64 v[64:65], v[80:81], 0, s[0:1]
	v_cvt_pk_bf16_f32 v71, v66, v67
	global_store_dwordx4 v[64:65], v[68:71], off sc1
	v_lshl_add_u64 v[64:65], v[140:141], 0, s[20:21]
	v_cvt_pk_bf16_f32 v60, v60, v61
	v_cvt_pk_bf16_f32 v61, v62, v63
	v_cvt_pk_bf16_f32 v62, v56, v57
	v_cvt_pk_bf16_f32 v63, v58, v59
	global_store_dwordx4 v[64:65], v[60:63], off sc1
	v_cvt_pk_bf16_f32 v48, v48, v49
	v_cvt_pk_bf16_f32 v49, v50, v51
	v_cvt_pk_bf16_f32 v50, v40, v41
	v_lshl_add_u64 v[40:41], v[64:65], 0, s[0:1]
	v_cvt_pk_bf16_f32 v51, v42, v43
	global_store_dwordx4 v[40:41], v[48:51], off sc1
	v_cvt_pk_bf16_f32 v40, v52, v53
	v_cvt_pk_bf16_f32 v41, v54, v55
	v_cvt_pk_bf16_f32 v42, v44, v45
	v_cvt_pk_bf16_f32 v43, v46, v47
	s_mov_b32 s62, s8
	s_nop 0
	v_lshl_add_u64 v[48:49], v[64:65], 0, s[18:19]
	global_store_dwordx4 v[48:49], v[40:43], off sc1
	v_cvt_pk_bf16_f32 v32, v32, v33
	v_cvt_pk_bf16_f32 v33, v34, v35
	v_cvt_pk_bf16_f32 v34, v24, v25
	v_lshl_add_u64 v[24:25], v[48:49], 0, s[0:1]
	v_cvt_pk_bf16_f32 v35, v26, v27
	global_store_dwordx4 v[24:25], v[32:35], off sc1
	v_cvt_pk_bf16_f32 v24, v36, v37
	v_cvt_pk_bf16_f32 v25, v38, v39
	v_cvt_pk_bf16_f32 v26, v28, v29
	v_cvt_pk_bf16_f32 v27, v30, v31
	s_mov_b64 s[20:21], s[12:13]
	s_nop 0
	v_lshl_add_u64 v[32:33], v[48:49], 0, s[18:19]
	global_store_dwordx4 v[32:33], v[24:27], off sc1
	v_cvt_pk_bf16_f32 v16, v16, v17
	v_cvt_pk_bf16_f32 v17, v18, v19
	v_cvt_pk_bf16_f32 v18, v8, v9
	v_lshl_add_u64 v[8:9], v[32:33], 0, s[0:1]
	v_cvt_pk_bf16_f32 v19, v10, v11
	global_store_dwordx4 v[8:9], v[16:19], off sc1
	v_cvt_pk_bf16_f32 v8, v20, v21
	v_cvt_pk_bf16_f32 v9, v22, v23
	v_cvt_pk_bf16_f32 v10, v12, v13
	v_cvt_pk_bf16_f32 v11, v14, v15
	s_nop 1
	v_lshl_add_u64 v[16:17], v[32:33], 0, s[18:19]
	global_store_dwordx4 v[16:17], v[8:11], off sc1
	v_cvt_pk_bf16_f32 v4, v4, v5
	v_cvt_pk_bf16_f32 v5, v6, v7
	v_cvt_pk_bf16_f32 v6, v0, v1
	v_lshl_add_u64 v[0:1], v[16:17], 0, s[0:1]
	s_mov_b32 s0, s10
	s_mov_b64 s[18:19], s[14:15]
	v_cvt_pk_bf16_f32 v7, v2, v3
	global_store_dwordx4 v[0:1], v[4:7], off sc1
	s_cbranch_vccnz .LBB0_708

; #define PG8_STAGE(bufoff, gbase, voff) do { _Pragma("unroll") for (int _i = 0; _i < 2; ++_i) \
;         __builtin_amdgcn_global_load_lds((const unsigned*)((const char*)(gbase) + (voff)[_i]), (LAS unsigned*)(lds + (bufoff) + ldsw + _i * 8192), 16, 0, 0); } while (0)
; #define PG8_LDA(dst, b, h) do { _Pragma("unroll") for (int m = 0; m < 4; ++m) _Pragma("unroll") for (int k = 0; k < 2; ++k) dst[m][k] = *(const LAS bf16x8*)(lds + PG8_SA(b, h) + aoff + m * 2048 + k * 1024); } while (0)
; #define PG8_LDB(dst, b, h) do { _Pragma("unroll") for (int n = 0; n < 2; ++n) _Pragma("unroll") for (int k = 0; k < 2; ++k) dst[n][k] = *(const LAS bf16x8*)(lds + PG8_SB(b, h) + boff + n * 2048 + k * 1024); } while (0)
; #define PG8_MMA(ai, bj, At, Bt) do { __builtin_amdgcn_s_setprio(1); _Pragma("unroll") for (int m = 0; m < 4; ++m) _Pragma("unroll") for (int n = 0; n < 2; ++n) _Pragma("unroll") for (int k = 0; k < 2; ++k) \
;         acc[ai][bj][m][n] = __builtin_amdgcn_mfma_f32_16x16x32_bf16(Bt[n][k], At[m][k], acc[ai][bj][m][n], 0, 0, 0); __builtin_amdgcn_s_setprio(0); } while (0)
; #define PG8_WAIT_V(n) asm volatile("s_waitcnt vmcnt(" #n ")" ::: "memory")
; #define PG8_WAIT_L(n) asm volatile("s_waitcnt lgkmcnt(" #n ")" ::: "memory")
; #define PG8_BAR __builtin_amdgcn_s_barrier()
; #define PG8_SCHED __builtin_amdgcn_sched_barrier(0)
; template <class Epi, bool KS0 = false>
; __device__ __forceinline__ void gemm_phase(const int WID, LAS unsigned char* lds, const Gemm g, const StaticOrder& S, const Epi& E) {
;     ...
;             PG8_LDB(B0, 0, 0); PG8_SCHED; PG8_LDA(At, 0, 0); PG8_STAGE(PG8_SA(1, 1), a1 + hstep, voffA);
;             PG8_WAIT_L(8); PG8_BAR; PG8_WAIT_L(0); PG8_MMA(0, 0, At, B0); PG8_BAR; PG8_SCHED;
;             PG8_LDB(B1, 0, 1); PG8_STAGE(PG8_SB(0, 0), b2, voffB);
;             PG8_BAR; PG8_WAIT_L(0); PG8_MMA(0, 1, At, B1); PG8_BAR;
;             PG8_LDA(At, 0, 1); PG8_STAGE(PG8_SA(0, 0), a2, voffA);
;             PG8_BAR; PG8_WAIT_L(0); PG8_MMA(1, 0, At, B0); PG8_BAR; PG8_SCHED;
;             PG8_STAGE(PG8_SB(0, 1), b2 + hstep, voffB);
;             PG8_WAIT_V(6); PG8_BAR; PG8_MMA(1, 1, At, B1); PG8_BAR;
.LBB0_914:
	ds_read_b128 v[128:131], v187
	ds_read_b128 v[132:135], v187 offset:1024
	ds_read_b128 v[136:139], v187 offset:2048
	ds_read_b128 v[140:143], v187 offset:3072
	s_add_u32 s18, s2, 0x100
	s_addc_u32 s19, s3, 0
	s_cmpk_eq_i32 s42, 0x54
	s_cselect_b32 s29, s13, s19
	s_cselect_b32 s28, s12, s18
	s_cselect_b32 s21, s15, s41
	s_cselect_b32 s20, s14, s40
	v_lshl_add_u64 v[184:185], s[2:3], 0, v[160:161]
	s_add_i32 m0, s25, 0xc000
	ds_read_b128 v[144:147], v188
	ds_read_b128 v[148:151], v188 offset:1024
	ds_read_b128 v[168:171], v188 offset:2048
	ds_read_b128 v[172:175], v188 offset:3072
	ds_read_b128 v[176:179], v188 offset:4096
	ds_read_b128 v[180:183], v188 offset:5120
	ds_read_b128 v[190:193], v188 offset:6144
	ds_read_b128 v[194:197], v188 offset:7168
	global_load_lds_dwordx4 v[184:185], off
	v_lshl_add_u64 v[184:185], s[2:3], 0, v[162:163]
	s_add_i32 m0, s25, 0xe000
	s_nop 0
	global_load_lds_dwordx4 v[184:185], off
	s_waitcnt lgkmcnt(8)
	s_barrier
	s_waitcnt lgkmcnt(0)
	s_setprio 1
	s_waitcnt lgkmcnt(0)
	v_mfma_f32_16x16x32_bf16 v[124:127], v[128:131], v[144:147], v[124:127]
	v_mfma_f32_16x16x32_bf16 v[120:123], v[136:139], v[144:147], v[120:123]
	v_mfma_f32_16x16x32_bf16 v[108:111], v[128:131], v[168:171], v[108:111]
	v_mfma_f32_16x16x32_bf16 v[104:107], v[136:139], v[168:171], v[104:107]
	v_mfma_f32_16x16x32_bf16 v[92:95], v[128:131], v[176:179], v[92:95]
	v_mfma_f32_16x16x32_bf16 v[88:91], v[136:139], v[176:179], v[88:91]
	v_mfma_f32_16x16x32_bf16 v[76:79], v[128:131], v[190:193], v[76:79]
	v_mfma_f32_16x16x32_bf16 v[72:75], v[136:139], v[190:193], v[72:75]
	v_mfma_f32_16x16x32_bf16 v[124:127], v[132:135], v[148:151], v[124:127]
	v_mfma_f32_16x16x32_bf16 v[120:123], v[140:143], v[148:151], v[120:123]
	v_mfma_f32_16x16x32_bf16 v[108:111], v[132:135], v[172:175], v[108:111]
	v_mfma_f32_16x16x32_bf16 v[104:107], v[140:143], v[172:175], v[104:107]
	v_mfma_f32_16x16x32_bf16 v[92:95], v[132:135], v[180:183], v[92:95]
	v_mfma_f32_16x16x32_bf16 v[88:91], v[140:143], v[180:183], v[88:91]
	v_mfma_f32_16x16x32_bf16 v[76:79], v[132:135], v[194:197], v[76:79]
	v_mfma_f32_16x16x32_bf16 v[72:75], v[140:143], v[194:197], v[72:75]
	s_setprio 0
	s_barrier
	s_add_i32 s2, s47, s26
	v_lshl_add_u64 v[184:185], s[20:21], 0, v[154:155]
	s_mov_b32 m0, s2
	ds_read_b128 v[198:201], v189
	ds_read_b128 v[202:205], v189 offset:1024
	ds_read_b128 v[210:213], v189 offset:2048
	ds_read_b128 v[214:217], v189 offset:3072
	global_load_lds_dwordx4 v[184:185], off
	v_lshl_add_u64 v[206:207], s[20:21], 0, v[158:159]
	s_add_i32 m0, s2, 0x2000
	s_nop 0
	global_load_lds_dwordx4 v[206:207], off
	s_barrier
	s_waitcnt lgkmcnt(0)
	s_setprio 1
	s_waitcnt lgkmcnt(0)
	v_mfma_f32_16x16x32_bf16 v[116:119], v[198:201], v[144:147], v[116:119]
	v_mfma_f32_16x16x32_bf16 v[112:115], v[210:213], v[144:147], v[112:115]
	v_mfma_f32_16x16x32_bf16 v[100:103], v[198:201], v[168:171], v[100:103]
	v_mfma_f32_16x16x32_bf16 v[96:99], v[210:213], v[168:171], v[96:99]
	v_mfma_f32_16x16x32_bf16 v[84:87], v[198:201], v[176:179], v[84:87]
	v_mfma_f32_16x16x32_bf16 v[80:83], v[210:213], v[176:179], v[80:83]
	v_mfma_f32_16x16x32_bf16 v[68:71], v[198:201], v[190:193], v[68:71]
	v_mfma_f32_16x16x32_bf16 v[64:67], v[210:213], v[190:193], v[64:67]
	v_mfma_f32_16x16x32_bf16 v[116:119], v[202:205], v[148:151], v[116:119]
	v_mfma_f32_16x16x32_bf16 v[112:115], v[214:217], v[148:151], v[112:115]
	v_mfma_f32_16x16x32_bf16 v[100:103], v[202:205], v[172:175], v[100:103]
	v_mfma_f32_16x16x32_bf16 v[96:99], v[214:217], v[172:175], v[96:99]
	v_mfma_f32_16x16x32_bf16 v[84:87], v[202:205], v[180:183], v[84:87]
	v_mfma_f32_16x16x32_bf16 v[80:83], v[214:217], v[180:183], v[80:83]
	v_mfma_f32_16x16x32_bf16 v[68:71], v[202:205], v[194:197], v[68:71]
	v_mfma_f32_16x16x32_bf16 v[64:67], v[214:217], v[194:197], v[64:67]
	s_setprio 0
	s_mov_b32 m0, s25
	v_lshl_add_u64 v[218:219], s[28:29], 0, v[152:153]
	s_barrier
	ds_read_b128 v[144:147], v188 offset:16384
	ds_read_b128 v[148:151], v188 offset:17408
	ds_read_b128 v[168:171], v188 offset:18432
	ds_read_b128 v[172:175], v188 offset:19456
	ds_read_b128 v[176:179], v188 offset:20480
	ds_read_b128 v[180:183], v188 offset:21504
	ds_read_b128 v[190:193], v188 offset:22528
	ds_read_b128 v[194:197], v188 offset:23552
	global_load_lds_dwordx4 v[218:219], off
	v_lshl_add_u64 v[220:221], s[28:29], 0, v[156:157]
	s_mov_b32 m0, s30
	s_nop 0
	global_load_lds_dwordx4 v[220:221], off
	s_barrier
	s_waitcnt lgkmcnt(0)
	s_setprio 1
	s_waitcnt lgkmcnt(0)
	v_mfma_f32_16x16x32_bf16 v[60:63], v[128:131], v[144:147], v[60:63]
	v_mfma_f32_16x16x32_bf16 v[56:59], v[136:139], v[144:147], v[56:59]
	v_mfma_f32_16x16x32_bf16 v[44:47], v[128:131], v[168:171], v[44:47]
	v_mfma_f32_16x16x32_bf16 v[40:43], v[136:139], v[168:171], v[40:43]
	v_mfma_f32_16x16x32_bf16 v[28:31], v[128:131], v[176:179], v[28:31]
	v_mfma_f32_16x16x32_bf16 v[24:27], v[136:139], v[176:179], v[24:27]
	v_mfma_f32_16x16x32_bf16 v[12:15], v[128:131], v[190:193], v[12:15]
	v_mfma_f32_16x16x32_bf16 v[8:11], v[136:139], v[190:193], v[8:11]
	v_mfma_f32_16x16x32_bf16 v[60:63], v[132:135], v[148:151], v[60:63]
	v_mfma_f32_16x16x32_bf16 v[56:59], v[140:143], v[148:151], v[56:59]
	v_mfma_f32_16x16x32_bf16 v[44:47], v[132:135], v[172:175], v[44:47]
	v_mfma_f32_16x16x32_bf16 v[40:43], v[140:143], v[172:175], v[40:43]
	v_mfma_f32_16x16x32_bf16 v[28:31], v[132:135], v[180:183], v[28:31]
	v_mfma_f32_16x16x32_bf16 v[24:27], v[140:143], v[180:183], v[24:27]
	v_mfma_f32_16x16x32_bf16 v[12:15], v[132:135], v[194:197], v[12:15]
	v_mfma_f32_16x16x32_bf16 v[8:11], v[140:143], v[194:197], v[8:11]
	s_setprio 0
	s_barrier
; #define PG8_STAGE(bufoff, gbase, voff) do { _Pragma("unroll") for (int _i = 0; _i < 2; ++_i) \
;         __builtin_amdgcn_global_load_lds((const unsigned*)((const char*)(gbase) + (voff)[_i]), (LAS unsigned*)(lds + (bufoff) + ldsw + _i * 8192), 16, 0, 0); } while (0)
; #define PG8_LDA(dst, b, h) do { _Pragma("unroll") for (int m = 0; m < 4; ++m) _Pragma("unroll") for (int k = 0; k < 2; ++k) dst[m][k] = *(const LAS bf16x8*)(lds + PG8_SA(b, h) + aoff + m * 2048 + k * 1024); } while (0)
; #define PG8_LDB(dst, b, h) do { _Pragma("unroll") for (int n = 0; n < 2; ++n) _Pragma("unroll") for (int k = 0; k < 2; ++k) dst[n][k] = *(const LAS bf16x8*)(lds + PG8_SB(b, h) + boff + n * 2048 + k * 1024); } while (0)
; #define PG8_MMA(ai, bj, At, Bt) do { __builtin_amdgcn_s_setprio(1); _Pragma("unroll") for (int m = 0; m < 4; ++m) _Pragma("unroll") for (int n = 0; n < 2; ++n) _Pragma("unroll") for (int k = 0; k < 2; ++k) \
;         acc[ai][bj][m][n] = __builtin_amdgcn_mfma_f32_16x16x32_bf16(Bt[n][k], At[m][k], acc[ai][bj][m][n], 0, 0, 0); __builtin_amdgcn_s_setprio(0); } while (0)
; #define PG8_WAIT_V(n) asm volatile("s_waitcnt vmcnt(" #n ")" ::: "memory")
; #define PG8_WAIT_L(n) asm volatile("s_waitcnt lgkmcnt(" #n ")" ::: "memory")
; #define PG8_BAR __builtin_amdgcn_s_barrier()
; #define PG8_SCHED __builtin_amdgcn_sched_barrier(0)
; template <class Epi, bool KS0 = false>
; __device__ __forceinline__ void gemm_phase(const int WID, LAS unsigned char* lds, const Gemm g, const StaticOrder& S, const Epi& E) {
;     ...
;             PG8_STAGE(PG8_SB(0, 1), b2 + hstep, voffB);
;             PG8_WAIT_V(6); PG8_BAR; PG8_MMA(1, 1, At, B1); PG8_BAR;
;             PG8_LDB(B0, 1, 0); PG8_SCHED; PG8_LDA(At, 1, 0); PG8_STAGE(PG8_SA(0, 1), a2 + hstep, voffA);
;             PG8_WAIT_L(8); PG8_BAR; PG8_WAIT_L(0); PG8_MMA(0, 0, At, B0); PG8_BAR; PG8_SCHED;
;             PG8_LDB(B1, 1, 1); PG8_STAGE(PG8_SB(1, 0), b3, voffB);
;             PG8_BAR; PG8_WAIT_L(0); PG8_MMA(0, 1, At, B1); PG8_BAR;
;             PG8_LDA(At, 1, 1); PG8_STAGE(PG8_SA(1, 0), a3, voffA);
;             PG8_BAR; PG8_WAIT_L(0); PG8_MMA(1, 0, At, B0); PG8_BAR; PG8_SCHED;
	s_add_u32 s2, s20, 0x160000
	s_addc_u32 s3, s21, 0
	s_add_i32 s43, s48, s26
	v_lshl_add_u64 v[128:129], s[2:3], 0, v[154:155]
	s_mov_b32 m0, s43
	s_nop 0
	global_load_lds_dwordx4 v[128:129], off
	v_lshl_add_u64 v[128:129], s[2:3], 0, v[158:159]
	s_add_i32 m0, s43, 0x2000
	s_nop 0
	global_load_lds_dwordx4 v[128:129], off
	s_waitcnt vmcnt(6)
	s_barrier
	s_setprio 1
	v_mfma_f32_16x16x32_bf16 v[52:55], v[198:201], v[144:147], v[52:55]
	v_mfma_f32_16x16x32_bf16 v[48:51], v[210:213], v[144:147], v[48:51]
	v_mfma_f32_16x16x32_bf16 v[36:39], v[198:201], v[168:171], v[36:39]
	v_mfma_f32_16x16x32_bf16 v[32:35], v[210:213], v[168:171], v[32:35]
	v_mfma_f32_16x16x32_bf16 v[20:23], v[198:201], v[176:179], v[20:23]
	v_mfma_f32_16x16x32_bf16 v[16:19], v[210:213], v[176:179], v[16:19]
	v_mfma_f32_16x16x32_bf16 v[4:7], v[198:201], v[190:193], v[4:7]
	v_mfma_f32_16x16x32_bf16 v[0:3], v[210:213], v[190:193], v[0:3]
	v_mfma_f32_16x16x32_bf16 v[52:55], v[202:205], v[148:151], v[52:55]
	v_mfma_f32_16x16x32_bf16 v[48:51], v[214:217], v[148:151], v[48:51]
	v_mfma_f32_16x16x32_bf16 v[36:39], v[202:205], v[172:175], v[36:39]
	v_mfma_f32_16x16x32_bf16 v[32:35], v[214:217], v[172:175], v[32:35]
	v_mfma_f32_16x16x32_bf16 v[20:23], v[202:205], v[180:183], v[20:23]
	v_mfma_f32_16x16x32_bf16 v[16:19], v[214:217], v[180:183], v[16:19]
	v_mfma_f32_16x16x32_bf16 v[4:7], v[202:205], v[194:197], v[4:7]
	v_mfma_f32_16x16x32_bf16 v[0:3], v[214:217], v[194:197], v[0:3]
	s_setprio 0
	s_add_i32 s43, 0, 0x18000
	v_add_u32_e32 v140, s43, v186
	s_barrier
	ds_read_b128 v[128:131], v140
	ds_read_b128 v[132:135], v140 offset:1024
	ds_read_b128 v[136:139], v140 offset:2048
	ds_read_b128 v[140:143], v140 offset:3072
	s_add_u32 s2, s28, 0x160000
	s_addc_u32 s3, s29, 0
	s_mov_b32 m0, s31
	v_lshl_add_u64 v[198:199], s[2:3], 0, v[152:153]
	ds_read_b128 v[144:147], v188 offset:32768
	ds_read_b128 v[148:151], v188 offset:33792
	ds_read_b128 v[168:171], v188 offset:34816
	ds_read_b128 v[172:175], v188 offset:35840
	ds_read_b128 v[176:179], v188 offset:36864
	ds_read_b128 v[180:183], v188 offset:37888
	ds_read_b128 v[190:193], v188 offset:38912
	ds_read_b128 v[194:197], v188 offset:39936
	global_load_lds_dwordx4 v[198:199], off
	v_lshl_add_u64 v[198:199], s[2:3], 0, v[156:157]
	s_mov_b32 m0, s44
	s_nop 0
	global_load_lds_dwordx4 v[198:199], off
	s_waitcnt lgkmcnt(8)
	s_barrier
	s_waitcnt lgkmcnt(0)
	s_setprio 1
	s_waitcnt lgkmcnt(0)
	v_mfma_f32_16x16x32_bf16 v[124:127], v[128:131], v[144:147], v[124:127]
	v_mfma_f32_16x16x32_bf16 v[120:123], v[136:139], v[144:147], v[120:123]
	v_mfma_f32_16x16x32_bf16 v[108:111], v[128:131], v[168:171], v[108:111]
	v_mfma_f32_16x16x32_bf16 v[104:107], v[136:139], v[168:171], v[104:107]
	v_mfma_f32_16x16x32_bf16 v[92:95], v[128:131], v[176:179], v[92:95]
	v_mfma_f32_16x16x32_bf16 v[88:91], v[136:139], v[176:179], v[88:91]
	v_mfma_f32_16x16x32_bf16 v[76:79], v[128:131], v[190:193], v[76:79]
	v_mfma_f32_16x16x32_bf16 v[72:75], v[136:139], v[190:193], v[72:75]
	v_mfma_f32_16x16x32_bf16 v[124:127], v[132:135], v[148:151], v[124:127]
	v_mfma_f32_16x16x32_bf16 v[120:123], v[140:143], v[148:151], v[120:123]
	v_mfma_f32_16x16x32_bf16 v[108:111], v[132:135], v[172:175], v[108:111]
	v_mfma_f32_16x16x32_bf16 v[104:107], v[140:143], v[172:175], v[104:107]
	v_mfma_f32_16x16x32_bf16 v[92:95], v[132:135], v[180:183], v[92:95]
	v_mfma_f32_16x16x32_bf16 v[88:91], v[140:143], v[180:183], v[88:91]
	v_mfma_f32_16x16x32_bf16 v[76:79], v[132:135], v[194:197], v[76:79]
	v_mfma_f32_16x16x32_bf16 v[72:75], v[140:143], v[194:197], v[72:75]
	s_setprio 0
	s_barrier
	s_add_i32 s28, 0, 0x1c000
	s_add_i32 s2, s43, s26
	v_add_u32_e32 v208, s28, v186
	v_lshl_add_u64 v[184:185], v[184:185], 0, s[10:11]
	s_mov_b32 m0, s2
	ds_read_b128 v[198:201], v208
	ds_read_b128 v[202:205], v208 offset:1024
	ds_read_b128 v[210:213], v208 offset:2048
	ds_read_b128 v[214:217], v208 offset:3072
	global_load_lds_dwordx4 v[184:185], off
	v_lshl_add_u64 v[184:185], v[206:207], 0, s[10:11]
	s_add_i32 m0, s2, 0x2000
	s_nop 0
	global_load_lds_dwordx4 v[184:185], off
	s_barrier
	s_waitcnt lgkmcnt(0)
	s_setprio 1
	s_waitcnt lgkmcnt(0)
	v_mfma_f32_16x16x32_bf16 v[116:119], v[198:201], v[144:147], v[116:119]
	v_mfma_f32_16x16x32_bf16 v[112:115], v[210:213], v[144:147], v[112:115]
	v_mfma_f32_16x16x32_bf16 v[100:103], v[198:201], v[168:171], v[100:103]
	v_mfma_f32_16x16x32_bf16 v[96:99], v[210:213], v[168:171], v[96:99]
	v_mfma_f32_16x16x32_bf16 v[84:87], v[198:201], v[176:179], v[84:87]
	v_mfma_f32_16x16x32_bf16 v[80:83], v[210:213], v[176:179], v[80:83]
	v_mfma_f32_16x16x32_bf16 v[68:71], v[198:201], v[190:193], v[68:71]
	v_mfma_f32_16x16x32_bf16 v[64:67], v[210:213], v[190:193], v[64:67]
	v_mfma_f32_16x16x32_bf16 v[116:119], v[202:205], v[148:151], v[116:119]
	v_mfma_f32_16x16x32_bf16 v[112:115], v[214:217], v[148:151], v[112:115]
	v_mfma_f32_16x16x32_bf16 v[100:103], v[202:205], v[172:175], v[100:103]
	v_mfma_f32_16x16x32_bf16 v[96:99], v[214:217], v[172:175], v[96:99]
	v_mfma_f32_16x16x32_bf16 v[84:87], v[202:205], v[180:183], v[84:87]
	v_mfma_f32_16x16x32_bf16 v[80:83], v[214:217], v[180:183], v[80:83]
	v_mfma_f32_16x16x32_bf16 v[68:71], v[202:205], v[194:197], v[68:71]
	v_mfma_f32_16x16x32_bf16 v[64:67], v[214:217], v[194:197], v[64:67]
	s_setprio 0
	s_mov_b32 m0, s45
	v_lshl_add_u64 v[184:185], v[218:219], 0, s[10:11]
	s_barrier
	ds_read_b128 v[144:147], v188 offset:49152
	ds_read_b128 v[148:151], v188 offset:50176
	ds_read_b128 v[168:171], v188 offset:51200
	ds_read_b128 v[172:175], v188 offset:52224
	ds_read_b128 v[176:179], v188 offset:53248
	ds_read_b128 v[180:183], v188 offset:54272
	ds_read_b128 v[190:193], v188 offset:55296
	ds_read_b128 v[194:197], v188 offset:56320
	global_load_lds_dwordx4 v[184:185], off
	v_lshl_add_u64 v[184:185], v[220:221], 0, s[10:11]
	s_mov_b32 m0, s46
	s_nop 0
	global_load_lds_dwordx4 v[184:185], off
	s_barrier
; __device__ __forceinline__ float bflo(unsigned w) { return __uint_as_float(w << 16); }
; __device__ __forceinline__ float bfhi(unsigned w) { return __uint_as_float(w & 0xffff0000u); }
; #define PG8_STAGE(bufoff, gbase, voff) do { _Pragma("unroll") for (int _i = 0; _i < 2; ++_i) \
;         __builtin_amdgcn_global_load_lds((const unsigned*)((const char*)(gbase) + (voff)[_i]), (LAS unsigned*)(lds + (bufoff) + ldsw + _i * 8192), 16, 0, 0); } while (0)
; #define PG8_MMA(ai, bj, At, Bt) do { __builtin_amdgcn_s_setprio(1); _Pragma("unroll") for (int m = 0; m < 4; ++m) _Pragma("unroll") for (int n = 0; n < 2; ++n) _Pragma("unroll") for (int k = 0; k < 2; ++k) \
;         acc[ai][bj][m][n] = __builtin_amdgcn_mfma_f32_16x16x32_bf16(Bt[n][k], At[m][k], acc[ai][bj][m][n], 0, 0, 0); __builtin_amdgcn_s_setprio(0); } while (0)
; #define PG8_WAIT_V(n) asm volatile("s_waitcnt vmcnt(" #n ")" ::: "memory")
; #define PG8_WAIT_L(n) asm volatile("s_waitcnt lgkmcnt(" #n ")" ::: "memory")
; #define PG8_BAR __builtin_amdgcn_s_barrier()
; #define PG8_SCHED __builtin_amdgcn_sched_barrier(0)
; template <class Epi, bool KS0 = false>
; __device__ __forceinline__ void gemm_phase(const int WID, LAS unsigned char* lds, const Gemm g, const StaticOrder& S, const Epi& E) {
;     ...
;             PG8_BAR; PG8_WAIT_L(0); PG8_MMA(1, 0, At, B0); PG8_BAR; PG8_SCHED;
;             PG8_STAGE(PG8_SB(1, 1), b3 + hstep, voffB);
;             PG8_WAIT_V(6); PG8_BAR; PG8_MMA(1, 1, At, B1); PG8_BAR;
;     __device__ __forceinline__ void operator()(f32x4 (&acc)[2][2][4][2], const Unit& u, int wr, int wc, int fr, int fq) const {
;         const int row0 = u.pm * BM + wr * 64 + fr, col0 = u.pn * BM + wc * 32 + 8 * fq;
; #pragma unroll
;         for (int ai = 0; ai < 2; ++ai) {
;             f32x4 r[4][2][2];
; #pragma unroll
;             for (int m = 0; m < 4; ++m)
; #pragma unroll
;                 for (int bj = 0; bj < 2; ++bj) { const size_t o = (size_t)(row0 + ai * HALF + m * 16) * DM + col0 + bj * HALF;
;                     if (RB) { const u32x4 w = *(const u32x4*)((const bf16_t*)res + o); r[m][bj][0] = (f32x4){bflo(w.x), bfhi(w.x), bflo(w.y), bfhi(w.y)}; r[m][bj][1] = (f32x4){bflo(w.z), bfhi(w.z), bflo(w.w), bfhi(w.w)}; }
	s_waitcnt lgkmcnt(0)
	s_setprio 1
	s_waitcnt lgkmcnt(0)
	v_mfma_f32_16x16x32_bf16 v[60:63], v[128:131], v[144:147], v[60:63]
	v_mfma_f32_16x16x32_bf16 v[56:59], v[136:139], v[144:147], v[56:59]
	v_mfma_f32_16x16x32_bf16 v[44:47], v[128:131], v[168:171], v[44:47]
	v_mfma_f32_16x16x32_bf16 v[40:43], v[136:139], v[168:171], v[40:43]
	v_mfma_f32_16x16x32_bf16 v[28:31], v[128:131], v[176:179], v[28:31]
	v_mfma_f32_16x16x32_bf16 v[24:27], v[136:139], v[176:179], v[24:27]
	v_mfma_f32_16x16x32_bf16 v[12:15], v[128:131], v[190:193], v[12:15]
	v_mfma_f32_16x16x32_bf16 v[8:11], v[136:139], v[190:193], v[8:11]
	v_mfma_f32_16x16x32_bf16 v[60:63], v[132:135], v[148:151], v[60:63]
	v_mfma_f32_16x16x32_bf16 v[56:59], v[140:143], v[148:151], v[56:59]
	v_mfma_f32_16x16x32_bf16 v[44:47], v[132:135], v[172:175], v[44:47]
	v_mfma_f32_16x16x32_bf16 v[40:43], v[140:143], v[172:175], v[40:43]
	v_mfma_f32_16x16x32_bf16 v[28:31], v[132:135], v[180:183], v[28:31]
	v_mfma_f32_16x16x32_bf16 v[24:27], v[140:143], v[180:183], v[24:27]
	v_mfma_f32_16x16x32_bf16 v[12:15], v[132:135], v[194:197], v[12:15]
	v_mfma_f32_16x16x32_bf16 v[8:11], v[140:143], v[194:197], v[8:11]
	s_setprio 0
	s_barrier
	s_add_u32 s2, s20, 0x160080
	s_addc_u32 s3, s21, 0
	s_add_i32 s20, s28, s26
	v_lshl_add_u64 v[128:129], s[2:3], 0, v[154:155]
	s_mov_b32 m0, s20
	s_nop 0
	global_load_lds_dwordx4 v[128:129], off
	v_lshl_add_u64 v[128:129], s[2:3], 0, v[158:159]
	s_add_i32 m0, s20, 0x2000
	s_nop 0
	global_load_lds_dwordx4 v[128:129], off
	s_waitcnt vmcnt(6)
	s_barrier
	s_setprio 1
	v_mfma_f32_16x16x32_bf16 v[52:55], v[198:201], v[144:147], v[52:55]
	v_mfma_f32_16x16x32_bf16 v[48:51], v[210:213], v[144:147], v[48:51]
	v_mfma_f32_16x16x32_bf16 v[36:39], v[198:201], v[168:171], v[36:39]
	v_mfma_f32_16x16x32_bf16 v[32:35], v[210:213], v[168:171], v[32:35]
	v_mfma_f32_16x16x32_bf16 v[20:23], v[198:201], v[176:179], v[20:23]
	v_mfma_f32_16x16x32_bf16 v[16:19], v[210:213], v[176:179], v[16:19]
	v_mfma_f32_16x16x32_bf16 v[4:7], v[198:201], v[190:193], v[4:7]
	v_mfma_f32_16x16x32_bf16 v[0:3], v[210:213], v[190:193], v[0:3]
	v_mfma_f32_16x16x32_bf16 v[52:55], v[202:205], v[148:151], v[52:55]
	v_mfma_f32_16x16x32_bf16 v[48:51], v[214:217], v[148:151], v[48:51]
	v_mfma_f32_16x16x32_bf16 v[36:39], v[202:205], v[172:175], v[36:39]
	v_mfma_f32_16x16x32_bf16 v[32:35], v[214:217], v[172:175], v[32:35]
	v_mfma_f32_16x16x32_bf16 v[20:23], v[202:205], v[180:183], v[20:23]
	v_mfma_f32_16x16x32_bf16 v[16:19], v[214:217], v[180:183], v[16:19]
	v_mfma_f32_16x16x32_bf16 v[4:7], v[202:205], v[194:197], v[4:7]
	v_mfma_f32_16x16x32_bf16 v[0:3], v[214:217], v[194:197], v[0:3]
	s_setprio 0
	s_add_i32 s42, s42, 2
	s_add_u32 s40, s40, 0x100
	s_addc_u32 s41, s41, 0
	s_cmpk_gt_u32 s42, 0x55
	s_mov_b64 s[2:3], s[18:19]
	s_barrier
	s_cbranch_scc0 .LBB0_914
	v_mbcnt_lo_u32_b32 v128, -1, 0
	v_mbcnt_hi_u32_b32 v128, -1, v128
	s_lshl_b32 s2, s52, 8
	v_ashrrev_i32_e32 v129, 4, v128
	v_and_b32_e32 v128, 15, v128
	s_add_i32 s2, s2, s22
	v_readlane_b32 s3, v254, 19
	v_add_u32_e32 v172, s2, v128
	s_lshl_b32 s2, s8, 8
	s_or_b32 s2, s2, s3
	v_lshl_add_u32 v168, v129, 3, s2
	v_ashrrev_i32_e32 v169, 31, v168
	v_lshlrev_b64 v[190:191], 1, v[168:169]
	v_ashrrev_i32_e32 v173, 31, v172
	v_lshl_add_u64 v[170:171], s[6:7], 0, v[190:191]
	v_lshlrev_b64 v[192:193], 12, v[172:173]
	v_lshl_add_u64 v[132:133], v[170:171], 0, v[192:193]
	v_cmp_eq_u32_e32 vcc, 0, v129
	global_load_dwordx4 v[128:131], v[132:133], off
	v_add_u32_e32 v182, 16, v172
	v_ashrrev_i32_e32 v183, 31, v182
	v_add_u32_e32 v178, 32, v172
	v_lshlrev_b64 v[184:185], 12, v[182:183]
	v_ashrrev_i32_e32 v179, 31, v178
	v_add_u32_e32 v174, 48, v172
	v_lshlrev_b64 v[180:181], 12, v[178:179]
	v_ashrrev_i32_e32 v175, 31, v174
	v_lshlrev_b64 v[176:177], 12, v[174:175]
	v_lshl_add_u64 v[192:193], s[6:7], 0, v[192:193]
	v_lshl_add_u64 v[190:191], v[192:193], 0, v[190:191]
	s_lshl_b32 s18, s8, 2
	s_ashr_i32 s19, s18, 31
	s_waitcnt vmcnt(0)
	v_lshlrev_b32_e32 v194, 16, v128
	v_and_b32_e32 v195, 0xffff0000, v128
	v_lshlrev_b32_e32 v196, 16, v129
	v_and_b32_e32 v197, 0xffff0000, v129
	v_lshlrev_b32_e32 v198, 16, v130
	v_and_b32_e32 v199, 0xffff0000, v130
	v_lshlrev_b32_e32 v200, 16, v131
	v_and_b32_e32 v201, 0xffff0000, v131
	global_load_dwordx4 v[128:131], v[132:133], off offset:256
	v_pk_add_f32 v[126:127], v[126:127], v[196:197]
	v_pk_add_f32 v[124:125], v[124:125], v[194:195]
	v_pk_add_f32 v[196:197], v[120:121], v[198:199]
	v_pk_add_f32 v[194:195], v[122:123], v[200:201]
	s_waitcnt vmcnt(0)
; __device__ __forceinline__ unsigned cvt_pk_bf16(float lo, float hi) { unsigned r; asm volatile("v_cvt_pk_bf16_f32 %0, %1, %2" : "=v"(r) : "v"(lo), "v"(hi)); return r; }
; __device__ __forceinline__ float bflo(unsigned w) { return __uint_as_float(w << 16); }
; __device__ __forceinline__ float bfhi(unsigned w) { return __uint_as_float(w & 0xffff0000u); }
;     __device__ __forceinline__ void operator()(f32x4 (&acc)[2][2][4][2], const Unit& u, int wr, int wc, int fr, int fq) const {
;     ...
;                 for (int bj = 0; bj < 2; ++bj) { const size_t o = (size_t)(row0 + ai * HALF + m * 16) * DM + col0 + bj * HALF;
;                     if (RB) { const u32x4 w = *(const u32x4*)((const bf16_t*)res + o); r[m][bj][0] = (f32x4){bflo(w.x), bfhi(w.x), bflo(w.y), bfhi(w.y)}; r[m][bj][1] = (f32x4){bflo(w.z), bfhi(w.z), bflo(w.w), bfhi(w.w)}; }
;                     else { r[m][bj][0] = __builtin_nontemporal_load((const f32x4*)((const float*)res + o)); r[m][bj][1] = __builtin_nontemporal_load((const f32x4*)((const float*)res + o + 4)); } }
; #pragma unroll
;             for (int m = 0; m < 4; ++m) { const int row = row0 + ai * HALF + m * 16; const size_t off = (size_t)row * DM + col0; float s = 0.f;
; #pragma unroll
;                 for (int bj = 0; bj < 2; ++bj) { const f32x4 v0 = acc[ai][bj][m][0] + r[m][bj][0], v1 = acc[ai][bj][m][1] + r[m][bj][1];
;                     u32x4 w; w.x = cvt_pk_bf16(v0[0], v0[1]); w.y = cvt_pk_bf16(v0[2], v0[3]); w.z = cvt_pk_bf16(v1[0], v1[1]); w.w = cvt_pk_bf16(v1[2], v1[3]);
;                     *(u32x4*)(outb + off + bj * HALF) = w;
;                     s += ((v0[0] * v0[0] + v0[1] * v0[1]) + (v0[2] * v0[2] + v0[3] * v0[3])) + ((v1[0] * v1[0] + v1[1] * v1[1]) + (v1[2] * v1[2] + v1[3] * v1[3])); }
;                 s += __shfl_xor(s, 16); s += __shfl_xor(s, 32);
;                 if (fq == 0) ssq[(size_t)row * 32 + u.pn * 4 + wc] = s; }
	v_lshlrev_b32_e32 v202, 16, v128
	v_and_b32_e32 v203, 0xffff0000, v128
	v_lshlrev_b32_e32 v204, 16, v129
	v_and_b32_e32 v205, 0xffff0000, v129
	v_lshl_add_u64 v[128:129], v[170:171], 0, v[184:185]
	global_load_dwordx4 v[148:151], v[128:129], off
	global_load_dwordx4 v[144:147], v[128:129], off offset:256
	v_lshl_add_u64 v[128:129], v[170:171], 0, v[180:181]
	global_load_dwordx4 v[140:143], v[128:129], off
	global_load_dwordx4 v[136:139], v[128:129], off offset:256
	v_lshl_add_u64 v[128:129], v[170:171], 0, v[176:177]
	v_lshlrev_b32_e32 v206, 16, v130
	v_and_b32_e32 v207, 0xffff0000, v130
	v_lshlrev_b32_e32 v210, 16, v131
	v_and_b32_e32 v211, 0xffff0000, v131
	global_load_dwordx4 v[132:135], v[128:129], off
	s_nop 0
	global_load_dwordx4 v[128:131], v[128:129], off offset:256
	v_cvt_pk_bf16_f32 v120, v124, v125
	v_cvt_pk_bf16_f32 v121, v126, v127
	v_cvt_pk_bf16_f32 v122, v196, v197
	v_cvt_pk_bf16_f32 v123, v194, v195
	global_store_dwordx4 v[190:191], v[120:123], off sc1
	v_pk_add_f32 v[118:119], v[118:119], v[204:205]
	v_pk_add_f32 v[116:117], v[116:117], v[202:203]
	v_mul_f32_e32 v120, v125, v125
	v_mul_f32_e32 v121, v127, v127
	v_fmac_f32_e32 v120, v124, v124
	v_fmac_f32_e32 v121, v126, v126
	v_add_f32_e32 v120, v120, v121
	v_mul_f32_e32 v121, v197, v197
	v_mul_f32_e32 v122, v195, v195
	v_fmac_f32_e32 v121, v196, v196
	v_fmac_f32_e32 v122, v194, v194
	v_add_f32_e32 v121, v121, v122
	v_pk_add_f32 v[122:123], v[112:113], v[206:207]
	v_cvt_pk_bf16_f32 v112, v116, v117
	v_cvt_pk_bf16_f32 v113, v118, v119
	v_add_f32_e32 v124, v120, v121
	v_pk_add_f32 v[120:121], v[114:115], v[210:211]
	v_cvt_pk_bf16_f32 v114, v122, v123
	s_nop 0
	v_cvt_pk_bf16_f32 v115, v120, v121
	global_store_dwordx4 v[190:191], v[112:115], off offset:256 sc1
	s_nop 1
	v_mul_f32_e32 v112, v117, v117
	v_mul_f32_e32 v113, v119, v119
	v_fmac_f32_e32 v112, v116, v116
	v_fmac_f32_e32 v113, v118, v118
	v_add_f32_e32 v112, v112, v113
	v_mul_f32_e32 v113, v123, v123
	v_mul_f32_e32 v114, v121, v121
	v_fmac_f32_e32 v113, v122, v122
	v_fmac_f32_e32 v114, v120, v120
	v_add_f32_e32 v113, v113, v114
	v_add_f32_e32 v112, v112, v113
	v_and_b32_e32 v114, 64, v209
	v_add_f32_e32 v113, v124, v112
	v_xor_b32_e32 v112, 16, v209
	v_add_u32_e32 v115, 64, v114
	v_cmp_lt_i32_e64 s[2:3], v112, v115
	s_nop 1
	v_cndmask_b32_e64 v112, v209, v112, s[2:3]
	v_lshlrev_b32_e32 v112, 2, v112
	ds_bpermute_b32 v114, v112, v113
	s_waitcnt lgkmcnt(0)
	v_add_f32_e32 v114, v113, v114
	v_xor_b32_e32 v113, 32, v209
	v_cmp_lt_i32_e64 s[2:3], v113, v115
	s_nop 1
	v_cndmask_b32_e64 v113, v209, v113, s[2:3]
	v_lshlrev_b32_e32 v113, 2, v113
	ds_bpermute_b32 v115, v113, v114
	s_and_saveexec_b64 s[2:3], vcc
	s_cbranch_execz .LBB0_917
	v_lshlrev_b64 v[116:117], 7, v[172:173]
	v_lshl_add_u64 v[116:117], s[16:17], 0, v[116:117]
	v_lshl_add_u64 v[116:117], s[18:19], 2, v[116:117]
	s_lshl_b32 s8, s27, 2
	v_lshl_add_u64 v[116:117], v[116:117], 0, s[8:9]
	s_waitcnt lgkmcnt(0)
	v_add_f32_e32 v114, v114, v115
	global_store_dword v[116:117], v114, off
.LBB0_917:
	s_or_b64 exec, exec, s[2:3]
	s_waitcnt vmcnt(7)
	v_lshlrev_b32_e32 v114, 16, v148
	s_waitcnt lgkmcnt(0)
	v_and_b32_e32 v115, 0xffff0000, v148
	v_lshlrev_b32_e32 v116, 16, v149
	v_and_b32_e32 v117, 0xffff0000, v149
	v_lshlrev_b32_e32 v118, 16, v150
	v_and_b32_e32 v119, 0xffff0000, v150
	v_pk_add_f32 v[108:109], v[108:109], v[114:115]
	v_pk_add_f32 v[110:111], v[110:111], v[116:117]
	v_pk_add_f32 v[116:117], v[104:105], v[118:119]
	v_cvt_pk_bf16_f32 v104, v108, v109
	v_mul_f32_e32 v109, v109, v109
	v_lshlrev_b32_e32 v120, 16, v151
	v_and_b32_e32 v121, 0xffff0000, v151
	v_fmac_f32_e32 v109, v108, v108
	v_mul_f32_e32 v108, v111, v111
	v_pk_add_f32 v[114:115], v[106:107], v[120:121]
	v_fmac_f32_e32 v108, v110, v110
	s_waitcnt vmcnt(6)
	v_lshlrev_b32_e32 v122, 16, v144
	v_and_b32_e32 v123, 0xffff0000, v144
	v_lshlrev_b32_e32 v124, 16, v145
	v_and_b32_e32 v125, 0xffff0000, v145
	v_cvt_pk_bf16_f32 v105, v110, v111
	v_add_f32_e32 v108, v109, v108
	v_mul_f32_e32 v109, v117, v117
	v_mul_f32_e32 v110, v115, v115
	v_lshlrev_b32_e32 v126, 16, v146
	v_and_b32_e32 v127, 0xffff0000, v146
	v_fmac_f32_e32 v109, v116, v116
	v_fmac_f32_e32 v110, v114, v114
	v_pk_add_f32 v[102:103], v[102:103], v[124:125]
	v_pk_add_f32 v[100:101], v[100:101], v[122:123]
	v_lshlrev_b32_e32 v144, 16, v147
	v_and_b32_e32 v145, 0xffff0000, v147
	v_add_f32_e32 v109, v109, v110
	v_pk_add_f32 v[110:111], v[96:97], v[126:127]
	v_mul_f32_e32 v96, v101, v101
	v_mul_f32_e32 v97, v103, v103
	v_cvt_pk_bf16_f32 v106, v116, v117
	v_cvt_pk_bf16_f32 v107, v114, v115
	v_add_f32_e32 v114, v108, v109
	v_pk_add_f32 v[108:109], v[98:99], v[144:145]
	v_fmac_f32_e32 v96, v100, v100
	v_fmac_f32_e32 v97, v102, v102
	v_add_f32_e32 v96, v96, v97
	v_mul_f32_e32 v97, v111, v111
	v_mul_f32_e32 v98, v109, v109
	v_fmac_f32_e32 v97, v110, v110
	v_fmac_f32_e32 v98, v108, v108
	v_add_f32_e32 v97, v97, v98
	v_add_f32_e32 v96, v96, v97
	v_add_f32_e32 v99, v114, v96
	ds_bpermute_b32 v116, v112, v99
	v_lshl_add_u64 v[96:97], s[6:7], 0, v[184:185]
	v_lshl_add_u64 v[114:115], v[168:169], 1, v[96:97]
	global_store_dwordx4 v[114:115], v[104:107], off sc1
	v_cvt_pk_bf16_f32 v98, v100, v101
	s_waitcnt lgkmcnt(0)
	v_add_f32_e32 v96, v99, v116
	ds_bpermute_b32 v97, v113, v96
	v_cvt_pk_bf16_f32 v99, v102, v103
	v_cvt_pk_bf16_f32 v100, v110, v111
	v_cvt_pk_bf16_f32 v101, v108, v109
	global_store_dwordx4 v[114:115], v[98:101], off offset:256 sc1
	s_and_saveexec_b64 s[2:3], vcc
	s_cbranch_execz .LBB0_919
	v_lshlrev_b64 v[98:99], 7, v[182:183]
	v_lshl_add_u64 v[98:99], s[16:17], 0, v[98:99]
	v_lshl_add_u64 v[98:99], s[18:19], 2, v[98:99]
	s_lshl_b32 s8, s27, 2
	v_lshl_add_u64 v[98:99], v[98:99], 0, s[8:9]
	s_waitcnt lgkmcnt(0)
	v_add_f32_e32 v96, v96, v97
	global_store_dword v[98:99], v96, off
; __device__ __forceinline__ unsigned cvt_pk_bf16(float lo, float hi) { unsigned r; asm volatile("v_cvt_pk_bf16_f32 %0, %1, %2" : "=v"(r) : "v"(lo), "v"(hi)); return r; }
; __device__ __forceinline__ float bflo(unsigned w) { return __uint_as_float(w << 16); }
; __device__ __forceinline__ float bfhi(unsigned w) { return __uint_as_float(w & 0xffff0000u); }
;     __device__ __forceinline__ void operator()(f32x4 (&acc)[2][2][4][2], const Unit& u, int wr, int wc, int fr, int fq) const {
;     ...
;                 for (int bj = 0; bj < 2; ++bj) { const size_t o = (size_t)(row0 + ai * HALF + m * 16) * DM + col0 + bj * HALF;
;                     if (RB) { const u32x4 w = *(const u32x4*)((const bf16_t*)res + o); r[m][bj][0] = (f32x4){bflo(w.x), bfhi(w.x), bflo(w.y), bfhi(w.y)}; r[m][bj][1] = (f32x4){bflo(w.z), bfhi(w.z), bflo(w.w), bfhi(w.w)}; }
;                     else { r[m][bj][0] = __builtin_nontemporal_load((const f32x4*)((const float*)res + o)); r[m][bj][1] = __builtin_nontemporal_load((const f32x4*)((const float*)res + o + 4)); } }
; #pragma unroll
;             for (int m = 0; m < 4; ++m) { const int row = row0 + ai * HALF + m * 16; const size_t off = (size_t)row * DM + col0; float s = 0.f;
; #pragma unroll
;                 for (int bj = 0; bj < 2; ++bj) { const f32x4 v0 = acc[ai][bj][m][0] + r[m][bj][0], v1 = acc[ai][bj][m][1] + r[m][bj][1];
;                     u32x4 w; w.x = cvt_pk_bf16(v0[0], v0[1]); w.y = cvt_pk_bf16(v0[2], v0[3]); w.z = cvt_pk_bf16(v1[0], v1[1]); w.w = cvt_pk_bf16(v1[2], v1[3]);
;                     *(u32x4*)(outb + off + bj * HALF) = w;
;                     s += ((v0[0] * v0[0] + v0[1] * v0[1]) + (v0[2] * v0[2] + v0[3] * v0[3])) + ((v1[0] * v1[0] + v1[1] * v1[1]) + (v1[2] * v1[2] + v1[3] * v1[3])); }
;                 s += __shfl_xor(s, 16); s += __shfl_xor(s, 32);
;                 if (fq == 0) ssq[(size_t)row * 32 + u.pn * 4 + wc] = s; }
.LBB0_919:
	s_or_b64 exec, exec, s[2:3]
	s_waitcnt vmcnt(7)
	v_lshlrev_b32_e32 v96, 16, v140
	s_waitcnt lgkmcnt(0)
	v_and_b32_e32 v97, 0xffff0000, v140
	v_lshlrev_b32_e32 v98, 16, v141
	v_and_b32_e32 v99, 0xffff0000, v141
	v_lshlrev_b32_e32 v100, 16, v142
	v_and_b32_e32 v101, 0xffff0000, v142
	v_pk_add_f32 v[92:93], v[92:93], v[96:97]
	v_pk_add_f32 v[94:95], v[94:95], v[98:99]
	v_pk_add_f32 v[98:99], v[88:89], v[100:101]
	v_cvt_pk_bf16_f32 v88, v92, v93
	v_mul_f32_e32 v93, v93, v93
	v_lshlrev_b32_e32 v102, 16, v143
	v_and_b32_e32 v103, 0xffff0000, v143
	v_fmac_f32_e32 v93, v92, v92
	v_mul_f32_e32 v92, v95, v95
	v_pk_add_f32 v[96:97], v[90:91], v[102:103]
	v_fmac_f32_e32 v92, v94, v94
	s_waitcnt vmcnt(6)
	v_lshlrev_b32_e32 v104, 16, v136
	v_and_b32_e32 v105, 0xffff0000, v136
	v_lshlrev_b32_e32 v106, 16, v137
	v_and_b32_e32 v107, 0xffff0000, v137
	v_cvt_pk_bf16_f32 v89, v94, v95
	v_add_f32_e32 v92, v93, v92
	v_mul_f32_e32 v93, v99, v99
	v_mul_f32_e32 v94, v97, v97
	v_lshlrev_b32_e32 v108, 16, v138
	v_and_b32_e32 v109, 0xffff0000, v138
	v_fmac_f32_e32 v93, v98, v98
	v_fmac_f32_e32 v94, v96, v96
	v_pk_add_f32 v[86:87], v[86:87], v[106:107]
	v_pk_add_f32 v[84:85], v[84:85], v[104:105]
	v_lshlrev_b32_e32 v110, 16, v139
	v_and_b32_e32 v111, 0xffff0000, v139
	v_add_f32_e32 v93, v93, v94
	v_pk_add_f32 v[94:95], v[80:81], v[108:109]
	v_mul_f32_e32 v80, v85, v85
	v_mul_f32_e32 v81, v87, v87
	v_cvt_pk_bf16_f32 v90, v98, v99
	v_cvt_pk_bf16_f32 v91, v96, v97
	v_add_f32_e32 v96, v92, v93
	v_pk_add_f32 v[92:93], v[82:83], v[110:111]
	v_fmac_f32_e32 v80, v84, v84
	v_fmac_f32_e32 v81, v86, v86
	v_add_f32_e32 v80, v80, v81
	v_mul_f32_e32 v81, v95, v95
	v_mul_f32_e32 v82, v93, v93
	v_fmac_f32_e32 v81, v94, v94
	v_fmac_f32_e32 v82, v92, v92
	v_add_f32_e32 v81, v81, v82
	v_add_f32_e32 v80, v80, v81
	v_add_f32_e32 v83, v96, v80
	ds_bpermute_b32 v98, v112, v83
	v_lshl_add_u64 v[80:81], s[6:7], 0, v[180:181]
	v_lshl_add_u64 v[96:97], v[168:169], 1, v[80:81]
	global_store_dwordx4 v[96:97], v[88:91], off sc1
	v_cvt_pk_bf16_f32 v82, v84, v85
	s_waitcnt lgkmcnt(0)
	v_add_f32_e32 v80, v83, v98
	ds_bpermute_b32 v81, v113, v80
	v_cvt_pk_bf16_f32 v83, v86, v87
	v_cvt_pk_bf16_f32 v84, v94, v95
	v_cvt_pk_bf16_f32 v85, v92, v93
	global_store_dwordx4 v[96:97], v[82:85], off offset:256 sc1
	s_and_saveexec_b64 s[2:3], vcc
	s_cbranch_execz .LBB0_921
	v_lshlrev_b64 v[82:83], 7, v[178:179]
	v_lshl_add_u64 v[82:83], s[16:17], 0, v[82:83]
	v_lshl_add_u64 v[82:83], s[18:19], 2, v[82:83]
	s_lshl_b32 s8, s27, 2
	v_lshl_add_u64 v[82:83], v[82:83], 0, s[8:9]
	s_waitcnt lgkmcnt(0)
	v_add_f32_e32 v80, v80, v81
	global_store_dword v[82:83], v80, off
.LBB0_921:
	s_or_b64 exec, exec, s[2:3]
	s_waitcnt vmcnt(7)
	v_lshlrev_b32_e32 v80, 16, v132
	s_waitcnt lgkmcnt(0)
	v_and_b32_e32 v81, 0xffff0000, v132
	v_lshlrev_b32_e32 v82, 16, v133
	v_and_b32_e32 v83, 0xffff0000, v133
	v_lshlrev_b32_e32 v84, 16, v134
	v_and_b32_e32 v85, 0xffff0000, v134
	v_pk_add_f32 v[76:77], v[76:77], v[80:81]
	v_pk_add_f32 v[78:79], v[78:79], v[82:83]
	v_pk_add_f32 v[82:83], v[72:73], v[84:85]
	v_cvt_pk_bf16_f32 v72, v76, v77
	v_mul_f32_e32 v77, v77, v77
	v_lshlrev_b32_e32 v86, 16, v135
	v_and_b32_e32 v87, 0xffff0000, v135
	v_fmac_f32_e32 v77, v76, v76
	v_mul_f32_e32 v76, v79, v79
	v_pk_add_f32 v[80:81], v[74:75], v[86:87]
	v_fmac_f32_e32 v76, v78, v78
	s_waitcnt vmcnt(6)
	v_lshlrev_b32_e32 v88, 16, v128
	v_and_b32_e32 v89, 0xffff0000, v128
	v_lshlrev_b32_e32 v90, 16, v129
	v_and_b32_e32 v91, 0xffff0000, v129
	v_cvt_pk_bf16_f32 v73, v78, v79
	v_add_f32_e32 v76, v77, v76
	v_mul_f32_e32 v77, v83, v83
	v_mul_f32_e32 v78, v81, v81
	v_lshlrev_b32_e32 v92, 16, v130
	v_and_b32_e32 v93, 0xffff0000, v130
	v_fmac_f32_e32 v77, v82, v82
	v_fmac_f32_e32 v78, v80, v80
	v_pk_add_f32 v[70:71], v[70:71], v[90:91]
	v_pk_add_f32 v[68:69], v[68:69], v[88:89]
	v_lshlrev_b32_e32 v94, 16, v131
	v_and_b32_e32 v95, 0xffff0000, v131
	v_add_f32_e32 v77, v77, v78
	v_pk_add_f32 v[78:79], v[64:65], v[92:93]
	v_mul_f32_e32 v64, v69, v69
	v_mul_f32_e32 v65, v71, v71
	v_cvt_pk_bf16_f32 v74, v82, v83
	v_cvt_pk_bf16_f32 v75, v80, v81
	v_add_f32_e32 v80, v76, v77
	v_pk_add_f32 v[76:77], v[66:67], v[94:95]
	v_fmac_f32_e32 v64, v68, v68
	v_fmac_f32_e32 v65, v70, v70
	v_add_f32_e32 v64, v64, v65
	v_mul_f32_e32 v65, v79, v79
	v_mul_f32_e32 v66, v77, v77
	v_fmac_f32_e32 v65, v78, v78
	v_fmac_f32_e32 v66, v76, v76
	v_add_f32_e32 v65, v65, v66
	v_add_f32_e32 v64, v64, v65
	v_add_f32_e32 v67, v80, v64
	ds_bpermute_b32 v82, v112, v67
	v_lshl_add_u64 v[64:65], s[6:7], 0, v[176:177]
	v_lshl_add_u64 v[80:81], v[168:169], 1, v[64:65]
	global_store_dwordx4 v[80:81], v[72:75], off sc1
	v_cvt_pk_bf16_f32 v66, v68, v69
	s_waitcnt lgkmcnt(0)
	v_add_f32_e32 v64, v67, v82
	ds_bpermute_b32 v65, v113, v64
	v_cvt_pk_bf16_f32 v67, v70, v71
	v_cvt_pk_bf16_f32 v68, v78, v79
	v_cvt_pk_bf16_f32 v69, v76, v77
	global_store_dwordx4 v[80:81], v[66:69], off offset:256 sc1
	s_and_saveexec_b64 s[2:3], vcc
	s_cbranch_execz .LBB0_923
	v_lshlrev_b64 v[66:67], 7, v[174:175]
	v_lshl_add_u64 v[66:67], s[16:17], 0, v[66:67]
	v_lshl_add_u64 v[66:67], s[18:19], 2, v[66:67]
	s_lshl_b32 s8, s27, 2
	v_lshl_add_u64 v[66:67], v[66:67], 0, s[8:9]
	s_waitcnt lgkmcnt(0)
	v_add_f32_e32 v64, v64, v65
	global_store_dword v[66:67], v64, off
; __device__ __forceinline__ unsigned cvt_pk_bf16(float lo, float hi) { unsigned r; asm volatile("v_cvt_pk_bf16_f32 %0, %1, %2" : "=v"(r) : "v"(lo), "v"(hi)); return r; }
; __device__ __forceinline__ float bflo(unsigned w) { return __uint_as_float(w << 16); }
; __device__ __forceinline__ float bfhi(unsigned w) { return __uint_as_float(w & 0xffff0000u); }
;     __device__ __forceinline__ void operator()(f32x4 (&acc)[2][2][4][2], const Unit& u, int wr, int wc, int fr, int fq) const {
;     ...
;                 for (int bj = 0; bj < 2; ++bj) { const size_t o = (size_t)(row0 + ai * HALF + m * 16) * DM + col0 + bj * HALF;
;                     if (RB) { const u32x4 w = *(const u32x4*)((const bf16_t*)res + o); r[m][bj][0] = (f32x4){bflo(w.x), bfhi(w.x), bflo(w.y), bfhi(w.y)}; r[m][bj][1] = (f32x4){bflo(w.z), bfhi(w.z), bflo(w.w), bfhi(w.w)}; }
;                     else { r[m][bj][0] = __builtin_nontemporal_load((const f32x4*)((const float*)res + o)); r[m][bj][1] = __builtin_nontemporal_load((const f32x4*)((const float*)res + o + 4)); } }
; #pragma unroll
;             for (int m = 0; m < 4; ++m) { const int row = row0 + ai * HALF + m * 16; const size_t off = (size_t)row * DM + col0; float s = 0.f;
; #pragma unroll
;                 for (int bj = 0; bj < 2; ++bj) { const f32x4 v0 = acc[ai][bj][m][0] + r[m][bj][0], v1 = acc[ai][bj][m][1] + r[m][bj][1];
;                     u32x4 w; w.x = cvt_pk_bf16(v0[0], v0[1]); w.y = cvt_pk_bf16(v0[2], v0[3]); w.z = cvt_pk_bf16(v1[0], v1[1]); w.w = cvt_pk_bf16(v1[2], v1[3]);
;                     *(u32x4*)(outb + off + bj * HALF) = w;
;                     s += ((v0[0] * v0[0] + v0[1] * v0[1]) + (v0[2] * v0[2] + v0[3] * v0[3])) + ((v1[0] * v1[0] + v1[1] * v1[1]) + (v1[2] * v1[2] + v1[3] * v1[3])); }
;                 s += __shfl_xor(s, 16); s += __shfl_xor(s, 32);
;                 if (fq == 0) ssq[(size_t)row * 32 + u.pn * 4 + wc] = s; }
.LBB0_923:
	s_or_b64 exec, exec, s[2:3]
	v_add_u32_e32 v100, 0x80, v172
	v_ashrrev_i32_e32 v101, 31, v100
	v_lshlrev_b64 v[110:111], 12, v[100:101]
	v_lshl_add_u64 v[68:69], v[170:171], 0, v[110:111]
	s_waitcnt lgkmcnt(0)
	global_load_dwordx4 v[64:67], v[68:69], off
	v_add_u32_e32 v96, 0x90, v172
	v_ashrrev_i32_e32 v97, 31, v96
	v_add_u32_e32 v92, 0xa0, v172
	v_lshlrev_b64 v[98:99], 12, v[96:97]
	v_ashrrev_i32_e32 v93, 31, v92
	v_add_u32_e32 v88, 0xb0, v172
	v_lshlrev_b64 v[94:95], 12, v[92:93]
	v_ashrrev_i32_e32 v89, 31, v88
	v_lshlrev_b64 v[90:91], 12, v[88:89]
	v_lshl_add_u64 v[110:111], s[6:7], 0, v[110:111]
	v_lshl_add_u64 v[110:111], v[168:169], 1, v[110:111]
	s_waitcnt vmcnt(0)
	v_lshlrev_b32_e32 v114, 16, v64
	v_and_b32_e32 v115, 0xffff0000, v64
	v_lshlrev_b32_e32 v116, 16, v65
	v_and_b32_e32 v117, 0xffff0000, v65
	v_lshlrev_b32_e32 v118, 16, v66
	v_and_b32_e32 v119, 0xffff0000, v66
	v_lshlrev_b32_e32 v120, 16, v67
	v_and_b32_e32 v121, 0xffff0000, v67
	global_load_dwordx4 v[64:67], v[68:69], off offset:256
	v_pk_add_f32 v[62:63], v[62:63], v[116:117]
	v_pk_add_f32 v[60:61], v[60:61], v[114:115]
	v_pk_add_f32 v[116:117], v[56:57], v[118:119]
	v_pk_add_f32 v[114:115], v[58:59], v[120:121]
	s_waitcnt vmcnt(0)
	v_lshlrev_b32_e32 v104, 16, v64
	v_and_b32_e32 v105, 0xffff0000, v64
	v_lshlrev_b32_e32 v108, 16, v65
	v_and_b32_e32 v109, 0xffff0000, v65
	v_lshl_add_u64 v[64:65], v[170:171], 0, v[98:99]
	global_load_dwordx4 v[84:87], v[64:65], off
	global_load_dwordx4 v[80:83], v[64:65], off offset:256
	v_lshl_add_u64 v[64:65], v[170:171], 0, v[94:95]
	global_load_dwordx4 v[76:79], v[64:65], off
	global_load_dwordx4 v[72:75], v[64:65], off offset:256
	v_lshl_add_u64 v[64:65], v[170:171], 0, v[90:91]
	v_lshlrev_b32_e32 v102, 16, v66
	v_and_b32_e32 v103, 0xffff0000, v66
	v_lshlrev_b32_e32 v106, 16, v67
	v_and_b32_e32 v107, 0xffff0000, v67
	global_load_dwordx4 v[68:71], v[64:65], off
	s_nop 0
	global_load_dwordx4 v[64:67], v[64:65], off offset:256
	v_cvt_pk_bf16_f32 v56, v60, v61
	v_cvt_pk_bf16_f32 v57, v62, v63
	v_cvt_pk_bf16_f32 v58, v116, v117
	v_cvt_pk_bf16_f32 v59, v114, v115
	global_store_dwordx4 v[110:111], v[56:59], off sc1
	v_pk_add_f32 v[54:55], v[54:55], v[108:109]
	v_pk_add_f32 v[52:53], v[52:53], v[104:105]
	v_mul_f32_e32 v56, v61, v61
	v_mul_f32_e32 v57, v63, v63
	v_fmac_f32_e32 v56, v60, v60
	v_fmac_f32_e32 v57, v62, v62
	v_add_f32_e32 v56, v56, v57
	v_mul_f32_e32 v57, v117, v117
	v_mul_f32_e32 v58, v115, v115
	v_fmac_f32_e32 v57, v116, v116
	v_fmac_f32_e32 v58, v114, v114
	v_add_f32_e32 v57, v57, v58
	v_pk_add_f32 v[58:59], v[48:49], v[102:103]
	v_cvt_pk_bf16_f32 v48, v52, v53
	v_cvt_pk_bf16_f32 v49, v54, v55
	v_add_f32_e32 v60, v56, v57
	v_pk_add_f32 v[56:57], v[50:51], v[106:107]
	v_cvt_pk_bf16_f32 v50, v58, v59
	s_nop 0
	v_cvt_pk_bf16_f32 v51, v56, v57
	global_store_dwordx4 v[110:111], v[48:51], off offset:256 sc1
	s_nop 1
	v_mul_f32_e32 v48, v53, v53
	v_mul_f32_e32 v49, v55, v55
	v_fmac_f32_e32 v48, v52, v52
	v_fmac_f32_e32 v49, v54, v54
	v_add_f32_e32 v48, v48, v49
	v_mul_f32_e32 v49, v59, v59
	v_mul_f32_e32 v50, v57, v57
	v_fmac_f32_e32 v49, v58, v58
	v_fmac_f32_e32 v50, v56, v56
	v_add_f32_e32 v49, v49, v50
	v_add_f32_e32 v48, v48, v49
	v_add_f32_e32 v48, v60, v48
	ds_bpermute_b32 v49, v112, v48
	s_waitcnt lgkmcnt(0)
	v_add_f32_e32 v48, v48, v49
	ds_bpermute_b32 v49, v113, v48
	s_and_saveexec_b64 s[2:3], vcc
	s_cbranch_execz .LBB0_925
	v_lshlrev_b64 v[50:51], 7, v[100:101]
	v_lshl_add_u64 v[50:51], s[16:17], 0, v[50:51]
	v_lshl_add_u64 v[50:51], s[18:19], 2, v[50:51]
	s_lshl_b32 s8, s27, 2
	v_lshl_add_u64 v[50:51], v[50:51], 0, s[8:9]
	s_waitcnt lgkmcnt(0)
	v_add_f32_e32 v48, v48, v49
	global_store_dword v[50:51], v48, off
.LBB0_925:
	s_or_b64 exec, exec, s[2:3]
	s_waitcnt vmcnt(7)
	v_lshlrev_b32_e32 v48, 16, v84
	s_waitcnt lgkmcnt(0)
	v_and_b32_e32 v49, 0xffff0000, v84
	v_lshlrev_b32_e32 v50, 16, v85
	v_and_b32_e32 v51, 0xffff0000, v85
	v_lshlrev_b32_e32 v52, 16, v86
	v_and_b32_e32 v53, 0xffff0000, v86
	v_pk_add_f32 v[44:45], v[44:45], v[48:49]
	v_pk_add_f32 v[46:47], v[46:47], v[50:51]
	v_pk_add_f32 v[50:51], v[40:41], v[52:53]
	v_cvt_pk_bf16_f32 v40, v44, v45
	v_mul_f32_e32 v45, v45, v45
	v_lshlrev_b32_e32 v54, 16, v87
	v_and_b32_e32 v55, 0xffff0000, v87
	v_fmac_f32_e32 v45, v44, v44
	v_mul_f32_e32 v44, v47, v47
	v_pk_add_f32 v[48:49], v[42:43], v[54:55]
	v_fmac_f32_e32 v44, v46, v46
	s_waitcnt vmcnt(6)
	v_lshlrev_b32_e32 v56, 16, v80
	v_and_b32_e32 v57, 0xffff0000, v80
	v_lshlrev_b32_e32 v58, 16, v81
	v_and_b32_e32 v59, 0xffff0000, v81
	v_cvt_pk_bf16_f32 v41, v46, v47
	v_add_f32_e32 v44, v45, v44
	v_mul_f32_e32 v45, v51, v51
	v_mul_f32_e32 v46, v49, v49
	v_lshlrev_b32_e32 v60, 16, v82
	v_and_b32_e32 v61, 0xffff0000, v82
	v_fmac_f32_e32 v45, v50, v50
	v_fmac_f32_e32 v46, v48, v48
	v_pk_add_f32 v[38:39], v[38:39], v[58:59]
	v_pk_add_f32 v[36:37], v[36:37], v[56:57]
	v_lshlrev_b32_e32 v62, 16, v83
	v_and_b32_e32 v63, 0xffff0000, v83
	v_add_f32_e32 v45, v45, v46
	v_pk_add_f32 v[46:47], v[32:33], v[60:61]
	v_mul_f32_e32 v32, v37, v37
	v_mul_f32_e32 v33, v39, v39
	v_cvt_pk_bf16_f32 v42, v50, v51
	v_cvt_pk_bf16_f32 v43, v48, v49
	v_add_f32_e32 v48, v44, v45
	v_pk_add_f32 v[44:45], v[34:35], v[62:63]
	v_fmac_f32_e32 v32, v36, v36
	v_fmac_f32_e32 v33, v38, v38
	v_add_f32_e32 v32, v32, v33
	v_mul_f32_e32 v33, v47, v47
	v_mul_f32_e32 v34, v45, v45
	v_fmac_f32_e32 v33, v46, v46
	v_fmac_f32_e32 v34, v44, v44
	v_add_f32_e32 v33, v33, v34
	v_add_f32_e32 v32, v32, v33
	v_add_f32_e32 v35, v48, v32
	ds_bpermute_b32 v50, v112, v35
	v_lshl_add_u64 v[32:33], s[6:7], 0, v[98:99]
	v_lshl_add_u64 v[48:49], v[168:169], 1, v[32:33]
	global_store_dwordx4 v[48:49], v[40:43], off sc1
	v_cvt_pk_bf16_f32 v34, v36, v37
	s_waitcnt lgkmcnt(0)
	v_add_f32_e32 v32, v35, v50
	ds_bpermute_b32 v33, v113, v32
	v_cvt_pk_bf16_f32 v35, v38, v39
	v_cvt_pk_bf16_f32 v36, v46, v47
	v_cvt_pk_bf16_f32 v37, v44, v45
	global_store_dwordx4 v[48:49], v[34:37], off offset:256 sc1
	s_and_saveexec_b64 s[2:3], vcc
	s_cbranch_execz .LBB0_927
	v_lshlrev_b64 v[34:35], 7, v[96:97]
	v_lshl_add_u64 v[34:35], s[16:17], 0, v[34:35]
	v_lshl_add_u64 v[34:35], s[18:19], 2, v[34:35]
	s_lshl_b32 s8, s27, 2
	v_lshl_add_u64 v[34:35], v[34:35], 0, s[8:9]
	s_waitcnt lgkmcnt(0)
	v_add_f32_e32 v32, v32, v33
	global_store_dword v[34:35], v32, off
; __device__ __forceinline__ unsigned cvt_pk_bf16(float lo, float hi) { unsigned r; asm volatile("v_cvt_pk_bf16_f32 %0, %1, %2" : "=v"(r) : "v"(lo), "v"(hi)); return r; }
; __device__ __forceinline__ float bflo(unsigned w) { return __uint_as_float(w << 16); }
; __device__ __forceinline__ float bfhi(unsigned w) { return __uint_as_float(w & 0xffff0000u); }
;     __device__ __forceinline__ void operator()(f32x4 (&acc)[2][2][4][2], const Unit& u, int wr, int wc, int fr, int fq) const {
;     ...
;                 for (int bj = 0; bj < 2; ++bj) { const size_t o = (size_t)(row0 + ai * HALF + m * 16) * DM + col0 + bj * HALF;
;                     if (RB) { const u32x4 w = *(const u32x4*)((const bf16_t*)res + o); r[m][bj][0] = (f32x4){bflo(w.x), bfhi(w.x), bflo(w.y), bfhi(w.y)}; r[m][bj][1] = (f32x4){bflo(w.z), bfhi(w.z), bflo(w.w), bfhi(w.w)}; }
;                     else { r[m][bj][0] = __builtin_nontemporal_load((const f32x4*)((const float*)res + o)); r[m][bj][1] = __builtin_nontemporal_load((const f32x4*)((const float*)res + o + 4)); } }
; #pragma unroll
;             for (int m = 0; m < 4; ++m) { const int row = row0 + ai * HALF + m * 16; const size_t off = (size_t)row * DM + col0; float s = 0.f;
; #pragma unroll
;                 for (int bj = 0; bj < 2; ++bj) { const f32x4 v0 = acc[ai][bj][m][0] + r[m][bj][0], v1 = acc[ai][bj][m][1] + r[m][bj][1];
;                     u32x4 w; w.x = cvt_pk_bf16(v0[0], v0[1]); w.y = cvt_pk_bf16(v0[2], v0[3]); w.z = cvt_pk_bf16(v1[0], v1[1]); w.w = cvt_pk_bf16(v1[2], v1[3]);
;                     *(u32x4*)(outb + off + bj * HALF) = w;
;                     s += ((v0[0] * v0[0] + v0[1] * v0[1]) + (v0[2] * v0[2] + v0[3] * v0[3])) + ((v1[0] * v1[0] + v1[1] * v1[1]) + (v1[2] * v1[2] + v1[3] * v1[3])); }
;                 s += __shfl_xor(s, 16); s += __shfl_xor(s, 32);
;                 if (fq == 0) ssq[(size_t)row * 32 + u.pn * 4 + wc] = s; }
.LBB0_927:
	s_or_b64 exec, exec, s[2:3]
	s_waitcnt vmcnt(7)
	v_lshlrev_b32_e32 v32, 16, v76
	s_waitcnt lgkmcnt(0)
	v_and_b32_e32 v33, 0xffff0000, v76
	v_lshlrev_b32_e32 v34, 16, v77
	v_and_b32_e32 v35, 0xffff0000, v77
	v_lshlrev_b32_e32 v36, 16, v78
	v_and_b32_e32 v37, 0xffff0000, v78
	v_pk_add_f32 v[28:29], v[28:29], v[32:33]
	v_pk_add_f32 v[30:31], v[30:31], v[34:35]
	v_pk_add_f32 v[34:35], v[24:25], v[36:37]
	v_cvt_pk_bf16_f32 v24, v28, v29
	v_mul_f32_e32 v29, v29, v29
	v_lshlrev_b32_e32 v38, 16, v79
	v_and_b32_e32 v39, 0xffff0000, v79
	v_fmac_f32_e32 v29, v28, v28
	v_mul_f32_e32 v28, v31, v31
	v_pk_add_f32 v[32:33], v[26:27], v[38:39]
	v_fmac_f32_e32 v28, v30, v30
	s_waitcnt vmcnt(6)
	v_lshlrev_b32_e32 v40, 16, v72
	v_and_b32_e32 v41, 0xffff0000, v72
	v_lshlrev_b32_e32 v42, 16, v73
	v_and_b32_e32 v43, 0xffff0000, v73
	v_cvt_pk_bf16_f32 v25, v30, v31
	v_add_f32_e32 v28, v29, v28
	v_mul_f32_e32 v29, v35, v35
	v_mul_f32_e32 v30, v33, v33
	v_lshlrev_b32_e32 v44, 16, v74
	v_and_b32_e32 v45, 0xffff0000, v74
	v_fmac_f32_e32 v29, v34, v34
	v_fmac_f32_e32 v30, v32, v32
	v_pk_add_f32 v[22:23], v[22:23], v[42:43]
	v_pk_add_f32 v[20:21], v[20:21], v[40:41]
	v_lshlrev_b32_e32 v46, 16, v75
	v_and_b32_e32 v47, 0xffff0000, v75
	v_add_f32_e32 v29, v29, v30
	v_pk_add_f32 v[30:31], v[16:17], v[44:45]
	v_mul_f32_e32 v16, v21, v21
	v_mul_f32_e32 v17, v23, v23
	v_cvt_pk_bf16_f32 v26, v34, v35
	v_cvt_pk_bf16_f32 v27, v32, v33
	v_add_f32_e32 v32, v28, v29
	v_pk_add_f32 v[28:29], v[18:19], v[46:47]
	v_fmac_f32_e32 v16, v20, v20
	v_fmac_f32_e32 v17, v22, v22
	v_add_f32_e32 v16, v16, v17
	v_mul_f32_e32 v17, v31, v31
	v_mul_f32_e32 v18, v29, v29
	v_fmac_f32_e32 v17, v30, v30
	v_fmac_f32_e32 v18, v28, v28
	v_add_f32_e32 v17, v17, v18
	v_add_f32_e32 v16, v16, v17
	v_add_f32_e32 v19, v32, v16
	ds_bpermute_b32 v34, v112, v19
	v_lshl_add_u64 v[16:17], s[6:7], 0, v[94:95]
	v_lshl_add_u64 v[32:33], v[168:169], 1, v[16:17]
	global_store_dwordx4 v[32:33], v[24:27], off sc1
	v_cvt_pk_bf16_f32 v18, v20, v21
	s_waitcnt lgkmcnt(0)
	v_add_f32_e32 v16, v19, v34
	ds_bpermute_b32 v17, v113, v16
	v_cvt_pk_bf16_f32 v19, v22, v23
	v_cvt_pk_bf16_f32 v20, v30, v31
	v_cvt_pk_bf16_f32 v21, v28, v29
	global_store_dwordx4 v[32:33], v[18:21], off offset:256 sc1
	s_and_saveexec_b64 s[2:3], vcc
	s_cbranch_execz .LBB0_929
	v_lshlrev_b64 v[18:19], 7, v[92:93]
	v_lshl_add_u64 v[18:19], s[16:17], 0, v[18:19]
	v_lshl_add_u64 v[18:19], s[18:19], 2, v[18:19]
	s_lshl_b32 s8, s27, 2
	v_lshl_add_u64 v[18:19], v[18:19], 0, s[8:9]
	s_waitcnt lgkmcnt(0)
	v_add_f32_e32 v16, v16, v17
	global_store_dword v[18:19], v16, off
.LBB0_929:
	s_or_b64 exec, exec, s[2:3]
	s_waitcnt vmcnt(7)
	v_lshlrev_b32_e32 v16, 16, v68
	s_waitcnt lgkmcnt(0)
	v_and_b32_e32 v17, 0xffff0000, v68
	v_lshlrev_b32_e32 v18, 16, v69
	v_and_b32_e32 v19, 0xffff0000, v69
	v_lshlrev_b32_e32 v20, 16, v70
	v_and_b32_e32 v21, 0xffff0000, v70
	v_pk_add_f32 v[12:13], v[12:13], v[16:17]
	v_pk_add_f32 v[14:15], v[14:15], v[18:19]
	v_pk_add_f32 v[18:19], v[8:9], v[20:21]
	v_cvt_pk_bf16_f32 v8, v12, v13
	v_mul_f32_e32 v13, v13, v13
	v_lshlrev_b32_e32 v22, 16, v71
	v_and_b32_e32 v23, 0xffff0000, v71
	v_fmac_f32_e32 v13, v12, v12
	v_mul_f32_e32 v12, v15, v15
	v_pk_add_f32 v[16:17], v[10:11], v[22:23]
	v_fmac_f32_e32 v12, v14, v14
	s_waitcnt vmcnt(6)
	v_lshlrev_b32_e32 v24, 16, v64
	v_and_b32_e32 v25, 0xffff0000, v64
	v_lshlrev_b32_e32 v26, 16, v65
	v_and_b32_e32 v27, 0xffff0000, v65
	v_cvt_pk_bf16_f32 v9, v14, v15
	v_add_f32_e32 v12, v13, v12
	v_mul_f32_e32 v13, v19, v19
	v_mul_f32_e32 v14, v17, v17
	v_lshlrev_b32_e32 v28, 16, v66
	v_and_b32_e32 v29, 0xffff0000, v66
	v_fmac_f32_e32 v13, v18, v18
	v_fmac_f32_e32 v14, v16, v16
	v_pk_add_f32 v[6:7], v[6:7], v[26:27]
	v_pk_add_f32 v[4:5], v[4:5], v[24:25]
	v_lshlrev_b32_e32 v30, 16, v67
	v_and_b32_e32 v31, 0xffff0000, v67
	v_add_f32_e32 v13, v13, v14
	v_pk_add_f32 v[14:15], v[0:1], v[28:29]
	v_mul_f32_e32 v0, v5, v5
	v_mul_f32_e32 v1, v7, v7
	v_cvt_pk_bf16_f32 v10, v18, v19
	v_cvt_pk_bf16_f32 v11, v16, v17
	v_add_f32_e32 v16, v12, v13
	v_pk_add_f32 v[12:13], v[2:3], v[30:31]
	v_fmac_f32_e32 v0, v4, v4
	v_fmac_f32_e32 v1, v6, v6
	v_add_f32_e32 v0, v0, v1
	v_mul_f32_e32 v1, v15, v15
	v_mul_f32_e32 v2, v13, v13
	v_fmac_f32_e32 v1, v14, v14
	v_fmac_f32_e32 v2, v12, v12
	v_add_f32_e32 v1, v1, v2
	v_add_f32_e32 v0, v0, v1
	v_add_f32_e32 v3, v16, v0
	ds_bpermute_b32 v18, v112, v3
	v_lshl_add_u64 v[0:1], s[6:7], 0, v[90:91]
	v_lshl_add_u64 v[16:17], v[168:169], 1, v[0:1]
	global_store_dwordx4 v[16:17], v[8:11], off sc1
	v_cvt_pk_bf16_f32 v2, v4, v5
	s_waitcnt lgkmcnt(0)
	v_add_f32_e32 v0, v3, v18
	ds_bpermute_b32 v1, v113, v0
	v_cvt_pk_bf16_f32 v3, v6, v7
	v_cvt_pk_bf16_f32 v4, v14, v15
	v_cvt_pk_bf16_f32 v5, v12, v13
	global_store_dwordx4 v[16:17], v[2:5], off offset:256 sc1
	s_and_saveexec_b64 s[2:3], vcc
	s_cbranch_execz .LBB0_902
	v_lshlrev_b64 v[2:3], 7, v[88:89]
	v_lshl_add_u64 v[2:3], s[16:17], 0, v[2:3]
	v_lshl_add_u64 v[2:3], s[18:19], 2, v[2:3]
	s_lshl_b32 s8, s27, 2
	v_lshl_add_u64 v[2:3], v[2:3], 0, s[8:9]
	s_waitcnt lgkmcnt(0)
	v_add_f32_e32 v0, v0, v1
	global_store_dword v[2:3], v0, off
	s_branch .LBB0_902

; #define PG8_STAGE(bufoff, gbase, voff) do { _Pragma("unroll") for (int _i = 0; _i < 2; ++_i) \
;         __builtin_amdgcn_global_load_lds((const unsigned*)((const char*)(gbase) + (voff)[_i]), (LAS unsigned*)(lds + (bufoff) + ldsw + _i * 8192), 16, 0, 0); } while (0)
; #define PG8_LDA(dst, b, h) do { _Pragma("unroll") for (int m = 0; m < 4; ++m) _Pragma("unroll") for (int k = 0; k < 2; ++k) dst[m][k] = *(const LAS bf16x8*)(lds + PG8_SA(b, h) + aoff + m * 2048 + k * 1024); } while (0)
; #define PG8_LDB(dst, b, h) do { _Pragma("unroll") for (int n = 0; n < 2; ++n) _Pragma("unroll") for (int k = 0; k < 2; ++k) dst[n][k] = *(const LAS bf16x8*)(lds + PG8_SB(b, h) + boff + n * 2048 + k * 1024); } while (0)
; #define PG8_MMA(ai, bj, At, Bt) do { __builtin_amdgcn_s_setprio(1); _Pragma("unroll") for (int m = 0; m < 4; ++m) _Pragma("unroll") for (int n = 0; n < 2; ++n) _Pragma("unroll") for (int k = 0; k < 2; ++k) \
;         acc[ai][bj][m][n] = __builtin_amdgcn_mfma_f32_16x16x32_bf16(Bt[n][k], At[m][k], acc[ai][bj][m][n], 0, 0, 0); __builtin_amdgcn_s_setprio(0); } while (0)
; #define PG8_WAIT_V(n) asm volatile("s_waitcnt vmcnt(" #n ")" ::: "memory")
; #define PG8_WAIT_L(n) asm volatile("s_waitcnt lgkmcnt(" #n ")" ::: "memory")
; #define PG8_BAR __builtin_amdgcn_s_barrier()
; #define PG8_SCHED __builtin_amdgcn_sched_barrier(0)
; template <class Epi, bool KS0 = false>
; __device__ __forceinline__ void gemm_phase(const int WID, LAS unsigned char* lds, const Gemm g, const StaticOrder& S, const Epi& E) {
;     ...
;             PG8_LDB(B0, 0, 0); PG8_SCHED; PG8_LDA(At, 0, 0); PG8_STAGE(PG8_SA(1, 1), a1 + hstep, voffA);
;             PG8_WAIT_L(8); PG8_BAR; PG8_WAIT_L(0); PG8_MMA(0, 0, At, B0); PG8_BAR; PG8_SCHED;
;             PG8_LDB(B1, 0, 1); PG8_STAGE(PG8_SB(0, 0), b2, voffB);
;             PG8_BAR; PG8_WAIT_L(0); PG8_MMA(0, 1, At, B1); PG8_BAR;
;             PG8_LDA(At, 0, 1); PG8_STAGE(PG8_SA(0, 0), a2, voffA);
;             PG8_BAR; PG8_WAIT_L(0); PG8_MMA(1, 0, At, B0); PG8_BAR; PG8_SCHED;
;             PG8_STAGE(PG8_SB(0, 1), b2 + hstep, voffB);
;             PG8_WAIT_V(6); PG8_BAR; PG8_MMA(1, 1, At, B1); PG8_BAR;
.LBB0_1006:
	ds_read_b128 v[104:107], v246
	ds_read_b128 v[108:111], v246 offset:1024
	ds_read_b128 v[112:115], v246 offset:2048
	ds_read_b128 v[120:123], v246 offset:3072
	s_add_u32 s10, s8, 0xfff80080
	s_addc_u32 s11, s9, -1
	s_cmp_eq_u32 s43, 28
	s_cselect_b32 s13, s3, s11
	s_cselect_b32 s12, s14, s10
	s_cselect_b32 s11, s15, s41
	s_cselect_b32 s10, s36, s37
	v_lshl_add_u64 v[176:177], s[8:9], 0, v[200:201]
	s_add_i32 m0, s18, 0xc000
	ds_read_b128 v[136:139], v247
	ds_read_b128 v[144:147], v247 offset:1024
	ds_read_b128 v[148:151], v247 offset:2048
	ds_read_b128 v[156:159], v247 offset:3072
	ds_read_b128 v[160:163], v247 offset:4096
	ds_read_b128 v[164:167], v247 offset:5120
	ds_read_b128 v[168:171], v247 offset:6144
	ds_read_b128 v[172:175], v247 offset:7168
	global_load_lds_dwordx4 v[176:177], off
	v_lshl_add_u64 v[176:177], s[8:9], 0, v[202:203]
	s_add_i32 m0, s18, 0xe000
	s_nop 0
	global_load_lds_dwordx4 v[176:177], off
	s_waitcnt lgkmcnt(8)
	s_barrier
	s_waitcnt lgkmcnt(0)
	s_setprio 1
	s_waitcnt lgkmcnt(0)
	v_mfma_f32_16x16x32_bf16 v[152:155], v[104:107], v[136:139], v[152:155]
	v_mfma_f32_16x16x32_bf16 v[140:143], v[112:115], v[136:139], v[140:143]
	v_mfma_f32_16x16x32_bf16 v[124:127], v[104:107], v[148:151], v[124:127]
	v_mfma_f32_16x16x32_bf16 v[116:119], v[112:115], v[148:151], v[116:119]
	v_mfma_f32_16x16x32_bf16 v[92:95], v[104:107], v[160:163], v[92:95]
	v_mfma_f32_16x16x32_bf16 v[88:91], v[112:115], v[160:163], v[88:91]
	v_mfma_f32_16x16x32_bf16 v[76:79], v[104:107], v[168:171], v[76:79]
	v_mfma_f32_16x16x32_bf16 v[72:75], v[112:115], v[168:171], v[72:75]
	v_mfma_f32_16x16x32_bf16 v[152:155], v[108:111], v[144:147], v[152:155]
	v_mfma_f32_16x16x32_bf16 v[140:143], v[120:123], v[144:147], v[140:143]
	v_mfma_f32_16x16x32_bf16 v[124:127], v[108:111], v[156:159], v[124:127]
	v_mfma_f32_16x16x32_bf16 v[116:119], v[120:123], v[156:159], v[116:119]
	v_mfma_f32_16x16x32_bf16 v[92:95], v[108:111], v[164:167], v[92:95]
	v_mfma_f32_16x16x32_bf16 v[88:91], v[120:123], v[164:167], v[88:91]
	v_mfma_f32_16x16x32_bf16 v[76:79], v[108:111], v[172:175], v[76:79]
	v_mfma_f32_16x16x32_bf16 v[72:75], v[120:123], v[172:175], v[72:75]
	s_setprio 0
	s_barrier
	s_add_i32 s48, s50, s26
	v_lshl_add_u64 v[210:211], s[10:11], 0, v[194:195]
	s_mov_b32 m0, s48
	ds_read_b128 v[176:179], v248
	ds_read_b128 v[180:183], v248 offset:1024
	ds_read_b128 v[184:187], v248 offset:2048
	ds_read_b128 v[188:191], v248 offset:3072
	global_load_lds_dwordx4 v[210:211], off
	v_lshl_add_u64 v[212:213], s[10:11], 0, v[198:199]
	s_add_i32 m0, s48, 0x2000
	s_nop 0
	global_load_lds_dwordx4 v[212:213], off
	s_barrier
	s_waitcnt lgkmcnt(0)
	s_setprio 1
	s_waitcnt lgkmcnt(0)
	v_mfma_f32_16x16x32_bf16 v[132:135], v[176:179], v[136:139], v[132:135]
	v_mfma_f32_16x16x32_bf16 v[128:131], v[184:187], v[136:139], v[128:131]
	v_mfma_f32_16x16x32_bf16 v[100:103], v[176:179], v[148:151], v[100:103]
	v_mfma_f32_16x16x32_bf16 v[96:99], v[184:187], v[148:151], v[96:99]
	v_mfma_f32_16x16x32_bf16 v[84:87], v[176:179], v[160:163], v[84:87]
	v_mfma_f32_16x16x32_bf16 v[80:83], v[184:187], v[160:163], v[80:83]
	v_mfma_f32_16x16x32_bf16 v[68:71], v[176:179], v[168:171], v[68:71]
	v_mfma_f32_16x16x32_bf16 v[64:67], v[184:187], v[168:171], v[64:67]
	v_mfma_f32_16x16x32_bf16 v[132:135], v[180:183], v[144:147], v[132:135]
	v_mfma_f32_16x16x32_bf16 v[128:131], v[188:191], v[144:147], v[128:131]
	v_mfma_f32_16x16x32_bf16 v[100:103], v[180:183], v[156:159], v[100:103]
	v_mfma_f32_16x16x32_bf16 v[96:99], v[188:191], v[156:159], v[96:99]
	v_mfma_f32_16x16x32_bf16 v[84:87], v[180:183], v[164:167], v[84:87]
	v_mfma_f32_16x16x32_bf16 v[80:83], v[188:191], v[164:167], v[80:83]
	v_mfma_f32_16x16x32_bf16 v[68:71], v[180:183], v[172:175], v[68:71]
	v_mfma_f32_16x16x32_bf16 v[64:67], v[188:191], v[172:175], v[64:67]
	s_setprio 0
	s_mov_b32 m0, s18
	v_lshl_add_u64 v[214:215], s[12:13], 0, v[192:193]
	s_barrier
	ds_read_b128 v[136:139], v247 offset:16384
	ds_read_b128 v[144:147], v247 offset:17408
	ds_read_b128 v[148:151], v247 offset:18432
	ds_read_b128 v[156:159], v247 offset:19456
	ds_read_b128 v[160:163], v247 offset:20480
	ds_read_b128 v[164:167], v247 offset:21504
	ds_read_b128 v[168:171], v247 offset:22528
	ds_read_b128 v[172:175], v247 offset:23552
	global_load_lds_dwordx4 v[214:215], off
	v_lshl_add_u64 v[216:217], s[12:13], 0, v[196:197]
	s_mov_b32 m0, s19
	s_nop 0
	global_load_lds_dwordx4 v[216:217], off
	s_barrier
	s_waitcnt lgkmcnt(0)
	s_setprio 1
	s_waitcnt lgkmcnt(0)
	v_mfma_f32_16x16x32_bf16 v[60:63], v[104:107], v[136:139], v[60:63]
	v_mfma_f32_16x16x32_bf16 v[56:59], v[112:115], v[136:139], v[56:59]
	v_mfma_f32_16x16x32_bf16 v[44:47], v[104:107], v[148:151], v[44:47]
	v_mfma_f32_16x16x32_bf16 v[40:43], v[112:115], v[148:151], v[40:43]
	v_mfma_f32_16x16x32_bf16 v[28:31], v[104:107], v[160:163], v[28:31]
	v_mfma_f32_16x16x32_bf16 v[24:27], v[112:115], v[160:163], v[24:27]
	v_mfma_f32_16x16x32_bf16 v[12:15], v[104:107], v[168:171], v[12:15]
	v_mfma_f32_16x16x32_bf16 v[8:11], v[112:115], v[168:171], v[8:11]
	v_mfma_f32_16x16x32_bf16 v[60:63], v[108:111], v[144:147], v[60:63]
	v_mfma_f32_16x16x32_bf16 v[56:59], v[120:123], v[144:147], v[56:59]
	v_mfma_f32_16x16x32_bf16 v[44:47], v[108:111], v[156:159], v[44:47]
	v_mfma_f32_16x16x32_bf16 v[40:43], v[120:123], v[156:159], v[40:43]
	v_mfma_f32_16x16x32_bf16 v[28:31], v[108:111], v[164:167], v[28:31]
	v_mfma_f32_16x16x32_bf16 v[24:27], v[120:123], v[164:167], v[24:27]
	v_mfma_f32_16x16x32_bf16 v[12:15], v[108:111], v[172:175], v[12:15]
	v_mfma_f32_16x16x32_bf16 v[8:11], v[120:123], v[172:175], v[8:11]
	s_setprio 0
	s_barrier
; #define PG8_STAGE(bufoff, gbase, voff) do { _Pragma("unroll") for (int _i = 0; _i < 2; ++_i) \
;         __builtin_amdgcn_global_load_lds((const unsigned*)((const char*)(gbase) + (voff)[_i]), (LAS unsigned*)(lds + (bufoff) + ldsw + _i * 8192), 16, 0, 0); } while (0)
; #define PG8_LDA(dst, b, h) do { _Pragma("unroll") for (int m = 0; m < 4; ++m) _Pragma("unroll") for (int k = 0; k < 2; ++k) dst[m][k] = *(const LAS bf16x8*)(lds + PG8_SA(b, h) + aoff + m * 2048 + k * 1024); } while (0)
; #define PG8_LDB(dst, b, h) do { _Pragma("unroll") for (int n = 0; n < 2; ++n) _Pragma("unroll") for (int k = 0; k < 2; ++k) dst[n][k] = *(const LAS bf16x8*)(lds + PG8_SB(b, h) + boff + n * 2048 + k * 1024); } while (0)
; #define PG8_MMA(ai, bj, At, Bt) do { __builtin_amdgcn_s_setprio(1); _Pragma("unroll") for (int m = 0; m < 4; ++m) _Pragma("unroll") for (int n = 0; n < 2; ++n) _Pragma("unroll") for (int k = 0; k < 2; ++k) \
;         acc[ai][bj][m][n] = __builtin_amdgcn_mfma_f32_16x16x32_bf16(Bt[n][k], At[m][k], acc[ai][bj][m][n], 0, 0, 0); __builtin_amdgcn_s_setprio(0); } while (0)
; #define PG8_WAIT_V(n) asm volatile("s_waitcnt vmcnt(" #n ")" ::: "memory")
; #define PG8_WAIT_L(n) asm volatile("s_waitcnt lgkmcnt(" #n ")" ::: "memory")
; #define PG8_BAR __builtin_amdgcn_s_barrier()
; #define PG8_SCHED __builtin_amdgcn_sched_barrier(0)
; template <class Epi, bool KS0 = false>
; __device__ __forceinline__ void gemm_phase(const int WID, LAS unsigned char* lds, const Gemm g, const StaticOrder& S, const Epi& E) {
;     ...
;             PG8_STAGE(PG8_SB(0, 1), b2 + hstep, voffB);
;             PG8_WAIT_V(6); PG8_BAR; PG8_MMA(1, 1, At, B1); PG8_BAR;
;             PG8_LDB(B0, 1, 0); PG8_SCHED; PG8_LDA(At, 1, 0); PG8_STAGE(PG8_SA(0, 1), a2 + hstep, voffA);
;             PG8_WAIT_L(8); PG8_BAR; PG8_WAIT_L(0); PG8_MMA(0, 0, At, B0); PG8_BAR; PG8_SCHED;
;             PG8_LDB(B1, 1, 1); PG8_STAGE(PG8_SB(1, 0), b3, voffB);
;             PG8_BAR; PG8_WAIT_L(0); PG8_MMA(0, 1, At, B1); PG8_BAR;
;             PG8_LDA(At, 1, 1); PG8_STAGE(PG8_SA(1, 0), a3, voffA);
;             PG8_BAR; PG8_WAIT_L(0); PG8_MMA(1, 0, At, B0); PG8_BAR; PG8_SCHED;
	s_add_u32 s48, s10, 0x80000
	s_addc_u32 s49, s11, 0
	s_add_i32 s54, s51, s26
	v_lshl_add_u64 v[104:105], s[48:49], 0, v[194:195]
	s_mov_b32 m0, s54
	s_nop 0
	global_load_lds_dwordx4 v[104:105], off
	v_lshl_add_u64 v[104:105], s[48:49], 0, v[198:199]
	s_add_i32 m0, s54, 0x2000
	s_nop 0
	global_load_lds_dwordx4 v[104:105], off
	s_waitcnt vmcnt(6)
	s_barrier
	s_setprio 1
	v_mfma_f32_16x16x32_bf16 v[52:55], v[176:179], v[136:139], v[52:55]
	v_mfma_f32_16x16x32_bf16 v[48:51], v[184:187], v[136:139], v[48:51]
	v_mfma_f32_16x16x32_bf16 v[36:39], v[176:179], v[148:151], v[36:39]
	v_mfma_f32_16x16x32_bf16 v[32:35], v[184:187], v[148:151], v[32:35]
	v_mfma_f32_16x16x32_bf16 v[20:23], v[176:179], v[160:163], v[20:23]
	v_mfma_f32_16x16x32_bf16 v[16:19], v[184:187], v[160:163], v[16:19]
	v_mfma_f32_16x16x32_bf16 v[4:7], v[176:179], v[168:171], v[4:7]
	v_mfma_f32_16x16x32_bf16 v[0:3], v[184:187], v[168:171], v[0:3]
	v_mfma_f32_16x16x32_bf16 v[52:55], v[180:183], v[144:147], v[52:55]
	v_mfma_f32_16x16x32_bf16 v[48:51], v[188:191], v[144:147], v[48:51]
	v_mfma_f32_16x16x32_bf16 v[36:39], v[180:183], v[156:159], v[36:39]
	v_mfma_f32_16x16x32_bf16 v[32:35], v[188:191], v[156:159], v[32:35]
	v_mfma_f32_16x16x32_bf16 v[20:23], v[180:183], v[164:167], v[20:23]
	v_mfma_f32_16x16x32_bf16 v[16:19], v[188:191], v[164:167], v[16:19]
	v_mfma_f32_16x16x32_bf16 v[4:7], v[180:183], v[172:175], v[4:7]
	v_mfma_f32_16x16x32_bf16 v[0:3], v[188:191], v[172:175], v[0:3]
	s_setprio 0
	s_add_i32 s48, 0, 0x18000
	v_add_u32_e32 v120, s48, v245
	s_barrier
	ds_read_b128 v[104:107], v120
	ds_read_b128 v[108:111], v120 offset:1024
	ds_read_b128 v[112:115], v120 offset:2048
	ds_read_b128 v[120:123], v120 offset:3072
	s_add_u32 s12, s12, 0x80000
	s_addc_u32 s13, s13, 0
	s_mov_b32 m0, s20
	v_lshl_add_u64 v[176:177], s[12:13], 0, v[192:193]
	ds_read_b128 v[136:139], v247 offset:32768
	ds_read_b128 v[144:147], v247 offset:33792
	ds_read_b128 v[148:151], v247 offset:34816
	ds_read_b128 v[156:159], v247 offset:35840
	ds_read_b128 v[160:163], v247 offset:36864
	ds_read_b128 v[164:167], v247 offset:37888
	ds_read_b128 v[168:171], v247 offset:38912
	ds_read_b128 v[172:175], v247 offset:39936
	global_load_lds_dwordx4 v[176:177], off
	v_lshl_add_u64 v[176:177], s[12:13], 0, v[196:197]
	s_mov_b32 m0, s21
	s_nop 0
	global_load_lds_dwordx4 v[176:177], off
	s_waitcnt lgkmcnt(8)
	s_barrier
	s_waitcnt lgkmcnt(0)
	s_setprio 1
	s_waitcnt lgkmcnt(0)
	v_mfma_f32_16x16x32_bf16 v[152:155], v[104:107], v[136:139], v[152:155]
	v_mfma_f32_16x16x32_bf16 v[140:143], v[112:115], v[136:139], v[140:143]
	v_mfma_f32_16x16x32_bf16 v[124:127], v[104:107], v[148:151], v[124:127]
	v_mfma_f32_16x16x32_bf16 v[116:119], v[112:115], v[148:151], v[116:119]
	v_mfma_f32_16x16x32_bf16 v[92:95], v[104:107], v[160:163], v[92:95]
	v_mfma_f32_16x16x32_bf16 v[88:91], v[112:115], v[160:163], v[88:91]
	v_mfma_f32_16x16x32_bf16 v[76:79], v[104:107], v[168:171], v[76:79]
	v_mfma_f32_16x16x32_bf16 v[72:75], v[112:115], v[168:171], v[72:75]
	v_mfma_f32_16x16x32_bf16 v[152:155], v[108:111], v[144:147], v[152:155]
	v_mfma_f32_16x16x32_bf16 v[140:143], v[120:123], v[144:147], v[140:143]
	v_mfma_f32_16x16x32_bf16 v[124:127], v[108:111], v[156:159], v[124:127]
	v_mfma_f32_16x16x32_bf16 v[116:119], v[120:123], v[156:159], v[116:119]
	v_mfma_f32_16x16x32_bf16 v[92:95], v[108:111], v[164:167], v[92:95]
	v_mfma_f32_16x16x32_bf16 v[88:91], v[120:123], v[164:167], v[88:91]
	v_mfma_f32_16x16x32_bf16 v[76:79], v[108:111], v[172:175], v[76:79]
	v_mfma_f32_16x16x32_bf16 v[72:75], v[120:123], v[172:175], v[72:75]
	s_setprio 0
	s_barrier
	s_add_i32 s12, 0, 0x1c000
	s_add_i32 s13, s48, s26
	v_add_u32_e32 v188, s12, v245
	v_lshl_add_u64 v[210:211], v[210:211], 0, s[30:31]
	s_mov_b32 m0, s13
	ds_read_b128 v[176:179], v188
	ds_read_b128 v[180:183], v188 offset:1024
	ds_read_b128 v[184:187], v188 offset:2048
	ds_read_b128 v[188:191], v188 offset:3072
	global_load_lds_dwordx4 v[210:211], off
	v_lshl_add_u64 v[210:211], v[212:213], 0, s[30:31]
	s_add_i32 m0, s13, 0x2000
	s_nop 0
	global_load_lds_dwordx4 v[210:211], off
	s_barrier
	s_waitcnt lgkmcnt(0)
	s_setprio 1
	s_waitcnt lgkmcnt(0)
	v_mfma_f32_16x16x32_bf16 v[132:135], v[176:179], v[136:139], v[132:135]
	v_mfma_f32_16x16x32_bf16 v[128:131], v[184:187], v[136:139], v[128:131]
	v_mfma_f32_16x16x32_bf16 v[100:103], v[176:179], v[148:151], v[100:103]
	v_mfma_f32_16x16x32_bf16 v[96:99], v[184:187], v[148:151], v[96:99]
	v_mfma_f32_16x16x32_bf16 v[84:87], v[176:179], v[160:163], v[84:87]
	v_mfma_f32_16x16x32_bf16 v[80:83], v[184:187], v[160:163], v[80:83]
	v_mfma_f32_16x16x32_bf16 v[68:71], v[176:179], v[168:171], v[68:71]
	v_mfma_f32_16x16x32_bf16 v[64:67], v[184:187], v[168:171], v[64:67]
	v_mfma_f32_16x16x32_bf16 v[132:135], v[180:183], v[144:147], v[132:135]
	v_mfma_f32_16x16x32_bf16 v[128:131], v[188:191], v[144:147], v[128:131]
	v_mfma_f32_16x16x32_bf16 v[100:103], v[180:183], v[156:159], v[100:103]
	v_mfma_f32_16x16x32_bf16 v[96:99], v[188:191], v[156:159], v[96:99]
	v_mfma_f32_16x16x32_bf16 v[84:87], v[180:183], v[164:167], v[84:87]
	v_mfma_f32_16x16x32_bf16 v[80:83], v[188:191], v[164:167], v[80:83]
	v_mfma_f32_16x16x32_bf16 v[68:71], v[180:183], v[172:175], v[68:71]
	v_mfma_f32_16x16x32_bf16 v[64:67], v[188:191], v[172:175], v[64:67]
	s_setprio 0
	s_mov_b32 m0, s25
	v_lshl_add_u64 v[210:211], v[214:215], 0, s[30:31]
	s_barrier
	ds_read_b128 v[136:139], v247 offset:49152
	ds_read_b128 v[144:147], v247 offset:50176
	ds_read_b128 v[148:151], v247 offset:51200
	ds_read_b128 v[156:159], v247 offset:52224
	ds_read_b128 v[160:163], v247 offset:53248
	ds_read_b128 v[164:167], v247 offset:54272
	ds_read_b128 v[168:171], v247 offset:55296
	ds_read_b128 v[172:175], v247 offset:56320
	global_load_lds_dwordx4 v[210:211], off
	v_lshl_add_u64 v[210:211], v[216:217], 0, s[30:31]
	s_mov_b32 m0, s39
	s_nop 0
	global_load_lds_dwordx4 v[210:211], off
	s_barrier
; #define PG8_STAGE(bufoff, gbase, voff) do { _Pragma("unroll") for (int _i = 0; _i < 2; ++_i) \
;         __builtin_amdgcn_global_load_lds((const unsigned*)((const char*)(gbase) + (voff)[_i]), (LAS unsigned*)(lds + (bufoff) + ldsw + _i * 8192), 16, 0, 0); } while (0)
; #define PG8_MMA(ai, bj, At, Bt) do { __builtin_amdgcn_s_setprio(1); _Pragma("unroll") for (int m = 0; m < 4; ++m) _Pragma("unroll") for (int n = 0; n < 2; ++n) _Pragma("unroll") for (int k = 0; k < 2; ++k) \
;         acc[ai][bj][m][n] = __builtin_amdgcn_mfma_f32_16x16x32_bf16(Bt[n][k], At[m][k], acc[ai][bj][m][n], 0, 0, 0); __builtin_amdgcn_s_setprio(0); } while (0)
; #define PG8_WAIT_V(n) asm volatile("s_waitcnt vmcnt(" #n ")" ::: "memory")
; #define PG8_WAIT_L(n) asm volatile("s_waitcnt lgkmcnt(" #n ")" ::: "memory")
; #define PG8_BAR __builtin_amdgcn_s_barrier()
; #define PG8_SCHED __builtin_amdgcn_sched_barrier(0)
; template <class Epi, bool KS0 = false>
; __device__ __forceinline__ void gemm_phase(const int WID, LAS unsigned char* lds, const Gemm g, const StaticOrder& S, const Epi& E) {
;     ...
;             PG8_BAR; PG8_WAIT_L(0); PG8_MMA(1, 0, At, B0); PG8_BAR; PG8_SCHED;
;             PG8_STAGE(PG8_SB(1, 1), b3 + hstep, voffB);
;             PG8_WAIT_V(6); PG8_BAR; PG8_MMA(1, 1, At, B1); PG8_BAR;
;     __device__ __forceinline__ void operator()(f32x4 (&acc)[2][2][4][2], const Unit& u, int wr, int wc, int fr, int fq) const {
;         const int row0 = u.pm * BM + wr * 64 + fr, col0 = u.pn * BM + wc * 32 + 8 * fq;
;         const bf16_t* ppf = pp + ((size_t)(u.pm * (DM / 256) + u.pn) << 16) + (size_t)((((wr * 4 + wc) * 16) * 64 + fq * 16 + fr) << 3);
; #pragma unroll
;         for (int ai = 0; ai < 2; ++ai) {
;             u32x4 hw[4][2], pw[4][2]; float rstd[4];
; #pragma unroll
;             for (int m = 0; m < 4; ++m) { const int row = row0 + ai * HALF + m * 16;
; #pragma unroll
;                 for (int bj = 0; bj < 2; ++bj) { const size_t o = (size_t)row * DM + col0 + bj * HALF; hw[m][bj] = *(const u32x4*)(hb + o); pw[m][bj] = *(const u32x4*)(ppf + (((ai * 4 + m) * 2 + bj) << 9)); }
;                 rstd[m] = row_rstd(ssq_in, row, fq); }
	s_waitcnt lgkmcnt(0)
	s_setprio 1
	s_waitcnt lgkmcnt(0)
	v_mfma_f32_16x16x32_bf16 v[60:63], v[104:107], v[136:139], v[60:63]
	v_mfma_f32_16x16x32_bf16 v[56:59], v[112:115], v[136:139], v[56:59]
	v_mfma_f32_16x16x32_bf16 v[44:47], v[104:107], v[148:151], v[44:47]
	v_mfma_f32_16x16x32_bf16 v[40:43], v[112:115], v[148:151], v[40:43]
	v_mfma_f32_16x16x32_bf16 v[28:31], v[104:107], v[160:163], v[28:31]
	v_mfma_f32_16x16x32_bf16 v[24:27], v[112:115], v[160:163], v[24:27]
	v_mfma_f32_16x16x32_bf16 v[12:15], v[104:107], v[168:171], v[12:15]
	v_mfma_f32_16x16x32_bf16 v[8:11], v[112:115], v[168:171], v[8:11]
	v_mfma_f32_16x16x32_bf16 v[60:63], v[108:111], v[144:147], v[60:63]
	v_mfma_f32_16x16x32_bf16 v[56:59], v[120:123], v[144:147], v[56:59]
	v_mfma_f32_16x16x32_bf16 v[44:47], v[108:111], v[156:159], v[44:47]
	v_mfma_f32_16x16x32_bf16 v[40:43], v[120:123], v[156:159], v[40:43]
	v_mfma_f32_16x16x32_bf16 v[28:31], v[108:111], v[164:167], v[28:31]
	v_mfma_f32_16x16x32_bf16 v[24:27], v[120:123], v[164:167], v[24:27]
	v_mfma_f32_16x16x32_bf16 v[12:15], v[108:111], v[172:175], v[12:15]
	v_mfma_f32_16x16x32_bf16 v[8:11], v[120:123], v[172:175], v[8:11]
	s_setprio 0
	s_barrier
	s_add_u32 s10, s10, 0x80080
	s_addc_u32 s11, s11, 0
	s_add_i32 s12, s12, s26
	v_lshl_add_u64 v[104:105], s[10:11], 0, v[194:195]
	s_mov_b32 m0, s12
	s_nop 0
	global_load_lds_dwordx4 v[104:105], off
	v_lshl_add_u64 v[104:105], s[10:11], 0, v[198:199]
	s_add_i32 m0, s12, 0x2000
	s_nop 0
	global_load_lds_dwordx4 v[104:105], off
	s_waitcnt vmcnt(6)
	s_barrier
	s_setprio 1
	v_mfma_f32_16x16x32_bf16 v[52:55], v[176:179], v[136:139], v[52:55]
	v_mfma_f32_16x16x32_bf16 v[48:51], v[184:187], v[136:139], v[48:51]
	v_mfma_f32_16x16x32_bf16 v[36:39], v[176:179], v[148:151], v[36:39]
	v_mfma_f32_16x16x32_bf16 v[32:35], v[184:187], v[148:151], v[32:35]
	v_mfma_f32_16x16x32_bf16 v[20:23], v[176:179], v[160:163], v[20:23]
	v_mfma_f32_16x16x32_bf16 v[16:19], v[184:187], v[160:163], v[16:19]
	v_mfma_f32_16x16x32_bf16 v[4:7], v[176:179], v[168:171], v[4:7]
	v_mfma_f32_16x16x32_bf16 v[0:3], v[184:187], v[168:171], v[0:3]
	v_mfma_f32_16x16x32_bf16 v[52:55], v[180:183], v[144:147], v[52:55]
	v_mfma_f32_16x16x32_bf16 v[48:51], v[188:191], v[144:147], v[48:51]
	v_mfma_f32_16x16x32_bf16 v[36:39], v[180:183], v[156:159], v[36:39]
	v_mfma_f32_16x16x32_bf16 v[32:35], v[188:191], v[156:159], v[32:35]
	v_mfma_f32_16x16x32_bf16 v[20:23], v[180:183], v[164:167], v[20:23]
	v_mfma_f32_16x16x32_bf16 v[16:19], v[188:191], v[164:167], v[16:19]
	v_mfma_f32_16x16x32_bf16 v[4:7], v[180:183], v[172:175], v[4:7]
	v_mfma_f32_16x16x32_bf16 v[0:3], v[188:191], v[172:175], v[0:3]
	s_setprio 0
	s_add_i32 s43, s43, 2
	s_add_u32 s8, s8, 0x100
	s_addc_u32 s9, s9, 0
	s_add_u32 s37, s37, 0x100
	s_addc_u32 s41, s41, 0
	s_cmp_gt_u32 s43, 29
	s_barrier
	s_cbranch_scc0 .LBB0_1006
	s_lshl_b32 s3, s4, 8
	v_mbcnt_lo_u32_b32 v104, -1, 0
	v_mbcnt_hi_u32_b32 v104, -1, v104
	s_add_i32 s3, s3, s22
	v_ashrrev_i32_e32 v108, 4, v104
	v_and_b32_e32 v109, 15, v104
	v_readlane_b32 s8, v254, 19
	v_add_u32_e32 v212, s3, v109
	v_lshlrev_b32_e32 v104, 3, v108
	v_ashrrev_i32_e32 v105, 31, v104
	v_ashrrev_i32_e32 v213, 31, v212
	v_add_u32_e32 v160, 16, v212
	v_lshl_add_u64 v[214:215], v[104:105], 2, s[16:17]
	v_lshlrev_b64 v[236:237], 7, v[212:213]
	v_ashrrev_i32_e32 v161, 31, v160
	v_lshl_add_u64 v[106:107], v[214:215], 0, v[236:237]
	v_lshlrev_b64 v[228:229], 7, v[160:161]
	global_load_dwordx4 v[136:139], v[106:107], off
	global_load_dwordx4 v[144:147], v[106:107], off offset:16
	v_lshl_add_u64 v[106:107], v[214:215], 0, v[228:229]
	global_load_dwordx4 v[148:151], v[106:107], off
	global_load_dwordx4 v[156:159], v[106:107], off offset:16
	v_and_b32_e32 v106, 64, v209
	v_xor_b32_e32 v105, 16, v209
	v_add_u32_e32 v106, 64, v106
	v_add_u32_e32 v162, 32, v212
	v_xor_b32_e32 v107, 32, v209
	v_cmp_lt_i32_e32 vcc, v105, v106
	v_ashrrev_i32_e32 v163, 31, v162
	v_lshlrev_b64 v[222:223], 7, v[162:163]
	v_cndmask_b32_e32 v105, v209, v105, vcc
	v_cmp_lt_i32_e32 vcc, v107, v106
	v_add_u32_e32 v226, 48, v212
	s_lshl_b32 s3, s2, 8
	v_cndmask_b32_e32 v110, v209, v107, vcc
	v_lshl_add_u64 v[106:107], v[214:215], 0, v[222:223]
	v_ashrrev_i32_e32 v227, 31, v226
	s_or_b32 s3, s3, s8
	global_load_dwordx4 v[112:115], v[106:107], off
	global_load_dwordx4 v[120:123], v[106:107], off offset:16
	v_lshlrev_b64 v[220:221], 7, v[226:227]
	v_lshlrev_b32_e32 v250, 2, v105
	v_add_u32_e32 v210, s3, v104
	v_lshl_add_u64 v[104:105], v[214:215], 0, v[220:221]
	v_add_u32_e32 v164, s55, v109
	v_lshlrev_b32_e32 v165, 7, v108
	v_lshlrev_b32_e32 v249, 2, v110
	v_cmp_eq_u32_e64 s[36:37], 0, v108
	global_load_dwordx4 v[108:111], v[104:105], off
	s_nop 0
	global_load_dwordx4 v[104:107], v[104:105], off offset:16
	s_lshl_b32 s4, s4, 3
	s_add_i32 s8, s4, s2
	s_ashr_i32 s9, s8, 31
	s_lshl_b64 s[8:9], s[8:9], 17
	v_ashrrev_i32_e32 v211, 31, v210
	s_add_u32 s8, s23, s8
	v_lshl_add_u32 v164, v164, 3, v165
	v_lshlrev_b64 v[240:241], 1, v[210:211]
	s_addc_u32 s9, s24, s9
	v_ashrrev_i32_e32 v165, 31, v164
	v_lshlrev_b64 v[238:239], 12, v[212:213]
	v_lshl_add_u64 v[216:217], s[6:7], 0, v[240:241]
	v_lshl_add_u64 v[218:219], v[164:165], 1, s[8:9]
	v_lshl_add_u64 v[164:165], v[216:217], 0, v[238:239]
	global_load_dwordx4 v[184:187], v[218:219], off
	global_load_dwordx4 v[188:191], v[164:165], off
	global_load_dwordx4 v[176:179], v[218:219], off offset:1024
	s_lshl_b32 s48, s2, 2
	v_lshlrev_b64 v[234:235], 12, v[160:161]
	v_lshlrev_b64 v[224:225], 12, v[162:163]
	v_lshlrev_b64 v[226:227], 12, v[226:227]
	s_ashr_i32 s49, s48, 31
	s_waitcnt vmcnt(0)
; __device__ __forceinline__ float bflo(unsigned w) { return __uint_as_float(w << 16); }
; __device__ __forceinline__ float bfhi(unsigned w) { return __uint_as_float(w & 0xffff0000u); }
; __device__ __forceinline__ float sigmoidf_(float x) { return __builtin_amdgcn_rcpf(1.0f + __expf(-x)); }
; __device__ __forceinline__ float row_rstd(const float* ssq, int row, int fq) {
;     const f32x4 a = *(const f32x4*)(ssq + (size_t)row * 32 + 8 * fq), b = *(const f32x4*)(ssq + (size_t)row * 32 + 8 * fq + 4);
;     float t = ((a[0] + a[1]) + (a[2] + a[3])) + ((b[0] + b[1]) + (b[2] + b[3]));
;     t += __shfl_xor(t, 16); t += __shfl_xor(t, 32);
;     return rsqrtf(t * (1.0f / 2048.0f) + EPS);
;     __device__ __forceinline__ void operator()(f32x4 (&acc)[2][2][4][2], const Unit& u, int wr, int wc, int fr, int fq) const {
;     ...
;             for (int m = 0; m < 4; ++m) { const int row = row0 + ai * HALF + m * 16;
; #pragma unroll
;                 for (int bj = 0; bj < 2; ++bj) { const size_t o = (size_t)row * DM + col0 + bj * HALF; hw[m][bj] = *(const u32x4*)(hb + o); pw[m][bj] = *(const u32x4*)(ppf + (((ai * 4 + m) * 2 + bj) << 9)); }
;                 rstd[m] = row_rstd(ssq_in, row, fq); }
; #pragma unroll
;             for (int m = 0; m < 4; ++m) { const int row = row0 + ai * HALF + m * 16; const size_t off = (size_t)row * DM + col0; float s = 0.f;
; #pragma unroll
;                 for (int bj = 0; bj < 2; ++bj) { const f32x4 z0 = acc[ai][bj][m][0] * rstd[m], z1 = acc[ai][bj][m][1] * rstd[m]; const u32x4 h2 = hw[m][bj], p2 = pw[m][bj]; f32x4 v0, v1;
;                     v0[0] = bflo(h2.x) + sigmoidf_(z0[0]) * bflo(p2.x); v0[1] = bfhi(h2.x) + sigmoidf_(z0[1]) * bfhi(p2.x);
;                     v0[2] = bflo(h2.y) + sigmoidf_(z0[2]) * bflo(p2.y); v0[3] = bfhi(h2.y) + sigmoidf_(z0[3]) * bfhi(p2.y);
;                     v1[0] = bflo(h2.z) + sigmoidf_(z1[0]) * bflo(p2.z); v1[1] = bfhi(h2.z) + sigmoidf_(z1[1]) * bfhi(p2.z);
;                     v1[2] = bflo(h2.w) + sigmoidf_(z1[2]) * bflo(p2.w); v1[3] = bfhi(h2.w) + sigmoidf_(z1[3]) * bfhi(p2.w);
	v_mov_b32_e32 v166, v136
	v_mov_b32_e32 v167, v144
	v_mov_b32_e32 v144, v137
	v_mov_b32_e32 v136, v138
	v_mov_b32_e32 v137, v146
	v_mov_b32_e32 v146, v139
	v_pk_add_f32 v[138:139], v[166:167], v[144:145]
	v_pk_add_f32 v[136:137], v[136:137], v[146:147]
	v_mov_b32_e32 v144, v148
	v_mov_b32_e32 v145, v156
	v_mov_b32_e32 v156, v149
	v_mov_b32_e32 v146, v150
	v_mov_b32_e32 v147, v158
	v_mov_b32_e32 v158, v151
	v_pk_add_f32 v[136:137], v[138:139], v[136:137]
	v_pk_add_f32 v[138:139], v[144:145], v[156:157]
	v_pk_add_f32 v[144:145], v[146:147], v[158:159]
	v_lshl_add_u64 v[150:151], v[216:217], 0, v[234:235]
	v_pk_add_f32 v[138:139], v[138:139], v[144:145]
	v_mov_b32_e32 v145, v136
	v_mov_b32_e32 v144, v138
	v_mov_b32_e32 v136, v139
	v_pk_add_f32 v[136:137], v[144:145], v[136:137]
	ds_bpermute_b32 v139, v250, v137
	ds_bpermute_b32 v138, v250, v136
	v_mov_b32_e32 v232, v112
	v_mov_b32_e32 v233, v120
	v_mov_b32_e32 v120, v113
	v_pk_add_f32 v[112:113], v[232:233], v[120:121]
	s_waitcnt lgkmcnt(0)
	v_pk_add_f32 v[146:147], v[136:137], v[138:139]
	global_load_dwordx4 v[168:171], v[218:219], off offset:2048
	global_load_dwordx4 v[136:139], v[218:219], off offset:3072
	global_load_dwordx4 v[180:183], v[164:165], off offset:256
	ds_bpermute_b32 v149, v249, v147
	ds_bpermute_b32 v148, v249, v146
	v_mov_b32_e32 v120, v114
	v_mov_b32_e32 v121, v122
	v_mov_b32_e32 v122, v115
	v_pk_add_f32 v[114:115], v[120:121], v[122:123]
	s_waitcnt lgkmcnt(0)
	v_pk_add_f32 v[146:147], v[146:147], v[148:149]
	v_mov_b32_e32 v120, v108
	v_pk_fma_f32 v[242:243], v[146:147], s[38:39], v[208:209] op_sel_hi:[1,0,0]
	v_mov_b32_e32 v121, v104
	v_mul_f32_e32 v146, 0x4b800000, v243
	v_cmp_gt_f32_e64 s[2:3], s52, v243
	v_mov_b32_e32 v104, v109
	v_mov_b32_e32 v108, v110
	v_cndmask_b32_e64 v146, v243, v146, s[2:3]
	v_rsq_f32_e32 v146, v146
	v_mov_b32_e32 v109, v106
	v_mov_b32_e32 v106, v111
	v_pk_add_f32 v[104:105], v[120:121], v[104:105]
	v_mul_f32_e32 v147, 0x45800000, v146
	v_cndmask_b32_e64 v244, v146, v147, s[2:3]
	v_pk_add_f32 v[106:107], v[108:109], v[106:107]
	v_pk_mul_f32 v[152:153], v[152:153], v[244:245] op_sel_hi:[1,0]
	s_movk_i32 s2, 0x1000
	v_pk_add_f32 v[112:113], v[112:113], v[114:115]
	v_pk_add_f32 v[104:105], v[104:105], v[106:107]
	v_mul_f32_e32 v152, 0xbfb8aa3b, v152
	v_lshl_add_u64 v[144:145], v[216:217], 0, v[224:225]
	v_add_co_u32_e64 v230, s[2:3], s2, v218
	v_lshl_add_u64 v[114:115], v[216:217], 0, v[226:227]
	v_mov_b32_e32 v106, v104
	v_mov_b32_e32 v107, v112
	v_mov_b32_e32 v112, v105
	v_exp_f32_e32 v152, v152
	v_mul_f32_e32 v153, 0xbfb8aa3b, v153
	global_load_dwordx4 v[172:175], v[150:151], off
	global_load_dwordx4 v[156:159], v[150:151], off offset:256
	v_addc_co_u32_e64 v231, s[2:3], 0, v219, s[2:3]
	global_load_dwordx4 v[160:163], v[144:145], off
	s_nop 0
	global_load_dwordx4 v[144:147], v[144:145], off offset:256
	s_nop 0
	global_load_dwordx4 v[164:167], v[230:231], off
	global_load_dwordx4 v[148:151], v[230:231], off offset:1024
	v_pk_add_f32 v[232:233], v[106:107], v[112:113]
	global_load_dwordx4 v[120:123], v[114:115], off
	global_load_dwordx4 v[108:111], v[114:115], off offset:256
	s_nop 0
	global_load_dwordx4 v[112:115], v[230:231], off offset:2048
	global_load_dwordx4 v[104:107], v[230:231], off offset:3072
	v_exp_f32_e32 v153, v153
	v_add_f32_e32 v152, 1.0, v152
	v_rcp_f32_e32 v152, v152
	v_lshlrev_b32_e32 v213, 16, v188
	v_add_f32_e32 v153, 1.0, v153
	v_rcp_f32_e32 v153, v153
	v_lshlrev_b32_e32 v243, 16, v184
	v_pk_mul_f32 v[154:155], v[154:155], v[244:245] op_sel_hi:[1,0]
	v_fmac_f32_e32 v213, v152, v243
	v_and_b32_e32 v152, 0xffff0000, v188
	v_and_b32_e32 v184, 0xffff0000, v184
	v_fmac_f32_e32 v152, v153, v184
	v_mul_f32_e32 v153, 0xbfb8aa3b, v154
	v_pk_mul_f32 v[140:141], v[140:141], v[244:245] op_sel_hi:[1,0]
	v_exp_f32_e32 v153, v153
	v_mul_f32_e32 v155, 0xbfb8aa3b, v155
	v_exp_f32_e32 v155, v155
	v_mul_f32_e32 v140, 0xbfb8aa3b, v140
	v_exp_f32_e32 v140, v140
	v_mul_f32_e32 v141, 0xbfb8aa3b, v141
	v_exp_f32_e32 v141, v141
	v_add_f32_e32 v153, 1.0, v153
	v_rcp_f32_e32 v153, v153
	v_add_f32_e32 v155, 1.0, v155
	v_rcp_f32_e32 v155, v155
	v_add_f32_e32 v140, 1.0, v140
	v_rcp_f32_e32 v140, v140
	v_add_f32_e32 v141, 1.0, v141
	v_lshlrev_b32_e32 v154, 16, v189
	v_lshlrev_b32_e32 v184, 16, v185
	v_rcp_f32_e32 v141, v141
	v_fmac_f32_e32 v154, v153, v184
	v_and_b32_e32 v153, 0xffff0000, v189
	v_and_b32_e32 v184, 0xffff0000, v185
	v_fmac_f32_e32 v153, v155, v184
	v_lshlrev_b32_e32 v155, 16, v190
	v_lshlrev_b32_e32 v184, 16, v186
	v_pk_mul_f32 v[142:143], v[142:143], v[244:245] op_sel_hi:[1,0]
	v_fmac_f32_e32 v155, v140, v184
	v_and_b32_e32 v184, 0xffff0000, v190
	v_and_b32_e32 v140, 0xffff0000, v186
	v_fmac_f32_e32 v184, v141, v140
	v_mul_f32_e32 v140, 0xbfb8aa3b, v142
	v_exp_f32_e32 v140, v140
	v_mul_f32_e32 v141, 0xbfb8aa3b, v143
	v_exp_f32_e32 v141, v141
	v_pk_mul_f32 v[132:133], v[132:133], v[244:245] op_sel_hi:[1,0]
	v_add_f32_e32 v140, 1.0, v140
	v_rcp_f32_e32 v140, v140
	v_add_f32_e32 v141, 1.0, v141
	v_rcp_f32_e32 v141, v141
	v_mul_f32_e32 v132, 0xbfb8aa3b, v132
	v_exp_f32_e32 v132, v132
	v_mul_f32_e32 v133, 0xbfb8aa3b, v133
	v_lshlrev_b32_e32 v185, 16, v191
	v_lshlrev_b32_e32 v142, 16, v187
	v_exp_f32_e32 v133, v133
	v_fmac_f32_e32 v185, v140, v142
	v_and_b32_e32 v186, 0xffff0000, v191
	v_and_b32_e32 v140, 0xffff0000, v187
	v_fmac_f32_e32 v186, v141, v140
	v_cvt_pk_bf16_f32 v140, v213, v152
	v_cvt_pk_bf16_f32 v141, v154, v153
	v_mul_f32_e32 v152, v152, v152
	v_mul_f32_e32 v153, v153, v153
	v_fmac_f32_e32 v152, v213, v213
	v_fmac_f32_e32 v153, v154, v154
	v_add_f32_e32 v132, 1.0, v132
	v_add_f32_e32 v152, v152, v153
	v_mul_f32_e32 v153, v184, v184
	v_mul_f32_e32 v154, v186, v186
	v_rcp_f32_e32 v132, v132
	v_add_f32_e32 v133, 1.0, v133
	v_fmac_f32_e32 v153, v155, v155
	v_fmac_f32_e32 v154, v185, v185
	v_rcp_f32_e32 v133, v133
	v_add_f32_e32 v153, v153, v154
	v_add_f32_e32 v152, v152, v153
	s_waitcnt vmcnt(10)
; __device__ __forceinline__ unsigned cvt_pk_bf16(float lo, float hi) { unsigned r; asm volatile("v_cvt_pk_bf16_f32 %0, %1, %2" : "=v"(r) : "v"(lo), "v"(hi)); return r; }
; __device__ __forceinline__ float bflo(unsigned w) { return __uint_as_float(w << 16); }
; __device__ __forceinline__ float bfhi(unsigned w) { return __uint_as_float(w & 0xffff0000u); }
; __device__ __forceinline__ float sigmoidf_(float x) { return __builtin_amdgcn_rcpf(1.0f + __expf(-x)); }
;     __device__ __forceinline__ void operator()(f32x4 (&acc)[2][2][4][2], const Unit& u, int wr, int wc, int fr, int fq) const {
;     ...
;             for (int m = 0; m < 4; ++m) { const int row = row0 + ai * HALF + m * 16; const size_t off = (size_t)row * DM + col0; float s = 0.f;
; #pragma unroll
;                 for (int bj = 0; bj < 2; ++bj) { const f32x4 z0 = acc[ai][bj][m][0] * rstd[m], z1 = acc[ai][bj][m][1] * rstd[m]; const u32x4 h2 = hw[m][bj], p2 = pw[m][bj]; f32x4 v0, v1;
;                     v0[0] = bflo(h2.x) + sigmoidf_(z0[0]) * bflo(p2.x); v0[1] = bfhi(h2.x) + sigmoidf_(z0[1]) * bfhi(p2.x);
;                     v0[2] = bflo(h2.y) + sigmoidf_(z0[2]) * bflo(p2.y); v0[3] = bfhi(h2.y) + sigmoidf_(z0[3]) * bfhi(p2.y);
;                     v1[0] = bflo(h2.z) + sigmoidf_(z1[0]) * bflo(p2.z); v1[1] = bfhi(h2.z) + sigmoidf_(z1[1]) * bfhi(p2.z);
;                     v1[2] = bflo(h2.w) + sigmoidf_(z1[2]) * bflo(p2.w); v1[3] = bfhi(h2.w) + sigmoidf_(z1[3]) * bfhi(p2.w);
;                     u32x4 w; w.x = cvt_pk_bf16(v0[0], v0[1]); w.y = cvt_pk_bf16(v0[2], v0[3]); w.z = cvt_pk_bf16(v1[0], v1[1]); w.w = cvt_pk_bf16(v1[2], v1[3]);
;                     *(u32x4*)(out + off + bj * HALF) = w;
;                     s += ((v0[0] * v0[0] + v0[1] * v0[1]) + (v0[2] * v0[2] + v0[3] * v0[3])) + ((v1[0] * v1[0] + v1[1] * v1[1]) + (v1[2] * v1[2] + v1[3] * v1[3])); }
;                 s += __shfl_xor(s, 16); s += __shfl_xor(s, 32);
;                 if (fq == 0) ssq[(size_t)row * 32 + u.pn * 4 + wc] = s; }
	v_lshlrev_b32_e32 v153, 16, v180
	v_lshlrev_b32_e32 v154, 16, v176
	v_pk_mul_f32 v[134:135], v[134:135], v[244:245] op_sel_hi:[1,0]
	v_fmac_f32_e32 v153, v132, v154
	v_and_b32_e32 v132, 0xffff0000, v180
	v_and_b32_e32 v154, 0xffff0000, v176
	v_fmac_f32_e32 v132, v133, v154
	v_mul_f32_e32 v133, 0xbfb8aa3b, v134
	v_pk_mul_f32 v[128:129], v[128:129], v[244:245] op_sel_hi:[1,0]
	v_exp_f32_e32 v133, v133
	v_mul_f32_e32 v134, 0xbfb8aa3b, v135
	v_exp_f32_e32 v134, v134
	v_mul_f32_e32 v128, 0xbfb8aa3b, v128
	v_exp_f32_e32 v128, v128
	v_mul_f32_e32 v129, 0xbfb8aa3b, v129
	v_exp_f32_e32 v129, v129
	v_add_f32_e32 v133, 1.0, v133
	v_rcp_f32_e32 v133, v133
	v_add_f32_e32 v134, 1.0, v134
	v_rcp_f32_e32 v134, v134
	v_add_f32_e32 v128, 1.0, v128
	v_rcp_f32_e32 v128, v128
	v_add_f32_e32 v129, 1.0, v129
	v_lshlrev_b32_e32 v154, 16, v181
	v_lshlrev_b32_e32 v135, 16, v177
	v_rcp_f32_e32 v129, v129
	v_fmac_f32_e32 v154, v133, v135
	v_and_b32_e32 v133, 0xffff0000, v181
	v_and_b32_e32 v135, 0xffff0000, v177
	v_cvt_pk_bf16_f32 v142, v155, v184
	v_fmac_f32_e32 v133, v134, v135
	v_lshlrev_b32_e32 v155, 16, v182
	v_lshlrev_b32_e32 v134, 16, v178
	v_pk_mul_f32 v[130:131], v[130:131], v[244:245] op_sel_hi:[1,0]
	v_fmac_f32_e32 v155, v128, v134
	v_and_b32_e32 v176, 0xffff0000, v182
	v_and_b32_e32 v128, 0xffff0000, v178
	v_fmac_f32_e32 v176, v129, v128
	v_mul_f32_e32 v128, 0xbfb8aa3b, v130
	v_exp_f32_e32 v128, v128
	v_mul_f32_e32 v129, 0xbfb8aa3b, v131
	v_exp_f32_e32 v129, v129
	v_lshlrev_b32_e32 v177, 16, v183
	v_add_f32_e32 v128, 1.0, v128
	v_rcp_f32_e32 v128, v128
	v_add_f32_e32 v129, 1.0, v129
	v_rcp_f32_e32 v129, v129
	v_lshlrev_b32_e32 v130, 16, v179
	v_fmac_f32_e32 v177, v128, v130
	v_and_b32_e32 v178, 0xffff0000, v183
	v_and_b32_e32 v128, 0xffff0000, v179
	v_fmac_f32_e32 v178, v129, v128
	v_mul_f32_e32 v128, v132, v132
	v_mul_f32_e32 v129, v133, v133
	v_fmac_f32_e32 v128, v153, v153
	v_fmac_f32_e32 v129, v154, v154
	v_add_f32_e32 v128, v128, v129
	v_mul_f32_e32 v129, v176, v176
	v_mul_f32_e32 v130, v178, v178
	v_fmac_f32_e32 v129, v155, v155
	v_fmac_f32_e32 v130, v177, v177
	v_add_f32_e32 v129, v129, v130
	v_add_f32_e32 v128, v128, v129
	v_add_f32_e32 v131, v152, v128
	ds_bpermute_b32 v253, v250, v233
	ds_bpermute_b32 v252, v250, v232
	ds_bpermute_b32 v152, v250, v131
	v_lshl_add_u64 v[128:129], s[0:1], 0, v[238:239]
	v_lshl_add_u64 v[134:135], v[128:129], 0, v[240:241]
	v_cmp_gt_f32_e32 vcc, s52, v242
	s_waitcnt lgkmcnt(1)
	v_pk_add_f32 v[230:231], v[232:233], v[252:253]
	s_waitcnt lgkmcnt(0)
	v_add_f32_e32 v128, v131, v152
	ds_bpermute_b32 v233, v249, v231
	ds_bpermute_b32 v232, v249, v230
	ds_bpermute_b32 v129, v249, v128
	v_cvt_pk_bf16_f32 v143, v185, v186
	global_store_dwordx4 v[134:135], v[140:143], off sc1
	v_cvt_pk_bf16_f32 v130, v153, v132
	v_cvt_pk_bf16_f32 v131, v154, v133
	v_cvt_pk_bf16_f32 v132, v155, v176
	v_cvt_pk_bf16_f32 v133, v177, v178
	global_store_dwordx4 v[134:135], v[130:133], off offset:256 sc1
	s_and_saveexec_b64 s[2:3], s[36:37]
	s_cbranch_execz .LBB0_1009
	v_lshl_add_u64 v[130:131], s[28:29], 0, v[236:237]
	v_lshl_add_u64 v[130:131], s[48:49], 2, v[130:131]
	s_lshl_b32 s4, s27, 2
	v_lshl_add_u64 v[130:131], v[130:131], 0, s[4:5]
	s_waitcnt lgkmcnt(0)
	v_add_f32_e32 v128, v128, v129
	global_store_dword v[130:131], v128, off
.LBB0_1009:
	s_or_b64 exec, exec, s[2:3]
	v_mul_f32_e32 v128, 0x4b800000, v242
	v_cndmask_b32_e32 v128, v242, v128, vcc
	v_rsq_f32_e32 v128, v128
	v_lshlrev_b32_e32 v130, 16, v168
	s_waitcnt vmcnt(11)
	v_lshlrev_b32_e32 v131, 16, v173
	v_and_b32_e32 v132, 0xffff0000, v173
	s_waitcnt lgkmcnt(0)
	v_mul_f32_e32 v129, 0x45800000, v128
	v_cndmask_b32_e32 v128, v128, v129, vcc
	v_pk_mul_f32 v[124:125], v[124:125], v[128:129] op_sel_hi:[1,0]
	v_pk_mul_f32 v[126:127], v[126:127], v[128:129] op_sel_hi:[1,0]
	v_mul_f32_e32 v124, 0xbfb8aa3b, v124
	v_exp_f32_e32 v124, v124
	v_pk_mul_f32 v[118:119], v[118:119], v[128:129] op_sel_hi:[1,0]
	v_pk_mul_f32 v[116:117], v[116:117], v[128:129] op_sel_hi:[1,0]
	v_lshlrev_b32_e32 v129, 16, v172
	v_add_f32_e32 v124, 1.0, v124
	v_rcp_f32_e32 v124, v124
	v_mul_f32_e32 v116, 0xbfb8aa3b, v116
	v_exp_f32_e32 v116, v116
	v_lshlrev_b32_e32 v133, 16, v174
	v_fmac_f32_e32 v129, v124, v130
	v_mul_f32_e32 v124, 0xbfb8aa3b, v125
	v_exp_f32_e32 v124, v124
	v_and_b32_e32 v130, 0xffff0000, v172
	v_and_b32_e32 v125, 0xffff0000, v168
	v_add_f32_e32 v116, 1.0, v116
	v_add_f32_e32 v124, 1.0, v124
	v_rcp_f32_e32 v124, v124
	v_rcp_f32_e32 v116, v116
	v_and_b32_e32 v134, 0xffff0000, v174
	v_lshlrev_b32_e32 v135, 16, v175
	v_fmac_f32_e32 v130, v124, v125
	v_mul_f32_e32 v124, 0xbfb8aa3b, v126
	v_exp_f32_e32 v124, v124
	v_lshlrev_b32_e32 v125, 16, v169
	v_pk_mul_f32 v[100:101], v[100:101], v[128:129] op_sel_hi:[1,0]
	v_pk_mul_f32 v[102:103], v[102:103], v[128:129] op_sel_hi:[1,0]
	v_add_f32_e32 v124, 1.0, v124
	v_rcp_f32_e32 v124, v124
	v_mul_f32_e32 v100, 0xbfb8aa3b, v100
	v_exp_f32_e32 v100, v100
	v_mul_f32_e32 v101, 0xbfb8aa3b, v101
	v_fmac_f32_e32 v131, v124, v125
	v_mul_f32_e32 v124, 0xbfb8aa3b, v127
	v_exp_f32_e32 v124, v124
	v_and_b32_e32 v125, 0xffff0000, v169
	v_exp_f32_e32 v101, v101
	v_mul_f32_e32 v102, 0xbfb8aa3b, v102
	v_add_f32_e32 v124, 1.0, v124
	v_rcp_f32_e32 v124, v124
	v_pk_mul_f32 v[96:97], v[96:97], v[128:129] op_sel_hi:[1,0]
	v_exp_f32_e32 v102, v102
	v_mul_f32_e32 v103, 0xbfb8aa3b, v103
	v_fmac_f32_e32 v132, v124, v125
	v_lshlrev_b32_e32 v124, 16, v170
	v_fmac_f32_e32 v133, v116, v124
	v_mul_f32_e32 v116, 0xbfb8aa3b, v117
	v_exp_f32_e32 v116, v116
	v_and_b32_e32 v117, 0xffff0000, v170
	v_cvt_pk_bf16_f32 v124, v129, v130
	v_cvt_pk_bf16_f32 v125, v131, v132
	v_add_f32_e32 v116, 1.0, v116
	v_rcp_f32_e32 v116, v116
	v_exp_f32_e32 v103, v103
	v_mul_f32_e32 v96, 0xbfb8aa3b, v96
	v_add_f32_e32 v100, 1.0, v100
	v_fmac_f32_e32 v134, v116, v117
	v_mul_f32_e32 v116, 0xbfb8aa3b, v118
	v_exp_f32_e32 v116, v116
	v_lshlrev_b32_e32 v117, 16, v171
	v_and_b32_e32 v118, 0xffff0000, v175
	v_cvt_pk_bf16_f32 v126, v133, v134
	v_add_f32_e32 v116, 1.0, v116
	v_rcp_f32_e32 v116, v116
	v_exp_f32_e32 v96, v96
	v_rcp_f32_e32 v100, v100
	v_add_f32_e32 v101, 1.0, v101
	v_fmac_f32_e32 v135, v116, v117
	v_mul_f32_e32 v116, 0xbfb8aa3b, v119
	v_exp_f32_e32 v116, v116
	v_and_b32_e32 v117, 0xffff0000, v171
	v_mul_f32_e32 v119, v130, v130
	v_fmac_f32_e32 v119, v129, v129
	v_add_f32_e32 v116, 1.0, v116
	v_rcp_f32_e32 v116, v116
	v_rcp_f32_e32 v101, v101
	v_add_f32_e32 v102, 1.0, v102
	v_rcp_f32_e32 v102, v102
	v_fmac_f32_e32 v118, v116, v117
	v_lshl_add_u64 v[116:117], s[0:1], 0, v[234:235]
	v_lshl_add_u64 v[116:117], v[210:211], 1, v[116:117]
	v_cvt_pk_bf16_f32 v127, v135, v118
	global_store_dwordx4 v[116:117], v[124:127], off sc1
	v_mul_f32_e32 v118, v118, v118
	v_fmac_f32_e32 v118, v135, v135
	v_mul_f32_e32 v124, v132, v132
	v_fmac_f32_e32 v124, v131, v131
	v_add_f32_e32 v119, v119, v124
	v_mul_f32_e32 v124, v134, v134
	v_fmac_f32_e32 v124, v133, v133
	v_add_f32_e32 v118, v124, v118
	v_add_f32_e32 v103, 1.0, v103
	v_add_f32_e32 v118, v119, v118
	s_waitcnt vmcnt(11)
; __device__ __forceinline__ unsigned cvt_pk_bf16(float lo, float hi) { unsigned r; asm volatile("v_cvt_pk_bf16_f32 %0, %1, %2" : "=v"(r) : "v"(lo), "v"(hi)); return r; }
; __device__ __forceinline__ float bflo(unsigned w) { return __uint_as_float(w << 16); }
; __device__ __forceinline__ float bfhi(unsigned w) { return __uint_as_float(w & 0xffff0000u); }
; __device__ __forceinline__ float sigmoidf_(float x) { return __builtin_amdgcn_rcpf(1.0f + __expf(-x)); }
; __device__ __forceinline__ float row_rstd(const float* ssq, int row, int fq) {
;     const f32x4 a = *(const f32x4*)(ssq + (size_t)row * 32 + 8 * fq), b = *(const f32x4*)(ssq + (size_t)row * 32 + 8 * fq + 4);
;     float t = ((a[0] + a[1]) + (a[2] + a[3])) + ((b[0] + b[1]) + (b[2] + b[3]));
;     t += __shfl_xor(t, 16); t += __shfl_xor(t, 32);
;     return rsqrtf(t * (1.0f / 2048.0f) + EPS);
;     __device__ __forceinline__ void operator()(f32x4 (&acc)[2][2][4][2], const Unit& u, int wr, int wc, int fr, int fq) const {
;     ...
;             for (int m = 0; m < 4; ++m) { const int row = row0 + ai * HALF + m * 16; const size_t off = (size_t)row * DM + col0; float s = 0.f;
; #pragma unroll
;                 for (int bj = 0; bj < 2; ++bj) { const f32x4 z0 = acc[ai][bj][m][0] * rstd[m], z1 = acc[ai][bj][m][1] * rstd[m]; const u32x4 h2 = hw[m][bj], p2 = pw[m][bj]; f32x4 v0, v1;
;                     v0[0] = bflo(h2.x) + sigmoidf_(z0[0]) * bflo(p2.x); v0[1] = bfhi(h2.x) + sigmoidf_(z0[1]) * bfhi(p2.x);
;                     v0[2] = bflo(h2.y) + sigmoidf_(z0[2]) * bflo(p2.y); v0[3] = bfhi(h2.y) + sigmoidf_(z0[3]) * bfhi(p2.y);
;                     v1[0] = bflo(h2.z) + sigmoidf_(z1[0]) * bflo(p2.z); v1[1] = bfhi(h2.z) + sigmoidf_(z1[1]) * bfhi(p2.z);
;                     v1[2] = bflo(h2.w) + sigmoidf_(z1[2]) * bflo(p2.w); v1[3] = bfhi(h2.w) + sigmoidf_(z1[3]) * bfhi(p2.w);
;                     u32x4 w; w.x = cvt_pk_bf16(v0[0], v0[1]); w.y = cvt_pk_bf16(v0[2], v0[3]); w.z = cvt_pk_bf16(v1[0], v1[1]); w.w = cvt_pk_bf16(v1[2], v1[3]);
;                     *(u32x4*)(out + off + bj * HALF) = w;
;                     s += ((v0[0] * v0[0] + v0[1] * v0[1]) + (v0[2] * v0[2] + v0[3] * v0[3])) + ((v1[0] * v1[0] + v1[1] * v1[1]) + (v1[2] * v1[2] + v1[3] * v1[3])); }
;                 s += __shfl_xor(s, 16); s += __shfl_xor(s, 32);
;                 if (fq == 0) ssq[(size_t)row * 32 + u.pn * 4 + wc] = s; }
	v_lshlrev_b32_e32 v119, 16, v156
	v_lshlrev_b32_e32 v124, 16, v136
	v_rcp_f32_e32 v103, v103
	v_add_f32_e32 v96, 1.0, v96
	v_fmac_f32_e32 v119, v100, v124
	v_and_b32_e32 v100, 0xffff0000, v156
	v_and_b32_e32 v124, 0xffff0000, v136
	v_rcp_f32_e32 v96, v96
	v_fmac_f32_e32 v100, v101, v124
	v_lshlrev_b32_e32 v101, 16, v157
	v_lshlrev_b32_e32 v124, 16, v137
	v_fmac_f32_e32 v101, v102, v124
	v_and_b32_e32 v102, 0xffff0000, v157
	v_and_b32_e32 v124, 0xffff0000, v137
	v_fmac_f32_e32 v102, v103, v124
	v_lshlrev_b32_e32 v103, 16, v158
	v_lshlrev_b32_e32 v124, 16, v138
	v_fmac_f32_e32 v103, v96, v124
	v_mul_f32_e32 v96, 0xbfb8aa3b, v97
	v_exp_f32_e32 v96, v96
	v_pk_mul_f32 v[98:99], v[98:99], v[128:129] op_sel_hi:[1,0]
	v_and_b32_e32 v124, 0xffff0000, v158
	v_and_b32_e32 v97, 0xffff0000, v138
	v_add_f32_e32 v96, 1.0, v96
	v_rcp_f32_e32 v96, v96
	v_lshlrev_b32_e32 v125, 16, v159
	v_and_b32_e32 v126, 0xffff0000, v159
	v_fmac_f32_e32 v124, v96, v97
	v_mul_f32_e32 v96, 0xbfb8aa3b, v98
	v_exp_f32_e32 v96, v96
	v_lshlrev_b32_e32 v97, 16, v139
	v_add_f32_e32 v96, 1.0, v96
	v_rcp_f32_e32 v96, v96
	s_nop 0
	v_fmac_f32_e32 v125, v96, v97
	v_mul_f32_e32 v96, 0xbfb8aa3b, v99
	v_exp_f32_e32 v96, v96
	v_and_b32_e32 v97, 0xffff0000, v139
	v_add_f32_e32 v96, 1.0, v96
	v_rcp_f32_e32 v96, v96
	s_nop 0
	v_fmac_f32_e32 v126, v96, v97
	v_cvt_pk_bf16_f32 v96, v119, v100
	v_cvt_pk_bf16_f32 v97, v101, v102
	v_cvt_pk_bf16_f32 v98, v103, v124
	v_cvt_pk_bf16_f32 v99, v125, v126
	global_store_dwordx4 v[116:117], v[96:99], off offset:256 sc1
	s_nop 1
	v_mul_f32_e32 v96, v100, v100
	v_mul_f32_e32 v97, v102, v102
	v_fmac_f32_e32 v96, v119, v119
	v_fmac_f32_e32 v97, v101, v101
	v_add_f32_e32 v96, v96, v97
	v_mul_f32_e32 v97, v124, v124
	v_mul_f32_e32 v98, v126, v126
	v_fmac_f32_e32 v97, v103, v103
	v_fmac_f32_e32 v98, v125, v125
	v_add_f32_e32 v97, v97, v98
	v_add_f32_e32 v96, v96, v97
	v_add_f32_e32 v96, v118, v96
	ds_bpermute_b32 v97, v250, v96
	s_waitcnt lgkmcnt(0)
	v_add_f32_e32 v96, v96, v97
	ds_bpermute_b32 v97, v249, v96
	s_and_saveexec_b64 s[2:3], s[36:37]
	s_cbranch_execz .LBB0_1011
	v_lshl_add_u64 v[98:99], s[28:29], 0, v[228:229]
	v_lshl_add_u64 v[98:99], s[48:49], 2, v[98:99]
	s_lshl_b32 s4, s27, 2
	v_lshl_add_u64 v[98:99], v[98:99], 0, s[4:5]
	s_waitcnt lgkmcnt(0)
	v_add_f32_e32 v96, v96, v97
	global_store_dword v[98:99], v96, off
.LBB0_1011:
	s_or_b64 exec, exec, s[2:3]
	s_waitcnt lgkmcnt(0)
	v_pk_add_f32 v[96:97], v[230:231], v[232:233]
	s_waitcnt vmcnt(11)
	v_lshlrev_b32_e32 v100, 16, v163
	v_pk_fma_f32 v[96:97], v[96:97], s[38:39], v[208:209] op_sel_hi:[1,0,0]
	v_and_b32_e32 v101, 0xffff0000, v163
	v_mul_f32_e32 v98, 0x4b800000, v97
	v_cmp_gt_f32_e64 s[2:3], s52, v97
	v_cmp_gt_f32_e32 vcc, s52, v96
	s_nop 0
	v_cndmask_b32_e64 v97, v97, v98, s[2:3]
	v_rsq_f32_e32 v97, v97
	s_nop 0
	v_mul_f32_e32 v98, 0x45800000, v97
	v_cndmask_b32_e64 v98, v97, v98, s[2:3]
	v_pk_mul_f32 v[92:93], v[92:93], v[98:99] op_sel_hi:[1,0]
	v_pk_mul_f32 v[94:95], v[94:95], v[98:99] op_sel_hi:[1,0]
	v_mul_f32_e32 v92, 0xbfb8aa3b, v92
	v_exp_f32_e32 v92, v92
	v_mul_f32_e32 v93, 0xbfb8aa3b, v93
	v_exp_f32_e32 v93, v93
	v_pk_mul_f32 v[90:91], v[90:91], v[98:99] op_sel_hi:[1,0]
	v_add_f32_e32 v92, 1.0, v92
	v_rcp_f32_e32 v92, v92
	v_add_f32_e32 v93, 1.0, v93
	v_rcp_f32_e32 v93, v93
	v_pk_mul_f32 v[88:89], v[88:89], v[98:99] op_sel_hi:[1,0]
	v_lshlrev_b32_e32 v97, 16, v160
	s_waitcnt vmcnt(9)
	v_lshlrev_b32_e32 v99, 16, v164
	v_fmac_f32_e32 v97, v92, v99
	v_and_b32_e32 v92, 0xffff0000, v160
	v_and_b32_e32 v99, 0xffff0000, v164
	v_fmac_f32_e32 v92, v93, v99
	v_mul_f32_e32 v93, 0xbfb8aa3b, v94
	v_exp_f32_e32 v93, v93
	v_mul_f32_e32 v95, 0xbfb8aa3b, v95
	v_exp_f32_e32 v95, v95
	v_mul_f32_e32 v88, 0xbfb8aa3b, v88
	v_exp_f32_e32 v88, v88
	v_mul_f32_e32 v89, 0xbfb8aa3b, v89
	v_exp_f32_e32 v89, v89
	v_add_f32_e32 v93, 1.0, v93
	v_rcp_f32_e32 v93, v93
	v_add_f32_e32 v95, 1.0, v95
	v_rcp_f32_e32 v95, v95
	v_add_f32_e32 v88, 1.0, v88
	v_rcp_f32_e32 v88, v88
	v_add_f32_e32 v89, 1.0, v89
	v_lshlrev_b32_e32 v94, 16, v161
	v_lshlrev_b32_e32 v99, 16, v165
	v_rcp_f32_e32 v89, v89
	v_fmac_f32_e32 v94, v93, v99
	v_and_b32_e32 v93, 0xffff0000, v161
	v_and_b32_e32 v99, 0xffff0000, v165
	v_fmac_f32_e32 v93, v95, v99
	v_lshlrev_b32_e32 v95, 16, v162
	v_lshlrev_b32_e32 v99, 16, v166
	v_fmac_f32_e32 v95, v88, v99
	v_and_b32_e32 v99, 0xffff0000, v162
	v_and_b32_e32 v88, 0xffff0000, v166
	v_fmac_f32_e32 v99, v89, v88
	v_mul_f32_e32 v88, 0xbfb8aa3b, v90
	v_exp_f32_e32 v88, v88
	v_mul_f32_e32 v89, 0xbfb8aa3b, v91
	v_exp_f32_e32 v89, v89
	v_pk_mul_f32 v[84:85], v[84:85], v[98:99] op_sel_hi:[1,0]
	v_add_f32_e32 v88, 1.0, v88
	v_rcp_f32_e32 v88, v88
	v_add_f32_e32 v89, 1.0, v89
	v_rcp_f32_e32 v89, v89
	v_mul_f32_e32 v84, 0xbfb8aa3b, v84
	v_exp_f32_e32 v84, v84
	v_mul_f32_e32 v85, 0xbfb8aa3b, v85
	v_lshlrev_b32_e32 v90, 16, v167
	v_exp_f32_e32 v85, v85
	v_fmac_f32_e32 v100, v88, v90
	v_and_b32_e32 v88, 0xffff0000, v167
	v_fmac_f32_e32 v101, v89, v88
	v_cvt_pk_bf16_f32 v88, v97, v92
	v_cvt_pk_bf16_f32 v89, v94, v93
	v_mul_f32_e32 v92, v92, v92
	v_mul_f32_e32 v93, v93, v93
	v_fmac_f32_e32 v92, v97, v97
	v_fmac_f32_e32 v93, v94, v94
	v_add_f32_e32 v84, 1.0, v84
	v_add_f32_e32 v92, v92, v93
	v_mul_f32_e32 v93, v99, v99
	v_mul_f32_e32 v94, v101, v101
	v_rcp_f32_e32 v84, v84
	v_add_f32_e32 v85, 1.0, v85
	v_fmac_f32_e32 v93, v95, v95
	v_fmac_f32_e32 v94, v100, v100
	v_rcp_f32_e32 v85, v85
	v_add_f32_e32 v93, v93, v94
	v_add_f32_e32 v92, v92, v93
	v_lshlrev_b32_e32 v93, 16, v144
	s_waitcnt vmcnt(8)
; __device__ __forceinline__ unsigned cvt_pk_bf16(float lo, float hi) { unsigned r; asm volatile("v_cvt_pk_bf16_f32 %0, %1, %2" : "=v"(r) : "v"(lo), "v"(hi)); return r; }
; __device__ __forceinline__ float bflo(unsigned w) { return __uint_as_float(w << 16); }
; __device__ __forceinline__ float bfhi(unsigned w) { return __uint_as_float(w & 0xffff0000u); }
; __device__ __forceinline__ float sigmoidf_(float x) { return __builtin_amdgcn_rcpf(1.0f + __expf(-x)); }
;     __device__ __forceinline__ void operator()(f32x4 (&acc)[2][2][4][2], const Unit& u, int wr, int wc, int fr, int fq) const {
;     ...
;             for (int m = 0; m < 4; ++m) { const int row = row0 + ai * HALF + m * 16; const size_t off = (size_t)row * DM + col0; float s = 0.f;
; #pragma unroll
;                 for (int bj = 0; bj < 2; ++bj) { const f32x4 z0 = acc[ai][bj][m][0] * rstd[m], z1 = acc[ai][bj][m][1] * rstd[m]; const u32x4 h2 = hw[m][bj], p2 = pw[m][bj]; f32x4 v0, v1;
;                     v0[0] = bflo(h2.x) + sigmoidf_(z0[0]) * bflo(p2.x); v0[1] = bfhi(h2.x) + sigmoidf_(z0[1]) * bfhi(p2.x);
;                     v0[2] = bflo(h2.y) + sigmoidf_(z0[2]) * bflo(p2.y); v0[3] = bfhi(h2.y) + sigmoidf_(z0[3]) * bfhi(p2.y);
;                     v1[0] = bflo(h2.z) + sigmoidf_(z1[0]) * bflo(p2.z); v1[1] = bfhi(h2.z) + sigmoidf_(z1[1]) * bfhi(p2.z);
;                     v1[2] = bflo(h2.w) + sigmoidf_(z1[2]) * bflo(p2.w); v1[3] = bfhi(h2.w) + sigmoidf_(z1[3]) * bfhi(p2.w);
;                     u32x4 w; w.x = cvt_pk_bf16(v0[0], v0[1]); w.y = cvt_pk_bf16(v0[2], v0[3]); w.z = cvt_pk_bf16(v1[0], v1[1]); w.w = cvt_pk_bf16(v1[2], v1[3]);
;                     *(u32x4*)(out + off + bj * HALF) = w;
;                     s += ((v0[0] * v0[0] + v0[1] * v0[1]) + (v0[2] * v0[2] + v0[3] * v0[3])) + ((v1[0] * v1[0] + v1[1] * v1[1]) + (v1[2] * v1[2] + v1[3] * v1[3])); }
;                 s += __shfl_xor(s, 16); s += __shfl_xor(s, 32);
;                 if (fq == 0) ssq[(size_t)row * 32 + u.pn * 4 + wc] = s; }
	v_lshlrev_b32_e32 v94, 16, v148
	v_pk_mul_f32 v[86:87], v[86:87], v[98:99] op_sel_hi:[1,0]
	v_fmac_f32_e32 v93, v84, v94
	v_and_b32_e32 v84, 0xffff0000, v144
	v_and_b32_e32 v94, 0xffff0000, v148
	v_fmac_f32_e32 v84, v85, v94
	v_mul_f32_e32 v85, 0xbfb8aa3b, v86
	v_pk_mul_f32 v[80:81], v[80:81], v[98:99] op_sel_hi:[1,0]
	v_exp_f32_e32 v85, v85
	v_mul_f32_e32 v86, 0xbfb8aa3b, v87
	v_exp_f32_e32 v86, v86
	v_mul_f32_e32 v80, 0xbfb8aa3b, v80
	v_exp_f32_e32 v80, v80
	v_mul_f32_e32 v81, 0xbfb8aa3b, v81
	v_exp_f32_e32 v81, v81
	v_add_f32_e32 v85, 1.0, v85
	v_rcp_f32_e32 v85, v85
	v_add_f32_e32 v86, 1.0, v86
	v_rcp_f32_e32 v86, v86
	v_add_f32_e32 v80, 1.0, v80
	v_rcp_f32_e32 v80, v80
	v_add_f32_e32 v81, 1.0, v81
	v_lshlrev_b32_e32 v94, 16, v145
	v_lshlrev_b32_e32 v87, 16, v149
	v_rcp_f32_e32 v81, v81
	v_fmac_f32_e32 v94, v85, v87
	v_and_b32_e32 v85, 0xffff0000, v145
	v_and_b32_e32 v87, 0xffff0000, v149
	v_cvt_pk_bf16_f32 v90, v95, v99
	v_fmac_f32_e32 v85, v86, v87
	v_lshlrev_b32_e32 v95, 16, v146
	v_lshlrev_b32_e32 v86, 16, v150
	v_pk_mul_f32 v[82:83], v[82:83], v[98:99] op_sel_hi:[1,0]
	v_fmac_f32_e32 v95, v80, v86
	v_and_b32_e32 v97, 0xffff0000, v146
	v_and_b32_e32 v80, 0xffff0000, v150
	v_fmac_f32_e32 v97, v81, v80
	v_mul_f32_e32 v80, 0xbfb8aa3b, v82
	v_exp_f32_e32 v80, v80
	v_mul_f32_e32 v81, 0xbfb8aa3b, v83
	v_exp_f32_e32 v81, v81
	v_lshlrev_b32_e32 v98, 16, v147
	v_add_f32_e32 v80, 1.0, v80
	v_rcp_f32_e32 v80, v80
	v_add_f32_e32 v81, 1.0, v81
	v_rcp_f32_e32 v81, v81
	v_lshlrev_b32_e32 v82, 16, v151
	v_fmac_f32_e32 v98, v80, v82
	v_and_b32_e32 v99, 0xffff0000, v147
	v_and_b32_e32 v80, 0xffff0000, v151
	v_fmac_f32_e32 v99, v81, v80
	v_mul_f32_e32 v80, v84, v84
	v_mul_f32_e32 v81, v85, v85
	v_fmac_f32_e32 v80, v93, v93
	v_fmac_f32_e32 v81, v94, v94
	v_add_f32_e32 v80, v80, v81
	v_mul_f32_e32 v81, v97, v97
	v_mul_f32_e32 v82, v99, v99
	v_fmac_f32_e32 v81, v95, v95
	v_fmac_f32_e32 v82, v98, v98
	v_add_f32_e32 v81, v81, v82
	v_add_f32_e32 v80, v80, v81
	v_add_f32_e32 v83, v92, v80
	ds_bpermute_b32 v92, v250, v83
	v_lshl_add_u64 v[80:81], s[0:1], 0, v[224:225]
	v_lshl_add_u64 v[86:87], v[210:211], 1, v[80:81]
	v_cvt_pk_bf16_f32 v91, v100, v101
	global_store_dwordx4 v[86:87], v[88:91], off sc1
	s_waitcnt lgkmcnt(0)
	v_add_f32_e32 v80, v83, v92
	ds_bpermute_b32 v81, v249, v80
	v_cvt_pk_bf16_f32 v82, v93, v84
	v_cvt_pk_bf16_f32 v83, v94, v85
	v_cvt_pk_bf16_f32 v84, v95, v97
	v_cvt_pk_bf16_f32 v85, v98, v99
	global_store_dwordx4 v[86:87], v[82:85], off offset:256 sc1
	s_and_saveexec_b64 s[2:3], s[36:37]
	s_cbranch_execz .LBB0_1013
	v_lshl_add_u64 v[82:83], s[28:29], 0, v[222:223]
	v_lshl_add_u64 v[82:83], s[48:49], 2, v[82:83]
	s_lshl_b32 s4, s27, 2
	v_lshl_add_u64 v[82:83], v[82:83], 0, s[4:5]
	s_waitcnt lgkmcnt(0)
	v_add_f32_e32 v80, v80, v81
	global_store_dword v[82:83], v80, off
.LBB0_1013:
	s_or_b64 exec, exec, s[2:3]
	v_mul_f32_e32 v80, 0x4b800000, v96
	v_cndmask_b32_e32 v80, v96, v80, vcc
	v_rsq_f32_e32 v80, v80
	s_waitcnt vmcnt(7)
	v_lshlrev_b32_e32 v82, 16, v112
	v_lshlrev_b32_e32 v83, 16, v121
	v_and_b32_e32 v84, 0xffff0000, v122
	s_waitcnt lgkmcnt(0)
	v_mul_f32_e32 v81, 0x45800000, v80
	v_cndmask_b32_e32 v80, v80, v81, vcc
	v_pk_mul_f32 v[76:77], v[76:77], v[80:81] op_sel_hi:[1,0]
	v_pk_mul_f32 v[78:79], v[78:79], v[80:81] op_sel_hi:[1,0]
	v_mul_f32_e32 v76, 0xbfb8aa3b, v76
	v_exp_f32_e32 v76, v76
	v_pk_mul_f32 v[74:75], v[74:75], v[80:81] op_sel_hi:[1,0]
	v_pk_mul_f32 v[72:73], v[72:73], v[80:81] op_sel_hi:[1,0]
	v_lshlrev_b32_e32 v81, 16, v120
	v_add_f32_e32 v76, 1.0, v76
	v_rcp_f32_e32 v76, v76
	v_mul_f32_e32 v72, 0xbfb8aa3b, v72
	v_exp_f32_e32 v72, v72
	v_lshlrev_b32_e32 v85, 16, v123
	v_fmac_f32_e32 v81, v76, v82
	v_mul_f32_e32 v76, 0xbfb8aa3b, v77
	v_exp_f32_e32 v76, v76
	v_and_b32_e32 v82, 0xffff0000, v120
	v_and_b32_e32 v77, 0xffff0000, v112
	v_add_f32_e32 v72, 1.0, v72
	v_add_f32_e32 v76, 1.0, v76
	v_rcp_f32_e32 v76, v76
	v_rcp_f32_e32 v72, v72
	v_pk_mul_f32 v[68:69], v[68:69], v[80:81] op_sel_hi:[1,0]
	v_and_b32_e32 v86, 0xffff0000, v123
	v_fmac_f32_e32 v82, v76, v77
	v_mul_f32_e32 v76, 0xbfb8aa3b, v78
	v_exp_f32_e32 v76, v76
	v_lshlrev_b32_e32 v77, 16, v113
	v_and_b32_e32 v78, 0xffff0000, v121
	v_mul_f32_e32 v68, 0xbfb8aa3b, v68
	v_add_f32_e32 v76, 1.0, v76
	v_rcp_f32_e32 v76, v76
	v_pk_mul_f32 v[70:71], v[70:71], v[80:81] op_sel_hi:[1,0]
	v_exp_f32_e32 v68, v68
	v_mul_f32_e32 v69, 0xbfb8aa3b, v69
	v_fmac_f32_e32 v83, v76, v77
	v_mul_f32_e32 v76, 0xbfb8aa3b, v79
	v_exp_f32_e32 v76, v76
	v_and_b32_e32 v77, 0xffff0000, v113
	v_lshlrev_b32_e32 v79, 16, v122
	v_exp_f32_e32 v69, v69
	v_add_f32_e32 v76, 1.0, v76
	v_rcp_f32_e32 v76, v76
	v_mul_f32_e32 v70, 0xbfb8aa3b, v70
	v_pk_mul_f32 v[64:65], v[64:65], v[80:81] op_sel_hi:[1,0]
	v_exp_f32_e32 v70, v70
	v_fmac_f32_e32 v78, v76, v77
	v_lshlrev_b32_e32 v76, 16, v114
	v_fmac_f32_e32 v79, v72, v76
	v_mul_f32_e32 v72, 0xbfb8aa3b, v73
	v_exp_f32_e32 v72, v72
	v_and_b32_e32 v73, 0xffff0000, v114
	v_mul_f32_e32 v71, 0xbfb8aa3b, v71
	v_exp_f32_e32 v71, v71
	v_add_f32_e32 v72, 1.0, v72
	v_rcp_f32_e32 v72, v72
	v_mul_f32_e32 v64, 0xbfb8aa3b, v64
	v_add_f32_e32 v68, 1.0, v68
	v_exp_f32_e32 v64, v64
	v_fmac_f32_e32 v84, v72, v73
	v_mul_f32_e32 v72, 0xbfb8aa3b, v74
	v_exp_f32_e32 v72, v72
	v_lshlrev_b32_e32 v73, 16, v115
	v_cvt_pk_bf16_f32 v74, v81, v82
	v_rcp_f32_e32 v68, v68
	v_add_f32_e32 v72, 1.0, v72
	v_rcp_f32_e32 v72, v72
	v_add_f32_e32 v69, 1.0, v69
	v_rcp_f32_e32 v69, v69
	v_add_f32_e32 v70, 1.0, v70
	v_fmac_f32_e32 v85, v72, v73
	v_mul_f32_e32 v72, 0xbfb8aa3b, v75
	v_exp_f32_e32 v72, v72
	v_and_b32_e32 v73, 0xffff0000, v115
	v_cvt_pk_bf16_f32 v75, v83, v78
	v_cvt_pk_bf16_f32 v76, v79, v84
	v_add_f32_e32 v72, 1.0, v72
	v_rcp_f32_e32 v72, v72
	v_rcp_f32_e32 v70, v70
	v_add_f32_e32 v71, 1.0, v71
	v_rcp_f32_e32 v71, v71
	v_fmac_f32_e32 v86, v72, v73
	v_lshl_add_u64 v[72:73], s[0:1], 0, v[226:227]
	v_lshl_add_u64 v[72:73], v[210:211], 1, v[72:73]
	v_cvt_pk_bf16_f32 v77, v85, v86
	global_store_dwordx4 v[72:73], v[74:77], off sc1
	v_add_f32_e32 v64, 1.0, v64
	v_rcp_f32_e32 v64, v64
	v_mul_f32_e32 v74, v82, v82
	v_mul_f32_e32 v75, v78, v78
	v_fmac_f32_e32 v74, v81, v81
	v_fmac_f32_e32 v75, v83, v83
	v_add_f32_e32 v74, v74, v75
	v_mul_f32_e32 v75, v84, v84
	v_mul_f32_e32 v76, v86, v86
	v_fmac_f32_e32 v75, v79, v79
	v_fmac_f32_e32 v76, v85, v85
	v_add_f32_e32 v75, v75, v76
	v_add_f32_e32 v74, v74, v75
	v_lshlrev_b32_e32 v75, 16, v108
	s_waitcnt vmcnt(7)
; __device__ __forceinline__ unsigned cvt_pk_bf16(float lo, float hi) { unsigned r; asm volatile("v_cvt_pk_bf16_f32 %0, %1, %2" : "=v"(r) : "v"(lo), "v"(hi)); return r; }
; __device__ __forceinline__ float bflo(unsigned w) { return __uint_as_float(w << 16); }
; __device__ __forceinline__ float bfhi(unsigned w) { return __uint_as_float(w & 0xffff0000u); }
; __device__ __forceinline__ float sigmoidf_(float x) { return __builtin_amdgcn_rcpf(1.0f + __expf(-x)); }
;     __device__ __forceinline__ void operator()(f32x4 (&acc)[2][2][4][2], const Unit& u, int wr, int wc, int fr, int fq) const {
;     ...
;             for (int m = 0; m < 4; ++m) { const int row = row0 + ai * HALF + m * 16;
; #pragma unroll
;                 for (int bj = 0; bj < 2; ++bj) { const size_t o = (size_t)row * DM + col0 + bj * HALF; hw[m][bj] = *(const u32x4*)(hb + o); pw[m][bj] = *(const u32x4*)(ppf + (((ai * 4 + m) * 2 + bj) << 9)); }
;                 rstd[m] = row_rstd(ssq_in, row, fq); }
;     ...
;             for (int m = 0; m < 4; ++m) { const int row = row0 + ai * HALF + m * 16; const size_t off = (size_t)row * DM + col0; float s = 0.f;
; #pragma unroll
;                 for (int bj = 0; bj < 2; ++bj) { const f32x4 z0 = acc[ai][bj][m][0] * rstd[m], z1 = acc[ai][bj][m][1] * rstd[m]; const u32x4 h2 = hw[m][bj], p2 = pw[m][bj]; f32x4 v0, v1;
;                     v0[0] = bflo(h2.x) + sigmoidf_(z0[0]) * bflo(p2.x); v0[1] = bfhi(h2.x) + sigmoidf_(z0[1]) * bfhi(p2.x);
;                     v0[2] = bflo(h2.y) + sigmoidf_(z0[2]) * bflo(p2.y); v0[3] = bfhi(h2.y) + sigmoidf_(z0[3]) * bfhi(p2.y);
;                     v1[0] = bflo(h2.z) + sigmoidf_(z1[0]) * bflo(p2.z); v1[1] = bfhi(h2.z) + sigmoidf_(z1[1]) * bfhi(p2.z);
;                     v1[2] = bflo(h2.w) + sigmoidf_(z1[2]) * bflo(p2.w); v1[3] = bfhi(h2.w) + sigmoidf_(z1[3]) * bfhi(p2.w);
;                     u32x4 w; w.x = cvt_pk_bf16(v0[0], v0[1]); w.y = cvt_pk_bf16(v0[2], v0[3]); w.z = cvt_pk_bf16(v1[0], v1[1]); w.w = cvt_pk_bf16(v1[2], v1[3]);
;                     *(u32x4*)(out + off + bj * HALF) = w;
;                     s += ((v0[0] * v0[0] + v0[1] * v0[1]) + (v0[2] * v0[2] + v0[3] * v0[3])) + ((v1[0] * v1[0] + v1[1] * v1[1]) + (v1[2] * v1[2] + v1[3] * v1[3])); }
;                 s += __shfl_xor(s, 16); s += __shfl_xor(s, 32);
;                 if (fq == 0) ssq[(size_t)row * 32 + u.pn * 4 + wc] = s; }
	v_lshlrev_b32_e32 v76, 16, v104
	v_fmac_f32_e32 v75, v68, v76
	v_and_b32_e32 v68, 0xffff0000, v108
	v_and_b32_e32 v76, 0xffff0000, v104
	v_fmac_f32_e32 v68, v69, v76
	v_lshlrev_b32_e32 v69, 16, v109
	v_lshlrev_b32_e32 v76, 16, v105
	v_fmac_f32_e32 v69, v70, v76
	v_and_b32_e32 v70, 0xffff0000, v109
	v_and_b32_e32 v76, 0xffff0000, v105
	v_fmac_f32_e32 v70, v71, v76
	v_lshlrev_b32_e32 v71, 16, v110
	v_lshlrev_b32_e32 v76, 16, v106
	v_fmac_f32_e32 v71, v64, v76
	v_mul_f32_e32 v64, 0xbfb8aa3b, v65
	v_exp_f32_e32 v64, v64
	v_pk_mul_f32 v[66:67], v[66:67], v[80:81] op_sel_hi:[1,0]
	v_and_b32_e32 v76, 0xffff0000, v110
	v_and_b32_e32 v65, 0xffff0000, v106
	v_add_f32_e32 v64, 1.0, v64
	v_rcp_f32_e32 v64, v64
	v_lshlrev_b32_e32 v77, 16, v111
	v_and_b32_e32 v78, 0xffff0000, v111
	v_fmac_f32_e32 v76, v64, v65
	v_mul_f32_e32 v64, 0xbfb8aa3b, v66
	v_exp_f32_e32 v64, v64
	v_lshlrev_b32_e32 v65, 16, v107
	v_add_f32_e32 v64, 1.0, v64
	v_rcp_f32_e32 v64, v64
	s_nop 0
	v_fmac_f32_e32 v77, v64, v65
	v_mul_f32_e32 v64, 0xbfb8aa3b, v67
	v_exp_f32_e32 v64, v64
	v_and_b32_e32 v65, 0xffff0000, v107
	v_add_f32_e32 v64, 1.0, v64
	v_rcp_f32_e32 v64, v64
	s_nop 0
	v_fmac_f32_e32 v78, v64, v65
	v_cvt_pk_bf16_f32 v64, v75, v68
	v_cvt_pk_bf16_f32 v65, v69, v70
	v_cvt_pk_bf16_f32 v66, v71, v76
	v_cvt_pk_bf16_f32 v67, v77, v78
	global_store_dwordx4 v[72:73], v[64:67], off offset:256 sc1
	s_nop 1
	v_mul_f32_e32 v64, v68, v68
	v_mul_f32_e32 v65, v70, v70
	v_fmac_f32_e32 v64, v75, v75
	v_fmac_f32_e32 v65, v69, v69
	v_add_f32_e32 v64, v64, v65
	v_mul_f32_e32 v65, v76, v76
	v_mul_f32_e32 v66, v78, v78
	v_fmac_f32_e32 v65, v71, v71
	v_fmac_f32_e32 v66, v77, v77
	v_add_f32_e32 v65, v65, v66
	v_add_f32_e32 v64, v64, v65
	v_add_f32_e32 v64, v74, v64
	ds_bpermute_b32 v65, v250, v64
	s_waitcnt lgkmcnt(0)
	v_add_f32_e32 v64, v64, v65
	ds_bpermute_b32 v65, v249, v64
	s_and_saveexec_b64 s[2:3], s[36:37]
	s_cbranch_execz .LBB0_1015
	v_lshl_add_u64 v[66:67], s[28:29], 0, v[220:221]
	v_lshl_add_u64 v[66:67], s[48:49], 2, v[66:67]
	s_lshl_b32 s4, s27, 2
	v_lshl_add_u64 v[66:67], v[66:67], 0, s[4:5]
	s_waitcnt lgkmcnt(0)
	v_add_f32_e32 v64, v64, v65
	global_store_dword v[66:67], v64, off
.LBB0_1015:
	s_or_b64 exec, exec, s[2:3]
	v_add_u32_e32 v80, 0x80, v212
	v_add_u32_e32 v82, 0x90, v212
	v_ashrrev_i32_e32 v81, 31, v80
	v_ashrrev_i32_e32 v83, 31, v82
	v_lshlrev_b64 v[148:149], 7, v[80:81]
	v_lshlrev_b64 v[144:145], 7, v[82:83]
	s_waitcnt lgkmcnt(0)
	v_lshl_add_u64 v[64:65], v[214:215], 0, v[148:149]
	v_lshl_add_u64 v[68:69], v[214:215], 0, v[144:145]
	global_load_dwordx4 v[72:75], v[64:65], off
	s_nop 0
	global_load_dwordx4 v[64:67], v[64:65], off offset:16
	s_nop 0
	global_load_dwordx4 v[128:131], v[68:69], off
	s_nop 0
	global_load_dwordx4 v[68:71], v[68:69], off offset:16
	v_add_u32_e32 v84, 0xa0, v212
	v_add_u32_e32 v86, 0xb0, v212
	v_ashrrev_i32_e32 v85, 31, v84
	v_ashrrev_i32_e32 v87, 31, v86
	v_lshlrev_b64 v[140:141], 7, v[84:85]
	v_lshlrev_b64 v[136:137], 7, v[86:87]
	v_lshl_add_u64 v[76:77], v[214:215], 0, v[140:141]
	v_lshl_add_u64 v[88:89], v[214:215], 0, v[136:137]
	global_load_dwordx4 v[156:159], v[76:77], off
	s_nop 0
	global_load_dwordx4 v[76:79], v[76:77], off offset:16
	s_nop 0
	global_load_dwordx4 v[160:163], v[88:89], off
	global_load_dwordx4 v[132:135], v[88:89], off offset:16
	v_add_co_u32_e32 v88, vcc, 0x2000, v218
	s_movk_i32 s2, 0x3000
	s_nop 0
	v_addc_co_u32_e32 v89, vcc, 0, v219, vcc
	v_add_co_u32_e32 v152, vcc, s2, v218
	v_lshlrev_b64 v[150:151], 12, v[80:81]
	s_nop 0
	v_addc_co_u32_e32 v153, vcc, 0, v219, vcc
	v_lshlrev_b64 v[142:143], 12, v[84:85]
	v_lshl_add_u64 v[84:85], v[216:217], 0, v[150:151]
	global_load_dwordx4 v[120:123], v[88:89], off
	global_load_dwordx4 v[112:115], v[88:89], off offset:1024
	v_lshlrev_b64 v[146:147], 12, v[82:83]
	global_load_dwordx4 v[104:107], v[88:89], off offset:2048
	global_load_dwordx4 v[96:99], v[88:89], off offset:3072
	s_nop 0
	global_load_dwordx4 v[88:91], v[152:153], off
	global_load_dwordx4 v[80:83], v[152:153], off offset:1024
	global_load_dwordx4 v[124:127], v[84:85], off
	v_lshlrev_b64 v[138:139], 12, v[86:87]
	v_lshl_add_u64 v[86:87], v[216:217], 0, v[146:147]
	v_lshl_add_u64 v[164:165], v[216:217], 0, v[142:143]
	global_load_dwordx4 v[116:119], v[84:85], off offset:256
	global_load_dwordx4 v[108:111], v[86:87], off
	global_load_dwordx4 v[100:103], v[86:87], off offset:256
	global_load_dwordx4 v[92:95], v[164:165], off
	s_nop 0
	global_load_dwordx4 v[84:87], v[164:165], off offset:256
	v_lshl_add_u64 v[154:155], v[216:217], 0, v[138:139]
	s_waitcnt vmcnt(19)
	v_mov_b32_e32 v164, v72
	s_waitcnt vmcnt(18)
	v_mov_b32_e32 v165, v64
	v_mov_b32_e32 v64, v73
	v_mov_b32_e32 v72, v74
	v_mov_b32_e32 v73, v66
	v_mov_b32_e32 v66, v75
	s_waitcnt vmcnt(17)
	v_mov_b32_e32 v74, v128
	s_waitcnt vmcnt(16)
	v_mov_b32_e32 v75, v68
	v_mov_b32_e32 v68, v129
	v_mov_b32_e32 v128, v130
	v_mov_b32_e32 v129, v70
	v_mov_b32_e32 v70, v131
	v_pk_add_f32 v[64:65], v[164:165], v[64:65]
	v_pk_add_f32 v[66:67], v[72:73], v[66:67]
	v_pk_add_f32 v[68:69], v[74:75], v[68:69]
	v_pk_add_f32 v[70:71], v[128:129], v[70:71]
	v_pk_add_f32 v[64:65], v[64:65], v[66:67]
	v_pk_add_f32 v[66:67], v[68:69], v[70:71]
	v_mov_b32_e32 v69, v64
	v_mov_b32_e32 v68, v66
	v_mov_b32_e32 v64, v67
	v_pk_add_f32 v[64:65], v[68:69], v[64:65]
	ds_bpermute_b32 v67, v250, v65
	ds_bpermute_b32 v66, v250, v64
	s_waitcnt vmcnt(15)
	v_mov_b32_e32 v130, v156
	s_waitcnt vmcnt(14)
	v_mov_b32_e32 v131, v76
	v_mov_b32_e32 v76, v157
	v_mov_b32_e32 v156, v158
	s_waitcnt lgkmcnt(0)
	v_pk_add_f32 v[64:65], v[64:65], v[66:67]
	ds_bpermute_b32 v67, v249, v65
	ds_bpermute_b32 v66, v249, v64
	v_mov_b32_e32 v157, v78
	v_mov_b32_e32 v78, v159
	s_waitcnt vmcnt(13)
; __device__ __forceinline__ float bflo(unsigned w) { return __uint_as_float(w << 16); }
; __device__ __forceinline__ float row_rstd(const float* ssq, int row, int fq) {
;     const f32x4 a = *(const f32x4*)(ssq + (size_t)row * 32 + 8 * fq), b = *(const f32x4*)(ssq + (size_t)row * 32 + 8 * fq + 4);
;     float t = ((a[0] + a[1]) + (a[2] + a[3])) + ((b[0] + b[1]) + (b[2] + b[3]));
;     t += __shfl_xor(t, 16); t += __shfl_xor(t, 32);
;     return rsqrtf(t * (1.0f / 2048.0f) + EPS);
;     __device__ __forceinline__ void operator()(f32x4 (&acc)[2][2][4][2], const Unit& u, int wr, int wc, int fr, int fq) const {
;     ...
;             for (int m = 0; m < 4; ++m) { const int row = row0 + ai * HALF + m * 16;
; #pragma unroll
;                 for (int bj = 0; bj < 2; ++bj) { const size_t o = (size_t)row * DM + col0 + bj * HALF; hw[m][bj] = *(const u32x4*)(hb + o); pw[m][bj] = *(const u32x4*)(ppf + (((ai * 4 + m) * 2 + bj) << 9)); }
;                 rstd[m] = row_rstd(ssq_in, row, fq); }
; #pragma unroll
;             for (int m = 0; m < 4; ++m) { const int row = row0 + ai * HALF + m * 16; const size_t off = (size_t)row * DM + col0; float s = 0.f;
; #pragma unroll
;                 for (int bj = 0; bj < 2; ++bj) { const f32x4 z0 = acc[ai][bj][m][0] * rstd[m], z1 = acc[ai][bj][m][1] * rstd[m]; const u32x4 h2 = hw[m][bj], p2 = pw[m][bj]; f32x4 v0, v1;
;                     v0[0] = bflo(h2.x) + sigmoidf_(z0[0]) * bflo(p2.x); v0[1] = bfhi(h2.x) + sigmoidf_(z0[1]) * bfhi(p2.x);
;                     v0[2] = bflo(h2.y) + sigmoidf_(z0[2]) * bflo(p2.y); v0[3] = bfhi(h2.y) + sigmoidf_(z0[3]) * bfhi(p2.y);
;                     v1[0] = bflo(h2.z) + sigmoidf_(z1[0]) * bflo(p2.z); v1[1] = bfhi(h2.z) + sigmoidf_(z1[1]) * bfhi(p2.z);
;                     v1[2] = bflo(h2.w) + sigmoidf_(z1[2]) * bflo(p2.w); v1[3] = bfhi(h2.w) + sigmoidf_(z1[3]) * bfhi(p2.w);
;                     u32x4 w; w.x = cvt_pk_bf16(v0[0], v0[1]); w.y = cvt_pk_bf16(v0[2], v0[3]); w.z = cvt_pk_bf16(v1[0], v1[1]); w.w = cvt_pk_bf16(v1[2], v1[3]);
;                     *(u32x4*)(out + off + bj * HALF) = w;
;                     s += ((v0[0] * v0[0] + v0[1] * v0[1]) + (v0[2] * v0[2] + v0[3] * v0[3])) + ((v1[0] * v1[0] + v1[1] * v1[1]) + (v1[2] * v1[2] + v1[3] * v1[3])); }
;                 s += __shfl_xor(s, 16); s += __shfl_xor(s, 32);
;                 if (fq == 0) ssq[(size_t)row * 32 + u.pn * 4 + wc] = s; }
	v_mov_b32_e32 v158, v160
	s_waitcnt vmcnt(12)
	v_mov_b32_e32 v159, v132
	v_mov_b32_e32 v132, v161
	s_waitcnt lgkmcnt(0)
	v_pk_add_f32 v[64:65], v[64:65], v[66:67]
	v_pk_add_f32 v[74:75], v[158:159], v[132:133]
	v_pk_fma_f32 v[132:133], v[64:65], s[38:39], v[208:209] op_sel_hi:[1,0,0]
	v_mov_b32_e32 v68, v162
	v_mul_f32_e32 v64, 0x4b800000, v133
	v_cmp_gt_f32_e64 s[2:3], s52, v133
	v_mov_b32_e32 v69, v134
	v_mov_b32_e32 v134, v163
	v_cndmask_b32_e64 v64, v133, v64, s[2:3]
	v_rsq_f32_e32 v67, v64
	v_pk_add_f32 v[68:69], v[68:69], v[134:135]
	v_pk_add_f32 v[70:71], v[130:131], v[76:77]
	v_pk_add_f32 v[64:65], v[74:75], v[68:69]
	v_pk_add_f32 v[72:73], v[156:157], v[78:79]
	v_mov_b32_e32 v66, v64
	v_mul_f32_e32 v64, 0x45800000, v67
	v_cndmask_b32_e64 v134, v67, v64, s[2:3]
	v_pk_mul_f32 v[60:61], v[60:61], v[134:135] op_sel_hi:[1,0]
	v_pk_add_f32 v[70:71], v[70:71], v[72:73]
	v_mul_f32_e32 v60, 0xbfb8aa3b, v60
	v_mov_b32_e32 v67, v70
	v_mov_b32_e32 v70, v65
	v_exp_f32_e32 v60, v60
	v_mul_f32_e32 v61, 0xbfb8aa3b, v61
	v_pk_add_f32 v[128:129], v[66:67], v[70:71]
	global_load_dwordx4 v[76:79], v[154:155], off
	global_load_dwordx4 v[68:71], v[154:155], off offset:256
	global_load_dwordx4 v[72:75], v[152:153], off offset:2048
	global_load_dwordx4 v[64:67], v[152:153], off offset:3072
	v_exp_f32_e32 v61, v61
	v_add_f32_e32 v60, 1.0, v60
	v_rcp_f32_e32 v60, v60
	v_pk_mul_f32 v[62:63], v[62:63], v[134:135] op_sel_hi:[1,0]
	v_add_f32_e32 v61, 1.0, v61
	v_rcp_f32_e32 v61, v61
	v_pk_mul_f32 v[58:59], v[58:59], v[134:135] op_sel_hi:[1,0]
	v_pk_mul_f32 v[56:57], v[56:57], v[134:135] op_sel_hi:[1,0]
	s_waitcnt vmcnt(9)
	v_lshlrev_b32_e32 v133, 16, v124
	v_lshlrev_b32_e32 v135, 16, v120
	v_fmac_f32_e32 v133, v60, v135
	v_and_b32_e32 v60, 0xffff0000, v124
	v_and_b32_e32 v120, 0xffff0000, v120
	v_fmac_f32_e32 v60, v61, v120
	v_mul_f32_e32 v61, 0xbfb8aa3b, v62
	v_exp_f32_e32 v61, v61
	v_mul_f32_e32 v63, 0xbfb8aa3b, v63
	v_exp_f32_e32 v63, v63
	v_mul_f32_e32 v56, 0xbfb8aa3b, v56
	v_exp_f32_e32 v56, v56
	v_mul_f32_e32 v57, 0xbfb8aa3b, v57
	v_exp_f32_e32 v57, v57
	v_add_f32_e32 v61, 1.0, v61
	v_rcp_f32_e32 v61, v61
	v_add_f32_e32 v63, 1.0, v63
	v_rcp_f32_e32 v63, v63
	v_add_f32_e32 v56, 1.0, v56
	v_rcp_f32_e32 v56, v56
	v_add_f32_e32 v57, 1.0, v57
	v_lshlrev_b32_e32 v62, 16, v125
	v_lshlrev_b32_e32 v120, 16, v121
	v_rcp_f32_e32 v57, v57
	v_fmac_f32_e32 v62, v61, v120
	v_and_b32_e32 v61, 0xffff0000, v125
	v_and_b32_e32 v120, 0xffff0000, v121
	v_fmac_f32_e32 v61, v63, v120
	v_lshlrev_b32_e32 v63, 16, v126
	v_lshlrev_b32_e32 v120, 16, v122
	v_fmac_f32_e32 v63, v56, v120
	v_and_b32_e32 v120, 0xffff0000, v126
	v_and_b32_e32 v56, 0xffff0000, v122
	v_fmac_f32_e32 v120, v57, v56
	v_mul_f32_e32 v56, 0xbfb8aa3b, v58
	v_exp_f32_e32 v56, v56
	v_mul_f32_e32 v57, 0xbfb8aa3b, v59
	v_exp_f32_e32 v57, v57
	v_pk_mul_f32 v[52:53], v[52:53], v[134:135] op_sel_hi:[1,0]
	v_add_f32_e32 v56, 1.0, v56
	v_rcp_f32_e32 v56, v56
	v_add_f32_e32 v57, 1.0, v57
	v_rcp_f32_e32 v57, v57
	v_mul_f32_e32 v52, 0xbfb8aa3b, v52
	v_exp_f32_e32 v52, v52
	v_mul_f32_e32 v53, 0xbfb8aa3b, v53
	v_lshlrev_b32_e32 v121, 16, v127
	v_lshlrev_b32_e32 v58, 16, v123
	v_exp_f32_e32 v53, v53
	v_fmac_f32_e32 v121, v56, v58
	v_and_b32_e32 v122, 0xffff0000, v127
	v_and_b32_e32 v56, 0xffff0000, v123
	v_fmac_f32_e32 v122, v57, v56
	v_cvt_pk_bf16_f32 v56, v133, v60
	v_cvt_pk_bf16_f32 v57, v62, v61
	v_mul_f32_e32 v60, v60, v60
	v_mul_f32_e32 v61, v61, v61
	v_fmac_f32_e32 v60, v133, v133
	v_fmac_f32_e32 v61, v62, v62
	v_add_f32_e32 v52, 1.0, v52
	v_add_f32_e32 v60, v60, v61
	v_mul_f32_e32 v61, v120, v120
	v_mul_f32_e32 v62, v122, v122
	v_rcp_f32_e32 v52, v52
	v_add_f32_e32 v53, 1.0, v53
	v_fmac_f32_e32 v61, v63, v63
	v_fmac_f32_e32 v62, v121, v121
	v_rcp_f32_e32 v53, v53
	v_add_f32_e32 v61, v61, v62
	v_add_f32_e32 v60, v60, v61
	s_waitcnt vmcnt(8)
	v_lshlrev_b32_e32 v61, 16, v116
	v_lshlrev_b32_e32 v62, 16, v112
	v_pk_mul_f32 v[54:55], v[54:55], v[134:135] op_sel_hi:[1,0]
	v_fmac_f32_e32 v61, v52, v62
	v_and_b32_e32 v52, 0xffff0000, v116
	v_and_b32_e32 v62, 0xffff0000, v112
	v_fmac_f32_e32 v52, v53, v62
	v_mul_f32_e32 v53, 0xbfb8aa3b, v54
	v_pk_mul_f32 v[48:49], v[48:49], v[134:135] op_sel_hi:[1,0]
	v_exp_f32_e32 v53, v53
	v_mul_f32_e32 v54, 0xbfb8aa3b, v55
	v_exp_f32_e32 v54, v54
	v_mul_f32_e32 v48, 0xbfb8aa3b, v48
	v_exp_f32_e32 v48, v48
	v_mul_f32_e32 v49, 0xbfb8aa3b, v49
	v_exp_f32_e32 v49, v49
	v_add_f32_e32 v53, 1.0, v53
	v_rcp_f32_e32 v53, v53
	v_add_f32_e32 v54, 1.0, v54
	v_rcp_f32_e32 v54, v54
	v_add_f32_e32 v48, 1.0, v48
	v_rcp_f32_e32 v48, v48
	v_add_f32_e32 v49, 1.0, v49
	v_lshlrev_b32_e32 v62, 16, v117
	v_lshlrev_b32_e32 v55, 16, v113
	v_rcp_f32_e32 v49, v49
	v_fmac_f32_e32 v62, v53, v55
	v_and_b32_e32 v53, 0xffff0000, v117
	v_and_b32_e32 v55, 0xffff0000, v113
	v_cvt_pk_bf16_f32 v58, v63, v120
	v_fmac_f32_e32 v53, v54, v55
	v_lshlrev_b32_e32 v63, 16, v118
	v_lshlrev_b32_e32 v54, 16, v114
	v_pk_mul_f32 v[50:51], v[50:51], v[134:135] op_sel_hi:[1,0]
	v_fmac_f32_e32 v63, v48, v54
	v_and_b32_e32 v112, 0xffff0000, v118
	v_and_b32_e32 v48, 0xffff0000, v114
	v_fmac_f32_e32 v112, v49, v48
	v_mul_f32_e32 v48, 0xbfb8aa3b, v50
	v_exp_f32_e32 v48, v48
	v_mul_f32_e32 v49, 0xbfb8aa3b, v51
	v_exp_f32_e32 v49, v49
	v_lshlrev_b32_e32 v113, 16, v119
	v_add_f32_e32 v48, 1.0, v48
	v_rcp_f32_e32 v48, v48
	v_add_f32_e32 v49, 1.0, v49
	v_rcp_f32_e32 v49, v49
	v_lshlrev_b32_e32 v50, 16, v115
	v_fmac_f32_e32 v113, v48, v50
	v_and_b32_e32 v114, 0xffff0000, v119
	v_and_b32_e32 v48, 0xffff0000, v115
	v_fmac_f32_e32 v114, v49, v48
	v_mul_f32_e32 v48, v52, v52
	v_mul_f32_e32 v49, v53, v53
	v_fmac_f32_e32 v48, v61, v61
	v_fmac_f32_e32 v49, v62, v62
	v_add_f32_e32 v48, v48, v49
	v_mul_f32_e32 v49, v112, v112
	v_mul_f32_e32 v50, v114, v114
	v_fmac_f32_e32 v49, v63, v63
	v_fmac_f32_e32 v50, v113, v113
	v_add_f32_e32 v49, v49, v50
	v_add_f32_e32 v48, v48, v49
	v_add_f32_e32 v51, v60, v48
	ds_bpermute_b32 v131, v250, v129
	ds_bpermute_b32 v130, v250, v128
	ds_bpermute_b32 v60, v250, v51
	v_lshl_add_u64 v[48:49], s[0:1], 0, v[150:151]
	v_lshl_add_u64 v[54:55], v[210:211], 1, v[48:49]
	v_cmp_gt_f32_e32 vcc, s52, v132
	s_waitcnt lgkmcnt(1)
	v_pk_add_f32 v[128:129], v[128:129], v[130:131]
	s_waitcnt lgkmcnt(0)
	v_add_f32_e32 v48, v51, v60
	ds_bpermute_b32 v131, v249, v129
	ds_bpermute_b32 v130, v249, v128
	ds_bpermute_b32 v49, v249, v48
	v_cvt_pk_bf16_f32 v59, v121, v122
	global_store_dwordx4 v[54:55], v[56:59], off sc1
	v_cvt_pk_bf16_f32 v50, v61, v52
	v_cvt_pk_bf16_f32 v51, v62, v53
	v_cvt_pk_bf16_f32 v52, v63, v112
	v_cvt_pk_bf16_f32 v53, v113, v114
	global_store_dwordx4 v[54:55], v[50:53], off offset:256 sc1
	s_and_saveexec_b64 s[2:3], s[36:37]
	s_cbranch_execz .LBB0_1017
	v_lshl_add_u64 v[50:51], s[28:29], 0, v[148:149]
	v_lshl_add_u64 v[50:51], s[48:49], 2, v[50:51]
	s_lshl_b32 s4, s27, 2
	v_lshl_add_u64 v[50:51], v[50:51], 0, s[4:5]
	s_waitcnt lgkmcnt(0)
	v_add_f32_e32 v48, v48, v49
	global_store_dword v[50:51], v48, off
; __device__ __forceinline__ unsigned cvt_pk_bf16(float lo, float hi) { unsigned r; asm volatile("v_cvt_pk_bf16_f32 %0, %1, %2" : "=v"(r) : "v"(lo), "v"(hi)); return r; }
; __device__ __forceinline__ float bflo(unsigned w) { return __uint_as_float(w << 16); }
; __device__ __forceinline__ float bfhi(unsigned w) { return __uint_as_float(w & 0xffff0000u); }
; __device__ __forceinline__ float sigmoidf_(float x) { return __builtin_amdgcn_rcpf(1.0f + __expf(-x)); }
;     __device__ __forceinline__ void operator()(f32x4 (&acc)[2][2][4][2], const Unit& u, int wr, int wc, int fr, int fq) const {
;     ...
;             for (int m = 0; m < 4; ++m) { const int row = row0 + ai * HALF + m * 16; const size_t off = (size_t)row * DM + col0; float s = 0.f;
; #pragma unroll
;                 for (int bj = 0; bj < 2; ++bj) { const f32x4 z0 = acc[ai][bj][m][0] * rstd[m], z1 = acc[ai][bj][m][1] * rstd[m]; const u32x4 h2 = hw[m][bj], p2 = pw[m][bj]; f32x4 v0, v1;
;                     v0[0] = bflo(h2.x) + sigmoidf_(z0[0]) * bflo(p2.x); v0[1] = bfhi(h2.x) + sigmoidf_(z0[1]) * bfhi(p2.x);
;                     v0[2] = bflo(h2.y) + sigmoidf_(z0[2]) * bflo(p2.y); v0[3] = bfhi(h2.y) + sigmoidf_(z0[3]) * bfhi(p2.y);
;                     v1[0] = bflo(h2.z) + sigmoidf_(z1[0]) * bflo(p2.z); v1[1] = bfhi(h2.z) + sigmoidf_(z1[1]) * bfhi(p2.z);
;                     v1[2] = bflo(h2.w) + sigmoidf_(z1[2]) * bflo(p2.w); v1[3] = bfhi(h2.w) + sigmoidf_(z1[3]) * bfhi(p2.w);
;                     u32x4 w; w.x = cvt_pk_bf16(v0[0], v0[1]); w.y = cvt_pk_bf16(v0[2], v0[3]); w.z = cvt_pk_bf16(v1[0], v1[1]); w.w = cvt_pk_bf16(v1[2], v1[3]);
;                     *(u32x4*)(out + off + bj * HALF) = w;
;                     s += ((v0[0] * v0[0] + v0[1] * v0[1]) + (v0[2] * v0[2] + v0[3] * v0[3])) + ((v1[0] * v1[0] + v1[1] * v1[1]) + (v1[2] * v1[2] + v1[3] * v1[3])); }
;                 s += __shfl_xor(s, 16); s += __shfl_xor(s, 32);
;                 if (fq == 0) ssq[(size_t)row * 32 + u.pn * 4 + wc] = s; }
.LBB0_1017:
	s_or_b64 exec, exec, s[2:3]
	v_mul_f32_e32 v48, 0x4b800000, v132
	v_cndmask_b32_e32 v48, v132, v48, vcc
	v_rsq_f32_e32 v48, v48
	v_lshlrev_b32_e32 v50, 16, v104
	s_waitcnt vmcnt(9)
	v_lshlrev_b32_e32 v51, 16, v109
	v_and_b32_e32 v52, 0xffff0000, v110
	s_waitcnt lgkmcnt(0)
	v_mul_f32_e32 v49, 0x45800000, v48
	v_cndmask_b32_e32 v48, v48, v49, vcc
	v_pk_mul_f32 v[44:45], v[44:45], v[48:49] op_sel_hi:[1,0]
	v_pk_mul_f32 v[46:47], v[46:47], v[48:49] op_sel_hi:[1,0]
	v_mul_f32_e32 v44, 0xbfb8aa3b, v44
	v_exp_f32_e32 v44, v44
	v_pk_mul_f32 v[42:43], v[42:43], v[48:49] op_sel_hi:[1,0]
	v_pk_mul_f32 v[40:41], v[40:41], v[48:49] op_sel_hi:[1,0]
	v_lshlrev_b32_e32 v49, 16, v108
	v_add_f32_e32 v44, 1.0, v44
	v_rcp_f32_e32 v44, v44
	v_mul_f32_e32 v40, 0xbfb8aa3b, v40
	v_exp_f32_e32 v40, v40
	v_lshlrev_b32_e32 v53, 16, v111
	v_fmac_f32_e32 v49, v44, v50
	v_mul_f32_e32 v44, 0xbfb8aa3b, v45
	v_exp_f32_e32 v44, v44
	v_and_b32_e32 v50, 0xffff0000, v108
	v_and_b32_e32 v45, 0xffff0000, v104
	v_add_f32_e32 v40, 1.0, v40
	v_add_f32_e32 v44, 1.0, v44
	v_rcp_f32_e32 v44, v44
	v_rcp_f32_e32 v40, v40
	v_pk_mul_f32 v[36:37], v[36:37], v[48:49] op_sel_hi:[1,0]
	v_and_b32_e32 v54, 0xffff0000, v111
	v_fmac_f32_e32 v50, v44, v45
	v_mul_f32_e32 v44, 0xbfb8aa3b, v46
	v_exp_f32_e32 v44, v44
	v_lshlrev_b32_e32 v45, 16, v105
	v_and_b32_e32 v46, 0xffff0000, v109
	v_mul_f32_e32 v36, 0xbfb8aa3b, v36
	v_add_f32_e32 v44, 1.0, v44
	v_rcp_f32_e32 v44, v44
	v_pk_mul_f32 v[38:39], v[38:39], v[48:49] op_sel_hi:[1,0]
	v_exp_f32_e32 v36, v36
	v_mul_f32_e32 v37, 0xbfb8aa3b, v37
	v_fmac_f32_e32 v51, v44, v45
	v_mul_f32_e32 v44, 0xbfb8aa3b, v47
	v_exp_f32_e32 v44, v44
	v_and_b32_e32 v45, 0xffff0000, v105
	v_lshlrev_b32_e32 v47, 16, v110
	v_exp_f32_e32 v37, v37
	v_add_f32_e32 v44, 1.0, v44
	v_rcp_f32_e32 v44, v44
	v_mul_f32_e32 v38, 0xbfb8aa3b, v38
	v_pk_mul_f32 v[32:33], v[32:33], v[48:49] op_sel_hi:[1,0]
	v_exp_f32_e32 v38, v38
	v_fmac_f32_e32 v46, v44, v45
	v_lshlrev_b32_e32 v44, 16, v106
	v_fmac_f32_e32 v47, v40, v44
	v_mul_f32_e32 v40, 0xbfb8aa3b, v41
	v_exp_f32_e32 v40, v40
	v_and_b32_e32 v41, 0xffff0000, v106
	v_mul_f32_e32 v39, 0xbfb8aa3b, v39
	v_exp_f32_e32 v39, v39
	v_add_f32_e32 v40, 1.0, v40
	v_rcp_f32_e32 v40, v40
	v_mul_f32_e32 v32, 0xbfb8aa3b, v32
	v_add_f32_e32 v36, 1.0, v36
	v_exp_f32_e32 v32, v32
	v_fmac_f32_e32 v52, v40, v41
	v_mul_f32_e32 v40, 0xbfb8aa3b, v42
	v_exp_f32_e32 v40, v40
	v_lshlrev_b32_e32 v41, 16, v107
	v_cvt_pk_bf16_f32 v42, v49, v50
	v_rcp_f32_e32 v36, v36
	v_add_f32_e32 v40, 1.0, v40
	v_rcp_f32_e32 v40, v40
	v_add_f32_e32 v37, 1.0, v37
	v_rcp_f32_e32 v37, v37
	v_add_f32_e32 v38, 1.0, v38
	v_fmac_f32_e32 v53, v40, v41
	v_mul_f32_e32 v40, 0xbfb8aa3b, v43
	v_exp_f32_e32 v40, v40
	v_and_b32_e32 v41, 0xffff0000, v107
	v_cvt_pk_bf16_f32 v43, v51, v46
	v_cvt_pk_bf16_f32 v44, v47, v52
	v_add_f32_e32 v40, 1.0, v40
	v_rcp_f32_e32 v40, v40
	v_rcp_f32_e32 v38, v38
	v_add_f32_e32 v39, 1.0, v39
	v_rcp_f32_e32 v39, v39
	v_fmac_f32_e32 v54, v40, v41
	v_lshl_add_u64 v[40:41], s[0:1], 0, v[146:147]
	v_lshl_add_u64 v[40:41], v[210:211], 1, v[40:41]
	v_cvt_pk_bf16_f32 v45, v53, v54
	global_store_dwordx4 v[40:41], v[42:45], off sc1
	v_add_f32_e32 v32, 1.0, v32
	v_rcp_f32_e32 v32, v32
	v_mul_f32_e32 v42, v50, v50
	v_mul_f32_e32 v43, v46, v46
	v_fmac_f32_e32 v42, v49, v49
	v_fmac_f32_e32 v43, v51, v51
	v_add_f32_e32 v42, v42, v43
	v_mul_f32_e32 v43, v52, v52
	v_mul_f32_e32 v44, v54, v54
	v_fmac_f32_e32 v43, v47, v47
	v_fmac_f32_e32 v44, v53, v53
	v_add_f32_e32 v43, v43, v44
	v_add_f32_e32 v42, v42, v43
	s_waitcnt vmcnt(9)
	v_lshlrev_b32_e32 v43, 16, v100
	v_lshlrev_b32_e32 v44, 16, v96
	v_fmac_f32_e32 v43, v36, v44
	v_and_b32_e32 v36, 0xffff0000, v100
	v_and_b32_e32 v44, 0xffff0000, v96
	v_fmac_f32_e32 v36, v37, v44
	v_lshlrev_b32_e32 v37, 16, v101
	v_lshlrev_b32_e32 v44, 16, v97
	v_fmac_f32_e32 v37, v38, v44
	v_and_b32_e32 v38, 0xffff0000, v101
	v_and_b32_e32 v44, 0xffff0000, v97
	v_fmac_f32_e32 v38, v39, v44
	v_lshlrev_b32_e32 v39, 16, v102
	v_lshlrev_b32_e32 v44, 16, v98
	v_fmac_f32_e32 v39, v32, v44
	v_mul_f32_e32 v32, 0xbfb8aa3b, v33
	v_exp_f32_e32 v32, v32
	v_pk_mul_f32 v[34:35], v[34:35], v[48:49] op_sel_hi:[1,0]
	v_and_b32_e32 v44, 0xffff0000, v102
	v_and_b32_e32 v33, 0xffff0000, v98
	v_add_f32_e32 v32, 1.0, v32
	v_rcp_f32_e32 v32, v32
	v_lshlrev_b32_e32 v45, 16, v103
	v_and_b32_e32 v46, 0xffff0000, v103
	v_fmac_f32_e32 v44, v32, v33
	v_mul_f32_e32 v32, 0xbfb8aa3b, v34
	v_exp_f32_e32 v32, v32
	v_lshlrev_b32_e32 v33, 16, v99
	v_add_f32_e32 v32, 1.0, v32
	v_rcp_f32_e32 v32, v32
	s_nop 0
	v_fmac_f32_e32 v45, v32, v33
	v_mul_f32_e32 v32, 0xbfb8aa3b, v35
	v_exp_f32_e32 v32, v32
	v_and_b32_e32 v33, 0xffff0000, v99
	v_add_f32_e32 v32, 1.0, v32
	v_rcp_f32_e32 v32, v32
	s_nop 0
	v_fmac_f32_e32 v46, v32, v33
	v_cvt_pk_bf16_f32 v32, v43, v36
	v_cvt_pk_bf16_f32 v33, v37, v38
	v_cvt_pk_bf16_f32 v34, v39, v44
	v_cvt_pk_bf16_f32 v35, v45, v46
	global_store_dwordx4 v[40:41], v[32:35], off offset:256 sc1
	s_nop 1
	v_mul_f32_e32 v32, v36, v36
	v_mul_f32_e32 v33, v38, v38
	v_fmac_f32_e32 v32, v43, v43
	v_fmac_f32_e32 v33, v37, v37
	v_add_f32_e32 v32, v32, v33
	v_mul_f32_e32 v33, v44, v44
	v_mul_f32_e32 v34, v46, v46
	v_fmac_f32_e32 v33, v39, v39
	v_fmac_f32_e32 v34, v45, v45
	v_add_f32_e32 v33, v33, v34
	v_add_f32_e32 v32, v32, v33
	v_add_f32_e32 v32, v42, v32
	ds_bpermute_b32 v33, v250, v32
	s_waitcnt lgkmcnt(0)
	v_add_f32_e32 v32, v32, v33
	ds_bpermute_b32 v33, v249, v32
	s_and_saveexec_b64 s[2:3], s[36:37]
	s_cbranch_execz .LBB0_1019
	v_lshl_add_u64 v[34:35], s[28:29], 0, v[144:145]
	v_lshl_add_u64 v[34:35], s[48:49], 2, v[34:35]
	s_lshl_b32 s4, s27, 2
	v_lshl_add_u64 v[34:35], v[34:35], 0, s[4:5]
	s_waitcnt lgkmcnt(0)
	v_add_f32_e32 v32, v32, v33
	global_store_dword v[34:35], v32, off
; __device__ __forceinline__ unsigned cvt_pk_bf16(float lo, float hi) { unsigned r; asm volatile("v_cvt_pk_bf16_f32 %0, %1, %2" : "=v"(r) : "v"(lo), "v"(hi)); return r; }
; __device__ __forceinline__ float bflo(unsigned w) { return __uint_as_float(w << 16); }
; __device__ __forceinline__ float bfhi(unsigned w) { return __uint_as_float(w & 0xffff0000u); }
; __device__ __forceinline__ float sigmoidf_(float x) { return __builtin_amdgcn_rcpf(1.0f + __expf(-x)); }
; __device__ __forceinline__ float row_rstd(const float* ssq, int row, int fq) {
;     const f32x4 a = *(const f32x4*)(ssq + (size_t)row * 32 + 8 * fq), b = *(const f32x4*)(ssq + (size_t)row * 32 + 8 * fq + 4);
;     float t = ((a[0] + a[1]) + (a[2] + a[3])) + ((b[0] + b[1]) + (b[2] + b[3]));
;     t += __shfl_xor(t, 16); t += __shfl_xor(t, 32);
;     return rsqrtf(t * (1.0f / 2048.0f) + EPS);
;     __device__ __forceinline__ void operator()(f32x4 (&acc)[2][2][4][2], const Unit& u, int wr, int wc, int fr, int fq) const {
;     ...
;             for (int m = 0; m < 4; ++m) { const int row = row0 + ai * HALF + m * 16; const size_t off = (size_t)row * DM + col0; float s = 0.f;
; #pragma unroll
;                 for (int bj = 0; bj < 2; ++bj) { const f32x4 z0 = acc[ai][bj][m][0] * rstd[m], z1 = acc[ai][bj][m][1] * rstd[m]; const u32x4 h2 = hw[m][bj], p2 = pw[m][bj]; f32x4 v0, v1;
;                     v0[0] = bflo(h2.x) + sigmoidf_(z0[0]) * bflo(p2.x); v0[1] = bfhi(h2.x) + sigmoidf_(z0[1]) * bfhi(p2.x);
;                     v0[2] = bflo(h2.y) + sigmoidf_(z0[2]) * bflo(p2.y); v0[3] = bfhi(h2.y) + sigmoidf_(z0[3]) * bfhi(p2.y);
;                     v1[0] = bflo(h2.z) + sigmoidf_(z1[0]) * bflo(p2.z); v1[1] = bfhi(h2.z) + sigmoidf_(z1[1]) * bfhi(p2.z);
;                     v1[2] = bflo(h2.w) + sigmoidf_(z1[2]) * bflo(p2.w); v1[3] = bfhi(h2.w) + sigmoidf_(z1[3]) * bfhi(p2.w);
;                     u32x4 w; w.x = cvt_pk_bf16(v0[0], v0[1]); w.y = cvt_pk_bf16(v0[2], v0[3]); w.z = cvt_pk_bf16(v1[0], v1[1]); w.w = cvt_pk_bf16(v1[2], v1[3]);
;                     *(u32x4*)(out + off + bj * HALF) = w;
;                     s += ((v0[0] * v0[0] + v0[1] * v0[1]) + (v0[2] * v0[2] + v0[3] * v0[3])) + ((v1[0] * v1[0] + v1[1] * v1[1]) + (v1[2] * v1[2] + v1[3] * v1[3])); }
;                 s += __shfl_xor(s, 16); s += __shfl_xor(s, 32);
;                 if (fq == 0) ssq[(size_t)row * 32 + u.pn * 4 + wc] = s; }
.LBB0_1019:
	s_or_b64 exec, exec, s[2:3]
	s_waitcnt lgkmcnt(0)
	v_pk_add_f32 v[32:33], v[128:129], v[130:131]
	s_waitcnt vmcnt(9)
	v_lshlrev_b32_e32 v36, 16, v95
	v_pk_fma_f32 v[32:33], v[32:33], s[38:39], v[208:209] op_sel_hi:[1,0,0]
	v_and_b32_e32 v37, 0xffff0000, v95
	v_mul_f32_e32 v34, 0x4b800000, v33
	v_cmp_gt_f32_e64 s[2:3], s52, v33
	v_cmp_gt_f32_e32 vcc, s52, v32
	s_nop 0
	v_cndmask_b32_e64 v33, v33, v34, s[2:3]
	v_rsq_f32_e32 v33, v33
	s_nop 0
	v_mul_f32_e32 v34, 0x45800000, v33
	v_cndmask_b32_e64 v34, v33, v34, s[2:3]
	v_pk_mul_f32 v[28:29], v[28:29], v[34:35] op_sel_hi:[1,0]
	v_pk_mul_f32 v[30:31], v[30:31], v[34:35] op_sel_hi:[1,0]
	v_mul_f32_e32 v28, 0xbfb8aa3b, v28
	v_exp_f32_e32 v28, v28
	v_mul_f32_e32 v29, 0xbfb8aa3b, v29
	v_exp_f32_e32 v29, v29
	v_pk_mul_f32 v[26:27], v[26:27], v[34:35] op_sel_hi:[1,0]
	v_add_f32_e32 v28, 1.0, v28
	v_rcp_f32_e32 v28, v28
	v_add_f32_e32 v29, 1.0, v29
	v_rcp_f32_e32 v29, v29
	v_pk_mul_f32 v[24:25], v[24:25], v[34:35] op_sel_hi:[1,0]
	v_lshlrev_b32_e32 v33, 16, v92
	v_lshlrev_b32_e32 v35, 16, v88
	v_fmac_f32_e32 v33, v28, v35
	v_and_b32_e32 v28, 0xffff0000, v92
	v_and_b32_e32 v35, 0xffff0000, v88
	v_fmac_f32_e32 v28, v29, v35
	v_mul_f32_e32 v29, 0xbfb8aa3b, v30
	v_exp_f32_e32 v29, v29
	v_mul_f32_e32 v31, 0xbfb8aa3b, v31
	v_exp_f32_e32 v31, v31
	v_mul_f32_e32 v24, 0xbfb8aa3b, v24
	v_exp_f32_e32 v24, v24
	v_mul_f32_e32 v25, 0xbfb8aa3b, v25
	v_exp_f32_e32 v25, v25
	v_add_f32_e32 v29, 1.0, v29
	v_rcp_f32_e32 v29, v29
	v_add_f32_e32 v31, 1.0, v31
	v_rcp_f32_e32 v31, v31
	v_add_f32_e32 v24, 1.0, v24
	v_rcp_f32_e32 v24, v24
	v_add_f32_e32 v25, 1.0, v25
	v_lshlrev_b32_e32 v30, 16, v93
	v_lshlrev_b32_e32 v35, 16, v89
	v_rcp_f32_e32 v25, v25
	v_fmac_f32_e32 v30, v29, v35
	v_and_b32_e32 v29, 0xffff0000, v93
	v_and_b32_e32 v35, 0xffff0000, v89
	v_fmac_f32_e32 v29, v31, v35
	v_lshlrev_b32_e32 v31, 16, v94
	v_lshlrev_b32_e32 v35, 16, v90
	v_fmac_f32_e32 v31, v24, v35
	v_and_b32_e32 v35, 0xffff0000, v94
	v_and_b32_e32 v24, 0xffff0000, v90
	v_fmac_f32_e32 v35, v25, v24
	v_mul_f32_e32 v24, 0xbfb8aa3b, v26
	v_exp_f32_e32 v24, v24
	v_mul_f32_e32 v25, 0xbfb8aa3b, v27
	v_exp_f32_e32 v25, v25
	v_pk_mul_f32 v[20:21], v[20:21], v[34:35] op_sel_hi:[1,0]
	v_add_f32_e32 v24, 1.0, v24
	v_rcp_f32_e32 v24, v24
	v_add_f32_e32 v25, 1.0, v25
	v_rcp_f32_e32 v25, v25
	v_mul_f32_e32 v20, 0xbfb8aa3b, v20
	v_exp_f32_e32 v20, v20
	v_mul_f32_e32 v21, 0xbfb8aa3b, v21
	v_lshlrev_b32_e32 v26, 16, v91
	v_exp_f32_e32 v21, v21
	v_fmac_f32_e32 v36, v24, v26
	v_and_b32_e32 v24, 0xffff0000, v91
	v_fmac_f32_e32 v37, v25, v24
	v_cvt_pk_bf16_f32 v24, v33, v28
	v_cvt_pk_bf16_f32 v25, v30, v29
	v_mul_f32_e32 v28, v28, v28
	v_mul_f32_e32 v29, v29, v29
	v_fmac_f32_e32 v28, v33, v33
	v_fmac_f32_e32 v29, v30, v30
	v_add_f32_e32 v20, 1.0, v20
	v_add_f32_e32 v28, v28, v29
	v_mul_f32_e32 v29, v35, v35
	v_mul_f32_e32 v30, v37, v37
	v_rcp_f32_e32 v20, v20
	v_add_f32_e32 v21, 1.0, v21
	v_fmac_f32_e32 v29, v31, v31
	v_fmac_f32_e32 v30, v36, v36
	v_rcp_f32_e32 v21, v21
	v_add_f32_e32 v29, v29, v30
	v_add_f32_e32 v28, v28, v29
	s_waitcnt vmcnt(8)
	v_lshlrev_b32_e32 v29, 16, v84
	v_lshlrev_b32_e32 v30, 16, v80
	v_pk_mul_f32 v[22:23], v[22:23], v[34:35] op_sel_hi:[1,0]
	v_fmac_f32_e32 v29, v20, v30
	v_and_b32_e32 v20, 0xffff0000, v84
	v_and_b32_e32 v30, 0xffff0000, v80
	v_fmac_f32_e32 v20, v21, v30
	v_mul_f32_e32 v21, 0xbfb8aa3b, v22
	v_pk_mul_f32 v[16:17], v[16:17], v[34:35] op_sel_hi:[1,0]
	v_exp_f32_e32 v21, v21
	v_mul_f32_e32 v22, 0xbfb8aa3b, v23
	v_exp_f32_e32 v22, v22
	v_mul_f32_e32 v16, 0xbfb8aa3b, v16
	v_exp_f32_e32 v16, v16
	v_mul_f32_e32 v17, 0xbfb8aa3b, v17
	v_exp_f32_e32 v17, v17
	v_add_f32_e32 v21, 1.0, v21
	v_rcp_f32_e32 v21, v21
	v_add_f32_e32 v22, 1.0, v22
	v_rcp_f32_e32 v22, v22
	v_add_f32_e32 v16, 1.0, v16
	v_rcp_f32_e32 v16, v16
	v_add_f32_e32 v17, 1.0, v17
	v_lshlrev_b32_e32 v30, 16, v85
	v_lshlrev_b32_e32 v23, 16, v81
	v_rcp_f32_e32 v17, v17
	v_fmac_f32_e32 v30, v21, v23
	v_and_b32_e32 v21, 0xffff0000, v85
	v_and_b32_e32 v23, 0xffff0000, v81
	v_cvt_pk_bf16_f32 v26, v31, v35
	v_fmac_f32_e32 v21, v22, v23
	v_lshlrev_b32_e32 v31, 16, v86
	v_lshlrev_b32_e32 v22, 16, v82
	v_pk_mul_f32 v[18:19], v[18:19], v[34:35] op_sel_hi:[1,0]
	v_fmac_f32_e32 v31, v16, v22
	v_and_b32_e32 v33, 0xffff0000, v86
	v_and_b32_e32 v16, 0xffff0000, v82
	v_fmac_f32_e32 v33, v17, v16
	v_mul_f32_e32 v16, 0xbfb8aa3b, v18
	v_exp_f32_e32 v16, v16
	v_mul_f32_e32 v17, 0xbfb8aa3b, v19
	v_exp_f32_e32 v17, v17
	v_lshlrev_b32_e32 v34, 16, v87
	v_add_f32_e32 v16, 1.0, v16
	v_rcp_f32_e32 v16, v16
	v_add_f32_e32 v17, 1.0, v17
	v_rcp_f32_e32 v17, v17
	v_lshlrev_b32_e32 v18, 16, v83
	v_fmac_f32_e32 v34, v16, v18
	v_and_b32_e32 v35, 0xffff0000, v87
	v_and_b32_e32 v16, 0xffff0000, v83
	v_fmac_f32_e32 v35, v17, v16
	v_mul_f32_e32 v16, v20, v20
	v_mul_f32_e32 v17, v21, v21
	v_fmac_f32_e32 v16, v29, v29
	v_fmac_f32_e32 v17, v30, v30
	v_add_f32_e32 v16, v16, v17
	v_mul_f32_e32 v17, v33, v33
	v_mul_f32_e32 v18, v35, v35
	v_fmac_f32_e32 v17, v31, v31
	v_fmac_f32_e32 v18, v34, v34
	v_add_f32_e32 v17, v17, v18
	v_add_f32_e32 v16, v16, v17
	v_add_f32_e32 v19, v28, v16
	ds_bpermute_b32 v28, v250, v19
	v_lshl_add_u64 v[16:17], s[0:1], 0, v[142:143]
	v_lshl_add_u64 v[22:23], v[210:211], 1, v[16:17]
	v_cvt_pk_bf16_f32 v27, v36, v37
	global_store_dwordx4 v[22:23], v[24:27], off sc1
	s_waitcnt lgkmcnt(0)
	v_add_f32_e32 v16, v19, v28
	ds_bpermute_b32 v17, v249, v16
	v_cvt_pk_bf16_f32 v18, v29, v20
	v_cvt_pk_bf16_f32 v19, v30, v21
	v_cvt_pk_bf16_f32 v20, v31, v33
	v_cvt_pk_bf16_f32 v21, v34, v35
	global_store_dwordx4 v[22:23], v[18:21], off offset:256 sc1
	s_and_saveexec_b64 s[2:3], s[36:37]
	s_cbranch_execz .LBB0_1021
	v_lshl_add_u64 v[18:19], s[28:29], 0, v[140:141]
	v_lshl_add_u64 v[18:19], s[48:49], 2, v[18:19]
	s_lshl_b32 s4, s27, 2
	v_lshl_add_u64 v[18:19], v[18:19], 0, s[4:5]
	s_waitcnt lgkmcnt(0)
	v_add_f32_e32 v16, v16, v17
	global_store_dword v[18:19], v16, off
; __device__ __forceinline__ unsigned cvt_pk_bf16(float lo, float hi) { unsigned r; asm volatile("v_cvt_pk_bf16_f32 %0, %1, %2" : "=v"(r) : "v"(lo), "v"(hi)); return r; }
; __device__ __forceinline__ float bflo(unsigned w) { return __uint_as_float(w << 16); }
; __device__ __forceinline__ float bfhi(unsigned w) { return __uint_as_float(w & 0xffff0000u); }
; __device__ __forceinline__ float sigmoidf_(float x) { return __builtin_amdgcn_rcpf(1.0f + __expf(-x)); }
; __device__ __forceinline__ float row_rstd(const float* ssq, int row, int fq) {
;     const f32x4 a = *(const f32x4*)(ssq + (size_t)row * 32 + 8 * fq), b = *(const f32x4*)(ssq + (size_t)row * 32 + 8 * fq + 4);
;     float t = ((a[0] + a[1]) + (a[2] + a[3])) + ((b[0] + b[1]) + (b[2] + b[3]));
;     t += __shfl_xor(t, 16); t += __shfl_xor(t, 32);
;     return rsqrtf(t * (1.0f / 2048.0f) + EPS);
;     __device__ __forceinline__ void operator()(f32x4 (&acc)[2][2][4][2], const Unit& u, int wr, int wc, int fr, int fq) const {
;     ...
;             for (int m = 0; m < 4; ++m) { const int row = row0 + ai * HALF + m * 16; const size_t off = (size_t)row * DM + col0; float s = 0.f;
; #pragma unroll
;                 for (int bj = 0; bj < 2; ++bj) { const f32x4 z0 = acc[ai][bj][m][0] * rstd[m], z1 = acc[ai][bj][m][1] * rstd[m]; const u32x4 h2 = hw[m][bj], p2 = pw[m][bj]; f32x4 v0, v1;
;                     v0[0] = bflo(h2.x) + sigmoidf_(z0[0]) * bflo(p2.x); v0[1] = bfhi(h2.x) + sigmoidf_(z0[1]) * bfhi(p2.x);
;                     v0[2] = bflo(h2.y) + sigmoidf_(z0[2]) * bflo(p2.y); v0[3] = bfhi(h2.y) + sigmoidf_(z0[3]) * bfhi(p2.y);
;                     v1[0] = bflo(h2.z) + sigmoidf_(z1[0]) * bflo(p2.z); v1[1] = bfhi(h2.z) + sigmoidf_(z1[1]) * bfhi(p2.z);
;                     v1[2] = bflo(h2.w) + sigmoidf_(z1[2]) * bflo(p2.w); v1[3] = bfhi(h2.w) + sigmoidf_(z1[3]) * bfhi(p2.w);
;                     u32x4 w; w.x = cvt_pk_bf16(v0[0], v0[1]); w.y = cvt_pk_bf16(v0[2], v0[3]); w.z = cvt_pk_bf16(v1[0], v1[1]); w.w = cvt_pk_bf16(v1[2], v1[3]);
;                     *(u32x4*)(out + off + bj * HALF) = w;
;                     s += ((v0[0] * v0[0] + v0[1] * v0[1]) + (v0[2] * v0[2] + v0[3] * v0[3])) + ((v1[0] * v1[0] + v1[1] * v1[1]) + (v1[2] * v1[2] + v1[3] * v1[3])); }
;                 s += __shfl_xor(s, 16); s += __shfl_xor(s, 32);
;                 if (fq == 0) ssq[(size_t)row * 32 + u.pn * 4 + wc] = s; }
.LBB0_1021:
	s_or_b64 exec, exec, s[2:3]
	v_mul_f32_e32 v16, 0x4b800000, v32
	v_cndmask_b32_e32 v16, v32, v16, vcc
	v_rsq_f32_e32 v16, v16
	s_waitcnt vmcnt(7)
	v_lshlrev_b32_e32 v18, 16, v72
	v_lshlrev_b32_e32 v19, 16, v77
	v_and_b32_e32 v20, 0xffff0000, v78
	s_waitcnt lgkmcnt(0)
	v_mul_f32_e32 v17, 0x45800000, v16
	v_cndmask_b32_e32 v16, v16, v17, vcc
	v_pk_mul_f32 v[12:13], v[12:13], v[16:17] op_sel_hi:[1,0]
	v_pk_mul_f32 v[14:15], v[14:15], v[16:17] op_sel_hi:[1,0]
	v_mul_f32_e32 v12, 0xbfb8aa3b, v12
	v_exp_f32_e32 v12, v12
	v_pk_mul_f32 v[10:11], v[10:11], v[16:17] op_sel_hi:[1,0]
	v_pk_mul_f32 v[8:9], v[8:9], v[16:17] op_sel_hi:[1,0]
	v_lshlrev_b32_e32 v17, 16, v76
	v_add_f32_e32 v12, 1.0, v12
	v_rcp_f32_e32 v12, v12
	v_mul_f32_e32 v8, 0xbfb8aa3b, v8
	v_exp_f32_e32 v8, v8
	v_lshlrev_b32_e32 v21, 16, v79
	v_fmac_f32_e32 v17, v12, v18
	v_mul_f32_e32 v12, 0xbfb8aa3b, v13
	v_exp_f32_e32 v12, v12
	v_and_b32_e32 v18, 0xffff0000, v76
	v_and_b32_e32 v13, 0xffff0000, v72
	v_add_f32_e32 v8, 1.0, v8
	v_add_f32_e32 v12, 1.0, v12
	v_rcp_f32_e32 v12, v12
	v_rcp_f32_e32 v8, v8
	v_pk_mul_f32 v[4:5], v[4:5], v[16:17] op_sel_hi:[1,0]
	v_and_b32_e32 v22, 0xffff0000, v79
	v_fmac_f32_e32 v18, v12, v13
	v_mul_f32_e32 v12, 0xbfb8aa3b, v14
	v_exp_f32_e32 v12, v12
	v_lshlrev_b32_e32 v13, 16, v73
	v_and_b32_e32 v14, 0xffff0000, v77
	v_mul_f32_e32 v4, 0xbfb8aa3b, v4
	v_add_f32_e32 v12, 1.0, v12
	v_rcp_f32_e32 v12, v12
	v_pk_mul_f32 v[6:7], v[6:7], v[16:17] op_sel_hi:[1,0]
	v_exp_f32_e32 v4, v4
	v_mul_f32_e32 v5, 0xbfb8aa3b, v5
	v_fmac_f32_e32 v19, v12, v13
	v_mul_f32_e32 v12, 0xbfb8aa3b, v15
	v_exp_f32_e32 v12, v12
	v_and_b32_e32 v13, 0xffff0000, v73
	v_lshlrev_b32_e32 v15, 16, v78
	v_exp_f32_e32 v5, v5
	v_add_f32_e32 v12, 1.0, v12
	v_rcp_f32_e32 v12, v12
	v_mul_f32_e32 v6, 0xbfb8aa3b, v6
	v_pk_mul_f32 v[0:1], v[0:1], v[16:17] op_sel_hi:[1,0]
	v_exp_f32_e32 v6, v6
	v_fmac_f32_e32 v14, v12, v13
	v_lshlrev_b32_e32 v12, 16, v74
	v_fmac_f32_e32 v15, v8, v12
	v_mul_f32_e32 v8, 0xbfb8aa3b, v9
	v_exp_f32_e32 v8, v8
	v_and_b32_e32 v9, 0xffff0000, v74
	v_mul_f32_e32 v7, 0xbfb8aa3b, v7
	v_exp_f32_e32 v7, v7
	v_add_f32_e32 v8, 1.0, v8
	v_rcp_f32_e32 v8, v8
	v_mul_f32_e32 v0, 0xbfb8aa3b, v0
	v_add_f32_e32 v4, 1.0, v4
	v_exp_f32_e32 v0, v0
	v_fmac_f32_e32 v20, v8, v9
	v_mul_f32_e32 v8, 0xbfb8aa3b, v10
	v_exp_f32_e32 v8, v8
	v_lshlrev_b32_e32 v9, 16, v75
	v_cvt_pk_bf16_f32 v10, v17, v18
	v_rcp_f32_e32 v4, v4
	v_add_f32_e32 v8, 1.0, v8
	v_rcp_f32_e32 v8, v8
	v_add_f32_e32 v5, 1.0, v5
	v_rcp_f32_e32 v5, v5
	v_add_f32_e32 v6, 1.0, v6
	v_fmac_f32_e32 v21, v8, v9
	v_mul_f32_e32 v8, 0xbfb8aa3b, v11
	v_exp_f32_e32 v8, v8
	v_and_b32_e32 v9, 0xffff0000, v75
	v_cvt_pk_bf16_f32 v11, v19, v14
	v_cvt_pk_bf16_f32 v12, v15, v20
	v_add_f32_e32 v8, 1.0, v8
	v_rcp_f32_e32 v8, v8
	v_rcp_f32_e32 v6, v6
	v_add_f32_e32 v7, 1.0, v7
	v_rcp_f32_e32 v7, v7
	v_fmac_f32_e32 v22, v8, v9
	v_lshl_add_u64 v[8:9], s[0:1], 0, v[138:139]
	v_lshl_add_u64 v[8:9], v[210:211], 1, v[8:9]
	v_cvt_pk_bf16_f32 v13, v21, v22
	global_store_dwordx4 v[8:9], v[10:13], off sc1
	v_add_f32_e32 v0, 1.0, v0
	v_rcp_f32_e32 v0, v0
	v_mul_f32_e32 v10, v18, v18
	v_mul_f32_e32 v11, v14, v14
	v_fmac_f32_e32 v10, v17, v17
	v_fmac_f32_e32 v11, v19, v19
	v_add_f32_e32 v10, v10, v11
	v_mul_f32_e32 v11, v20, v20
	v_mul_f32_e32 v12, v22, v22
	v_fmac_f32_e32 v11, v15, v15
	v_fmac_f32_e32 v12, v21, v21
	v_add_f32_e32 v11, v11, v12
	v_add_f32_e32 v10, v10, v11
	v_lshlrev_b32_e32 v11, 16, v68
	s_waitcnt vmcnt(7)
	v_lshlrev_b32_e32 v12, 16, v64
	v_fmac_f32_e32 v11, v4, v12
	v_and_b32_e32 v4, 0xffff0000, v68
	v_and_b32_e32 v12, 0xffff0000, v64
	v_fmac_f32_e32 v4, v5, v12
	v_lshlrev_b32_e32 v5, 16, v69
	v_lshlrev_b32_e32 v12, 16, v65
	v_fmac_f32_e32 v5, v6, v12
	v_and_b32_e32 v6, 0xffff0000, v69
	v_and_b32_e32 v12, 0xffff0000, v65
	v_fmac_f32_e32 v6, v7, v12
	v_lshlrev_b32_e32 v7, 16, v70
	v_lshlrev_b32_e32 v12, 16, v66
	v_fmac_f32_e32 v7, v0, v12
	v_mul_f32_e32 v0, 0xbfb8aa3b, v1
	v_exp_f32_e32 v0, v0
	v_pk_mul_f32 v[2:3], v[2:3], v[16:17] op_sel_hi:[1,0]
	v_and_b32_e32 v12, 0xffff0000, v70
	v_and_b32_e32 v1, 0xffff0000, v66
	v_add_f32_e32 v0, 1.0, v0
	v_rcp_f32_e32 v0, v0
	v_lshlrev_b32_e32 v13, 16, v71
	v_and_b32_e32 v14, 0xffff0000, v71
	v_fmac_f32_e32 v12, v0, v1
	v_mul_f32_e32 v0, 0xbfb8aa3b, v2
	v_exp_f32_e32 v0, v0
	v_lshlrev_b32_e32 v1, 16, v67
	v_add_f32_e32 v0, 1.0, v0
	v_rcp_f32_e32 v0, v0
	s_nop 0
	v_fmac_f32_e32 v13, v0, v1
	v_mul_f32_e32 v0, 0xbfb8aa3b, v3
	v_exp_f32_e32 v0, v0
	v_and_b32_e32 v1, 0xffff0000, v67
	v_add_f32_e32 v0, 1.0, v0
	v_rcp_f32_e32 v0, v0
	s_nop 0
	v_fmac_f32_e32 v14, v0, v1
	v_cvt_pk_bf16_f32 v0, v11, v4
	v_cvt_pk_bf16_f32 v1, v5, v6
	v_cvt_pk_bf16_f32 v2, v7, v12
	v_cvt_pk_bf16_f32 v3, v13, v14
	global_store_dwordx4 v[8:9], v[0:3], off offset:256 sc1
	s_nop 1
	v_mul_f32_e32 v0, v4, v4
	v_mul_f32_e32 v1, v6, v6
	v_fmac_f32_e32 v0, v11, v11
	v_fmac_f32_e32 v1, v5, v5
	v_add_f32_e32 v0, v0, v1
	v_mul_f32_e32 v1, v12, v12
	v_mul_f32_e32 v2, v14, v14
	v_fmac_f32_e32 v1, v7, v7
	v_fmac_f32_e32 v2, v13, v13
	v_add_f32_e32 v1, v1, v2
	v_add_f32_e32 v0, v0, v1
	v_add_f32_e32 v0, v10, v0
	ds_bpermute_b32 v1, v250, v0
	s_waitcnt lgkmcnt(0)
	v_add_f32_e32 v0, v0, v1
	ds_bpermute_b32 v1, v249, v0
	s_and_saveexec_b64 s[2:3], s[36:37]
	s_cbranch_execz .LBB0_998
	v_lshl_add_u64 v[2:3], s[28:29], 0, v[136:137]
	v_lshl_add_u64 v[2:3], s[48:49], 2, v[2:3]
	s_lshl_b32 s4, s27, 2
	v_lshl_add_u64 v[2:3], v[2:3], 0, s[4:5]
	s_waitcnt lgkmcnt(0)
	v_add_f32_e32 v0, v0, v1
	global_store_dword v[2:3], v0, off
	s_branch .LBB0_998
